# combo13 + slots B/D issue the 8 fragment reads before the slot's LDS-DMA loads (read latency covered by DMA issue)
# speedup vs baseline: 1.0051x; 1.0051x over previous
; #define PG8_STAGE(bufoff, gbase, voff) do { _Pragma("unroll") for (int _i = 0; _i < 2; ++_i) \
;     __builtin_amdgcn_global_load_lds((const unsigned*)((const char*)(gbase) + (voff)[_i]), (LAS unsigned*)(lds + (bufoff) + ldsw + _i * 8192), 16, 0, 0); } while (0)
; #define PG8_LDA(dst, b, h) do { _Pragma("unroll") for (int m = 0; m < 4; ++m) _Pragma("unroll") for (int k = 0; k < 2; ++k) dst[m][k] = *(const LAS bf16x8*)(lds + PG8_SA(b, h) + aoff + m * 2048 + k * 1024); } while (0)
; #define PG8_LDB(dst, b, h) do { _Pragma("unroll") for (int n = 0; n < 2; ++n) _Pragma("unroll") for (int k = 0; k < 2; ++k) dst[n][k] = *(const LAS bf16x8*)(lds + PG8_SB(b, h) + boff + n * 2048 + k * 1024); } while (0)
; #define PG8_MMA(ai, bj, At, Bt) do { __builtin_amdgcn_s_setprio(1); _Pragma("unroll") for (int m = 0; m < 4; ++m) _Pragma("unroll") for (int n = 0; n < 2; ++n) _Pragma("unroll") for (int k = 0; k < 2; ++k) \
;     acc[ai][bj][m][n] = __builtin_amdgcn_mfma_f32_16x16x32_bf16(Bt[n][k], At[m][k], acc[ai][bj][m][n], 0, 0, 0); __builtin_amdgcn_s_setprio(0); } while (0)
; #define PG8_WAIT_V(n) asm volatile("s_waitcnt vmcnt(" #n ")" ::: "memory")
; #define PG8_WAIT_L(n) asm volatile("s_waitcnt lgkmcnt(" #n ")" ::: "memory")
; #define PG8_BAR __builtin_amdgcn_s_barrier()
; #define PG8_SCHED __builtin_amdgcn_sched_barrier(0)
; template <class Epi, class Sched = StaticOrder>
; DI void gemm_phase(LAS unsigned char* lds, const Gemm g, const Sched& S, const Epi& E) {
;     ...
;     for (int t = 0; t < nt; t += 2) {
;       const bool last = (t == nt - 2);
;       const char* a1 = cA + (size_t)(t + 1) * kstep;
;       const char* a2 = last ? nA : cA + (size_t)(t + 2) * kstep; const char* b2 = last ? nB : cB + (size_t)(t + 2) * kstep;
;       const char* a3 = a2 + kstep; const char* b3 = b2 + kstep;
;       PG8_LDB(B0, 0, 0); PG8_SCHED; PG8_LDA(At, 0, 0); PG8_STAGE(PG8_SA(1, 1), a1 + hstep, voffA);
;       PG8_WAIT_L(8); PG8_BAR; PG8_WAIT_L(0); PG8_MMA(0, 0, At, B0); PG8_BAR; PG8_SCHED;
;       PG8_LDB(B1, 0, 1); PG8_STAGE(PG8_SB(0, 0), b2, voffB);
;       PG8_BAR; PG8_WAIT_L(0); PG8_MMA(0, 1, At, B1); PG8_BAR;
;       PG8_LDA(At, 0, 1); PG8_STAGE(PG8_SA(0, 0), a2, voffA);
;       PG8_BAR; PG8_WAIT_L(0); PG8_MMA(1, 0, At, B0); PG8_BAR; PG8_SCHED;
;       PG8_STAGE(PG8_SB(0, 1), b2 + hstep, voffB);
;       PG8_WAIT_V(6); PG8_BAR; PG8_MMA(1, 1, At, B1); PG8_BAR;
.LBB0_346:
	ds_read_b128 v[128:131], v173
	ds_read_b128 v[132:135], v173 offset:1024
	ds_read_b128 v[154:157], v173 offset:2048
	ds_read_b128 v[158:161], v173 offset:3072
	s_add_u32 s8, s6, 0xfff80080
	s_addc_u32 s9, s7, -1
	s_cmp_eq_u32 s52, 28
	s_cselect_b32 s11, s31, s9
	s_cselect_b32 s10, s42, s8
	s_cselect_b32 s9, s29, s45
	s_cselect_b32 s8, s43, s44
	s_add_i32 m0, s48, 0xc000
	ds_read_b128 v[162:165], v174
	ds_read_b128 v[166:169], v174 offset:1024
	ds_read_b128 v[178:181], v174 offset:2048
	ds_read_b128 v[182:185], v174 offset:3072
	ds_read_b128 v[186:189], v174 offset:4096
	ds_read_b128 v[190:193], v174 offset:5120
	ds_read_b128 v[194:197], v174 offset:6144
	ds_read_b128 v[198:201], v174 offset:7168
	global_load_lds_dwordx4 v146, s[6:7]
	s_add_i32 m0, s48, 0xe000
	s_nop 0
	global_load_lds_dwordx4 v148, s[6:7]
	ds_read_b128 v[202:205], v175
	ds_read_b128 v[206:209], v175 offset:1024
	ds_read_b128 v[212:215], v175 offset:2048
	ds_read_b128 v[216:219], v175 offset:3072
	s_waitcnt vmcnt(8)
	s_waitcnt lgkmcnt(4)
	s_setprio 1
	s_barrier
	v_mfma_f32_16x16x32_bf16 v[124:127], v[128:131], v[162:165], v[124:127]
	v_mfma_f32_16x16x32_bf16 v[120:123], v[154:157], v[162:165], v[120:123]
	v_mfma_f32_16x16x32_bf16 v[108:111], v[128:131], v[178:181], v[108:111]
	v_mfma_f32_16x16x32_bf16 v[104:107], v[154:157], v[178:181], v[104:107]
	v_mfma_f32_16x16x32_bf16 v[100:103], v[128:131], v[186:189], v[100:103]
	v_mfma_f32_16x16x32_bf16 v[92:95], v[154:157], v[186:189], v[92:95]
	v_mfma_f32_16x16x32_bf16 v[84:87], v[128:131], v[194:197], v[84:87]
	v_mfma_f32_16x16x32_bf16 v[76:79], v[154:157], v[194:197], v[76:79]
	v_mfma_f32_16x16x32_bf16 v[124:127], v[132:135], v[166:169], v[124:127]
	v_mfma_f32_16x16x32_bf16 v[120:123], v[158:161], v[166:169], v[120:123]
	v_mfma_f32_16x16x32_bf16 v[108:111], v[132:135], v[182:185], v[108:111]
	v_mfma_f32_16x16x32_bf16 v[104:107], v[158:161], v[182:185], v[104:107]
	v_mfma_f32_16x16x32_bf16 v[100:103], v[132:135], v[190:193], v[100:103]
	v_mfma_f32_16x16x32_bf16 v[92:95], v[158:161], v[190:193], v[92:95]
	v_mfma_f32_16x16x32_bf16 v[84:87], v[132:135], v[198:201], v[84:87]
	v_mfma_f32_16x16x32_bf16 v[76:79], v[158:161], v[198:201], v[76:79]
	s_waitcnt lgkmcnt(0)
	v_mfma_f32_16x16x32_bf16 v[116:119], v[202:205], v[162:165], v[116:119]
	v_mfma_f32_16x16x32_bf16 v[112:115], v[212:215], v[162:165], v[112:115]
	v_mfma_f32_16x16x32_bf16 v[96:99], v[202:205], v[178:181], v[96:99]
	v_mfma_f32_16x16x32_bf16 v[88:91], v[212:215], v[178:181], v[88:91]
	v_mfma_f32_16x16x32_bf16 v[80:83], v[202:205], v[186:189], v[80:83]
	v_mfma_f32_16x16x32_bf16 v[72:75], v[212:215], v[186:189], v[72:75]
	v_mfma_f32_16x16x32_bf16 v[68:71], v[202:205], v[194:197], v[68:71]
	v_mfma_f32_16x16x32_bf16 v[64:67], v[212:215], v[194:197], v[64:67]
	v_mfma_f32_16x16x32_bf16 v[116:119], v[206:209], v[166:169], v[116:119]
	v_mfma_f32_16x16x32_bf16 v[112:115], v[216:219], v[166:169], v[112:115]
	v_mfma_f32_16x16x32_bf16 v[96:99], v[206:209], v[182:185], v[96:99]
	v_mfma_f32_16x16x32_bf16 v[88:91], v[216:219], v[182:185], v[88:91]
	v_mfma_f32_16x16x32_bf16 v[80:83], v[206:209], v[190:193], v[80:83]
	v_mfma_f32_16x16x32_bf16 v[72:75], v[216:219], v[190:193], v[72:75]
	v_mfma_f32_16x16x32_bf16 v[68:71], v[206:209], v[198:201], v[68:71]
	v_mfma_f32_16x16x32_bf16 v[64:67], v[216:219], v[198:201], v[64:67]
	s_barrier
	s_setprio 0
	s_add_i32 s53, s65, s41
	s_add_u32 s98, s8, 0x80
	s_addc_u32 s99, s9, 0
	s_add_u32 s100, s10, 0x80
	s_addc_u32 s101, s11, 0
	ds_read_b128 v[162:165], v174 offset:16384
	ds_read_b128 v[166:169], v174 offset:17408
	ds_read_b128 v[178:181], v174 offset:18432
	ds_read_b128 v[182:185], v174 offset:19456
	ds_read_b128 v[186:189], v174 offset:20480
	ds_read_b128 v[190:193], v174 offset:21504
	ds_read_b128 v[194:197], v174 offset:22528
	ds_read_b128 v[198:201], v174 offset:23552
	s_mov_b32 m0, s53
	s_nop 0
	global_load_lds_dwordx4 v140, s[8:9]
	s_add_i32 m0, s53, 0x2000
	s_nop 0
	global_load_lds_dwordx4 v136, s[8:9]
	s_mov_b32 m0, s48
	s_nop 0
	global_load_lds_dwordx4 v142, s[10:11]
	s_mov_b32 m0, s49
	s_nop 0
	global_load_lds_dwordx4 v138, s[10:11]
	s_add_u32 s54, s8, 0x80000
	s_addc_u32 s55, s9, 0
	s_add_i32 s53, s72, s41
	s_waitcnt vmcnt(6)
	s_waitcnt lgkmcnt(0)
	s_setprio 1
	s_barrier
	v_mfma_f32_16x16x32_bf16 v[60:63], v[128:131], v[162:165], v[60:63]
	s_mov_b32 m0, s53
	v_mfma_f32_16x16x32_bf16 v[56:59], v[154:157], v[162:165], v[56:59]
	global_load_lds_dwordx4 v140, s[54:55]
	v_mfma_f32_16x16x32_bf16 v[52:55], v[128:131], v[178:181], v[52:55]
	s_bitset1_b32 m0, 13
	v_mfma_f32_16x16x32_bf16 v[44:47], v[154:157], v[178:181], v[44:47]
	global_load_lds_dwordx4 v136, s[54:55]
	v_mfma_f32_16x16x32_bf16 v[36:39], v[128:131], v[186:189], v[36:39]
	v_mfma_f32_16x16x32_bf16 v[28:31], v[154:157], v[186:189], v[28:31]
	v_mfma_f32_16x16x32_bf16 v[20:23], v[128:131], v[194:197], v[20:23]
	v_mfma_f32_16x16x32_bf16 v[12:15], v[154:157], v[194:197], v[12:15]
	v_mfma_f32_16x16x32_bf16 v[60:63], v[132:135], v[166:169], v[60:63]
	v_mfma_f32_16x16x32_bf16 v[56:59], v[158:161], v[166:169], v[56:59]
	v_mfma_f32_16x16x32_bf16 v[52:55], v[132:135], v[182:185], v[52:55]
	v_mfma_f32_16x16x32_bf16 v[44:47], v[158:161], v[182:185], v[44:47]
	v_mfma_f32_16x16x32_bf16 v[36:39], v[132:135], v[190:193], v[36:39]
	v_mfma_f32_16x16x32_bf16 v[28:31], v[158:161], v[190:193], v[28:31]
	v_mfma_f32_16x16x32_bf16 v[20:23], v[132:135], v[198:201], v[20:23]
	v_mfma_f32_16x16x32_bf16 v[12:15], v[158:161], v[198:201], v[12:15]
	v_mfma_f32_16x16x32_bf16 v[48:51], v[202:205], v[162:165], v[48:51]
	v_mfma_f32_16x16x32_bf16 v[40:43], v[212:215], v[162:165], v[40:43]
	v_mfma_f32_16x16x32_bf16 v[32:35], v[202:205], v[178:181], v[32:35]
	v_mfma_f32_16x16x32_bf16 v[24:27], v[212:215], v[178:181], v[24:27]
	v_mfma_f32_16x16x32_bf16 v[16:19], v[202:205], v[186:189], v[16:19]
	v_mfma_f32_16x16x32_bf16 v[8:11], v[212:215], v[186:189], v[8:11]
	v_mfma_f32_16x16x32_bf16 v[4:7], v[202:205], v[194:197], v[4:7]
	v_mfma_f32_16x16x32_bf16 v[0:3], v[212:215], v[194:197], v[0:3]
	v_mfma_f32_16x16x32_bf16 v[48:51], v[206:209], v[166:169], v[48:51]
	v_mfma_f32_16x16x32_bf16 v[40:43], v[216:219], v[166:169], v[40:43]
	v_mfma_f32_16x16x32_bf16 v[32:35], v[206:209], v[182:185], v[32:35]
	v_mfma_f32_16x16x32_bf16 v[24:27], v[216:219], v[182:185], v[24:27]
	v_mfma_f32_16x16x32_bf16 v[16:19], v[206:209], v[190:193], v[16:19]
	v_mfma_f32_16x16x32_bf16 v[8:11], v[216:219], v[190:193], v[8:11]
	v_mfma_f32_16x16x32_bf16 v[4:7], v[206:209], v[198:201], v[4:7]
	v_mfma_f32_16x16x32_bf16 v[0:3], v[216:219], v[198:201], v[0:3]
	s_barrier
; #define PG8_STAGE(bufoff, gbase, voff) do { _Pragma("unroll") for (int _i = 0; _i < 2; ++_i) \
;     __builtin_amdgcn_global_load_lds((const unsigned*)((const char*)(gbase) + (voff)[_i]), (LAS unsigned*)(lds + (bufoff) + ldsw + _i * 8192), 16, 0, 0); } while (0)
; #define PG8_LDA(dst, b, h) do { _Pragma("unroll") for (int m = 0; m < 4; ++m) _Pragma("unroll") for (int k = 0; k < 2; ++k) dst[m][k] = *(const LAS bf16x8*)(lds + PG8_SA(b, h) + aoff + m * 2048 + k * 1024); } while (0)
; #define PG8_LDB(dst, b, h) do { _Pragma("unroll") for (int n = 0; n < 2; ++n) _Pragma("unroll") for (int k = 0; k < 2; ++k) dst[n][k] = *(const LAS bf16x8*)(lds + PG8_SB(b, h) + boff + n * 2048 + k * 1024); } while (0)
; #define PG8_MMA(ai, bj, At, Bt) do { __builtin_amdgcn_s_setprio(1); _Pragma("unroll") for (int m = 0; m < 4; ++m) _Pragma("unroll") for (int n = 0; n < 2; ++n) _Pragma("unroll") for (int k = 0; k < 2; ++k) \
;     acc[ai][bj][m][n] = __builtin_amdgcn_mfma_f32_16x16x32_bf16(Bt[n][k], At[m][k], acc[ai][bj][m][n], 0, 0, 0); __builtin_amdgcn_s_setprio(0); } while (0)
; #define PG8_WAIT_V(n) asm volatile("s_waitcnt vmcnt(" #n ")" ::: "memory")
; #define PG8_WAIT_L(n) asm volatile("s_waitcnt lgkmcnt(" #n ")" ::: "memory")
; #define PG8_BAR __builtin_amdgcn_s_barrier()
; #define PG8_SCHED __builtin_amdgcn_sched_barrier(0)
; template <class Epi, class Sched = StaticOrder>
; DI void gemm_phase(LAS unsigned char* lds, const Gemm g, const Sched& S, const Epi& E) {
;     ...
;       PG8_LDB(B0, 1, 0); PG8_SCHED; PG8_LDA(At, 1, 0); PG8_STAGE(PG8_SA(0, 1), a2 + hstep, voffA);
;       PG8_WAIT_L(8); PG8_BAR; PG8_WAIT_L(0); PG8_MMA(0, 0, At, B0); PG8_BAR; PG8_SCHED;
;       PG8_LDB(B1, 1, 1); PG8_STAGE(PG8_SB(1, 0), b3, voffB);
;       PG8_BAR; PG8_WAIT_L(0); PG8_MMA(0, 1, At, B1); PG8_BAR;
;       PG8_LDA(At, 1, 1); PG8_STAGE(PG8_SA(1, 0), a3, voffA);
;       PG8_BAR; PG8_WAIT_L(0); PG8_MMA(1, 0, At, B0); PG8_BAR; PG8_SCHED;
;       PG8_STAGE(PG8_SB(1, 1), b3 + hstep, voffB);
;       PG8_WAIT_V(6); PG8_BAR; PG8_MMA(1, 1, At, B1); PG8_BAR;
;     }
	s_setprio 0
	s_add_i32 s53, 0, 0x18000
	v_add_u32_e32 v158, s53, v171
	ds_read_b128 v[128:131], v158
	ds_read_b128 v[132:135], v158 offset:1024
	ds_read_b128 v[154:157], v158 offset:2048
	ds_read_b128 v[158:161], v158 offset:3072
	s_add_u32 s10, s10, 0x80000
	s_addc_u32 s11, s11, 0
	s_mov_b32 m0, s50
	ds_read_b128 v[162:165], v174 offset:32768
	ds_read_b128 v[166:169], v174 offset:33792
	ds_read_b128 v[178:181], v174 offset:34816
	ds_read_b128 v[182:185], v174 offset:35840
	ds_read_b128 v[186:189], v174 offset:36864
	ds_read_b128 v[190:193], v174 offset:37888
	ds_read_b128 v[194:197], v174 offset:38912
	ds_read_b128 v[198:201], v174 offset:39936
	global_load_lds_dwordx4 v142, s[10:11]
	s_mov_b32 m0, s51
	s_nop 0
	global_load_lds_dwordx4 v138, s[10:11]
	s_add_i32 s10, 0, 0x1c000
	v_add_u32_e32 v177, s10, v171
	ds_read_b128 v[202:205], v177
	ds_read_b128 v[206:209], v177 offset:1024
	ds_read_b128 v[212:215], v177 offset:2048
	ds_read_b128 v[216:219], v177 offset:3072
	s_waitcnt vmcnt(8)
	s_waitcnt lgkmcnt(4)
	s_setprio 1
	s_barrier
	v_mfma_f32_16x16x32_bf16 v[124:127], v[128:131], v[162:165], v[124:127]
	v_mfma_f32_16x16x32_bf16 v[120:123], v[154:157], v[162:165], v[120:123]
	v_mfma_f32_16x16x32_bf16 v[108:111], v[128:131], v[178:181], v[108:111]
	v_mfma_f32_16x16x32_bf16 v[104:107], v[154:157], v[178:181], v[104:107]
	v_mfma_f32_16x16x32_bf16 v[100:103], v[128:131], v[186:189], v[100:103]
	v_mfma_f32_16x16x32_bf16 v[92:95], v[154:157], v[186:189], v[92:95]
	v_mfma_f32_16x16x32_bf16 v[84:87], v[128:131], v[194:197], v[84:87]
	v_mfma_f32_16x16x32_bf16 v[76:79], v[154:157], v[194:197], v[76:79]
	v_mfma_f32_16x16x32_bf16 v[124:127], v[132:135], v[166:169], v[124:127]
	v_mfma_f32_16x16x32_bf16 v[120:123], v[158:161], v[166:169], v[120:123]
	v_mfma_f32_16x16x32_bf16 v[108:111], v[132:135], v[182:185], v[108:111]
	v_mfma_f32_16x16x32_bf16 v[104:107], v[158:161], v[182:185], v[104:107]
	v_mfma_f32_16x16x32_bf16 v[100:103], v[132:135], v[190:193], v[100:103]
	v_mfma_f32_16x16x32_bf16 v[92:95], v[158:161], v[190:193], v[92:95]
	v_mfma_f32_16x16x32_bf16 v[84:87], v[132:135], v[198:201], v[84:87]
	v_mfma_f32_16x16x32_bf16 v[76:79], v[158:161], v[198:201], v[76:79]
	s_waitcnt lgkmcnt(0)
	v_mfma_f32_16x16x32_bf16 v[116:119], v[202:205], v[162:165], v[116:119]
	v_mfma_f32_16x16x32_bf16 v[112:115], v[212:215], v[162:165], v[112:115]
	v_mfma_f32_16x16x32_bf16 v[96:99], v[202:205], v[178:181], v[96:99]
	v_mfma_f32_16x16x32_bf16 v[88:91], v[212:215], v[178:181], v[88:91]
	v_mfma_f32_16x16x32_bf16 v[80:83], v[202:205], v[186:189], v[80:83]
	v_mfma_f32_16x16x32_bf16 v[72:75], v[212:215], v[186:189], v[72:75]
	v_mfma_f32_16x16x32_bf16 v[68:71], v[202:205], v[194:197], v[68:71]
	v_mfma_f32_16x16x32_bf16 v[64:67], v[212:215], v[194:197], v[64:67]
	v_mfma_f32_16x16x32_bf16 v[116:119], v[206:209], v[166:169], v[116:119]
	v_mfma_f32_16x16x32_bf16 v[112:115], v[216:219], v[166:169], v[112:115]
	v_mfma_f32_16x16x32_bf16 v[96:99], v[206:209], v[182:185], v[96:99]
	v_mfma_f32_16x16x32_bf16 v[88:91], v[216:219], v[182:185], v[88:91]
	v_mfma_f32_16x16x32_bf16 v[80:83], v[206:209], v[190:193], v[80:83]
	v_mfma_f32_16x16x32_bf16 v[72:75], v[216:219], v[190:193], v[72:75]
	v_mfma_f32_16x16x32_bf16 v[68:71], v[206:209], v[198:201], v[68:71]
	v_mfma_f32_16x16x32_bf16 v[64:67], v[216:219], v[198:201], v[64:67]
	s_barrier
	s_setprio 0
	s_add_i32 s11, s53, s41
	ds_read_b128 v[162:165], v174 offset:49152
	ds_read_b128 v[166:169], v174 offset:50176
	ds_read_b128 v[178:181], v174 offset:51200
	ds_read_b128 v[182:185], v174 offset:52224
	ds_read_b128 v[186:189], v174 offset:53248
	ds_read_b128 v[190:193], v174 offset:54272
	ds_read_b128 v[194:197], v174 offset:55296
	ds_read_b128 v[198:201], v174 offset:56320
	s_mov_b32 m0, s11
	s_nop 0
	global_load_lds_dwordx4 v140, s[98:99]
	s_add_i32 m0, s11, 0x2000
	s_nop 0
	global_load_lds_dwordx4 v136, s[98:99]
	s_mov_b32 m0, s56
	s_nop 0
	global_load_lds_dwordx4 v142, s[100:101]
	s_mov_b32 m0, s57
	s_nop 0
	global_load_lds_dwordx4 v138, s[100:101]
	s_add_u32 s8, s8, 0x80080
	s_addc_u32 s9, s9, 0
	s_add_i32 s10, s10, s41
	s_add_i32 s52, s52, 2
	s_add_u32 s6, s6, 0x100
	s_addc_u32 s7, s7, 0
	s_add_u32 s44, s44, 0x100
	s_addc_u32 s45, s45, 0
	s_cmp_gt_u32 s52, 29
	s_waitcnt vmcnt(6)
	s_waitcnt lgkmcnt(0)
	s_setprio 1
	s_barrier
	v_mfma_f32_16x16x32_bf16 v[60:63], v[128:131], v[162:165], v[60:63]
	s_mov_b32 m0, s10
	v_mfma_f32_16x16x32_bf16 v[56:59], v[154:157], v[162:165], v[56:59]
	global_load_lds_dwordx4 v140, s[8:9]
	v_mfma_f32_16x16x32_bf16 v[52:55], v[128:131], v[178:181], v[52:55]
	s_bitset1_b32 m0, 13
	v_mfma_f32_16x16x32_bf16 v[44:47], v[154:157], v[178:181], v[44:47]
	global_load_lds_dwordx4 v136, s[8:9]
	v_mfma_f32_16x16x32_bf16 v[36:39], v[128:131], v[186:189], v[36:39]
	v_mfma_f32_16x16x32_bf16 v[28:31], v[154:157], v[186:189], v[28:31]
	v_mfma_f32_16x16x32_bf16 v[20:23], v[128:131], v[194:197], v[20:23]
	v_mfma_f32_16x16x32_bf16 v[12:15], v[154:157], v[194:197], v[12:15]
	v_mfma_f32_16x16x32_bf16 v[60:63], v[132:135], v[166:169], v[60:63]
	v_mfma_f32_16x16x32_bf16 v[56:59], v[158:161], v[166:169], v[56:59]
	v_mfma_f32_16x16x32_bf16 v[52:55], v[132:135], v[182:185], v[52:55]
	v_mfma_f32_16x16x32_bf16 v[44:47], v[158:161], v[182:185], v[44:47]
	v_mfma_f32_16x16x32_bf16 v[36:39], v[132:135], v[190:193], v[36:39]
	v_mfma_f32_16x16x32_bf16 v[28:31], v[158:161], v[190:193], v[28:31]
	v_mfma_f32_16x16x32_bf16 v[20:23], v[132:135], v[198:201], v[20:23]
	v_mfma_f32_16x16x32_bf16 v[12:15], v[158:161], v[198:201], v[12:15]
	v_mfma_f32_16x16x32_bf16 v[48:51], v[202:205], v[162:165], v[48:51]
	v_mfma_f32_16x16x32_bf16 v[40:43], v[212:215], v[162:165], v[40:43]
	v_mfma_f32_16x16x32_bf16 v[32:35], v[202:205], v[178:181], v[32:35]
	v_mfma_f32_16x16x32_bf16 v[24:27], v[212:215], v[178:181], v[24:27]
	v_mfma_f32_16x16x32_bf16 v[16:19], v[202:205], v[186:189], v[16:19]
	v_mfma_f32_16x16x32_bf16 v[8:11], v[212:215], v[186:189], v[8:11]
	v_mfma_f32_16x16x32_bf16 v[4:7], v[202:205], v[194:197], v[4:7]
	v_mfma_f32_16x16x32_bf16 v[0:3], v[212:215], v[194:197], v[0:3]
	v_mfma_f32_16x16x32_bf16 v[48:51], v[206:209], v[166:169], v[48:51]
	v_mfma_f32_16x16x32_bf16 v[40:43], v[216:219], v[166:169], v[40:43]
	v_mfma_f32_16x16x32_bf16 v[32:35], v[206:209], v[182:185], v[32:35]
	v_mfma_f32_16x16x32_bf16 v[24:27], v[216:219], v[182:185], v[24:27]
	v_mfma_f32_16x16x32_bf16 v[16:19], v[206:209], v[190:193], v[16:19]
	v_mfma_f32_16x16x32_bf16 v[8:11], v[216:219], v[190:193], v[8:11]
	v_mfma_f32_16x16x32_bf16 v[4:7], v[206:209], v[198:201], v[4:7]
	v_mfma_f32_16x16x32_bf16 v[0:3], v[216:219], v[198:201], v[0:3]
	s_barrier
; DI unsigned pack2(float lo, float hi) { f32x2 v = {lo, hi}; bf16v2 r = __builtin_convertvector(v, bf16v2); return __builtin_bit_cast(unsigned, r); }
; DI float row_rstd(const float* ssq, int row, int fq) {
;   const f32x4 a = *(const f32x4*)(ssq + (size_t)row * 32 + fq * 8), b = *(const f32x4*)(ssq + (size_t)row * 32 + fq * 8 + 4);
;   float sm = ((a[0] + a[1]) + (a[2] + a[3])) + ((b[0] + b[1]) + (b[2] + b[3]));
;   sm += __shfl_xor(sm, 16); sm += __shfl_xor(sm, 32);
;   return rsqrtf(sm * (1.0f / 2048.f) + 1e-6f);
; }
;   DI void operator()(const f32x4 (&acc)[2][2][4][2], const Unit& u, int wr, int wc, int fr, int fq) const {
;     const int row0 = u.pm * BM + wr * 64 + fr, col0 = u.pn * BM + wc * 32 + 8 * fq;
;     float rsv[2][4];
; #pragma unroll
;     for (int ai = 0; ai < 2; ++ai)
; #pragma unroll
;       for (int m = 0; m < 4; ++m) rsv[ai][m] = row_rstd(ssq, row0 + ai * HALF + m * 16, fq);
; #pragma unroll
;     for (int ai = 0; ai < 2; ++ai)
; #pragma unroll
;       for (int m = 0; m < 4; ++m) {
;         const int row = row0 + ai * HALF + m * 16;
;         const float rs = rsv[ai][m];
;         bf16_t* rowp = O + (size_t)row * ldc + col0;
; #pragma unroll
;         for (int bj = 0; bj < 2; ++bj) {
;           const f32x4 v0 = acc[ai][bj][m][0] * rs, v1 = acc[ai][bj][m][1] * rs;
;           u32x4 w; w.x = pack2(v0[0], v0[1]); w.y = pack2(v0[2], v0[3]); w.z = pack2(v1[0], v1[1]); w.w = pack2(v1[2], v1[3]);
;           *(u32x4*)(rowp + bj * HALF) = w;
	s_setprio 0
	s_cbranch_scc0 .LBB0_346
	v_lshl_add_u32 v168, s4, 8, v170
	v_ashrrev_i32_e32 v169, 31, v168
	v_or_b32_e32 v154, 16, v168
	v_lshlrev_b64 v[128:129], 7, v[168:169]
	v_ashrrev_i32_e32 v155, 31, v154
	v_lshl_add_u64 v[128:129], v[144:145], 0, v[128:129]
	v_lshlrev_b64 v[156:157], 7, v[154:155]
	global_load_dwordx4 v[132:135], v[128:129], off
	s_nop 0
	global_load_dwordx4 v[128:131], v[128:129], off offset:16
	v_lshl_add_u64 v[156:157], v[144:145], 0, v[156:157]
	global_load_dwordx4 v[178:181], v[156:157], off
	global_load_dwordx4 v[182:185], v[156:157], off offset:16
	v_or_b32_e32 v160, 32, v168
	v_ashrrev_i32_e32 v161, 31, v160
	v_lshlrev_b64 v[156:157], 7, v[160:161]
	v_lshl_add_u64 v[156:157], v[144:145], 0, v[156:157]
	global_load_dwordx4 v[186:189], v[156:157], off
	global_load_dwordx4 v[190:193], v[156:157], off offset:16
	v_or_b32_e32 v156, 48, v168
	v_ashrrev_i32_e32 v157, 31, v156
	v_lshlrev_b64 v[158:159], 7, v[156:157]
	v_lshl_add_u64 v[158:159], v[144:145], 0, v[158:159]
	global_load_dwordx4 v[194:197], v[158:159], off
	global_load_dwordx4 v[198:201], v[158:159], off offset:16
	v_add_u32_e32 v164, 0x80, v168
	v_ashrrev_i32_e32 v165, 31, v164
	v_lshlrev_b64 v[158:159], 7, v[164:165]
	v_lshl_add_u64 v[158:159], v[144:145], 0, v[158:159]
	global_load_dwordx4 v[202:205], v[158:159], off
	global_load_dwordx4 v[206:209], v[158:159], off offset:16
	v_add_u32_e32 v158, 0x90, v168
	v_ashrrev_i32_e32 v159, 31, v158
	v_lshlrev_b64 v[162:163], 7, v[158:159]
	v_lshl_add_u64 v[162:163], v[144:145], 0, v[162:163]
	global_load_dwordx4 v[212:215], v[162:163], off
	global_load_dwordx4 v[216:219], v[162:163], off offset:16
	v_add_u32_e32 v166, 0xa0, v168
	v_ashrrev_i32_e32 v167, 31, v166
	v_lshlrev_b64 v[162:163], 7, v[166:167]
	v_lshl_add_u64 v[162:163], v[144:145], 0, v[162:163]
	global_load_dwordx4 v[220:223], v[162:163], off
	global_load_dwordx4 v[224:227], v[162:163], off offset:16
	v_add_u32_e32 v162, 0xb0, v168
	v_ashrrev_i32_e32 v163, 31, v162
	v_lshlrev_b64 v[228:229], 7, v[162:163]
	v_lshl_add_u64 v[232:233], v[144:145], 0, v[228:229]
	global_load_dwordx4 v[228:231], v[232:233], off
	s_nop 0
	global_load_dwordx4 v[232:235], v[232:233], off offset:16
	s_waitcnt vmcnt(0)
	v_mov_b32_e32 v236, v132
	v_mov_b32_e32 v237, v128
	v_mov_b32_e32 v128, v133
	v_mov_b32_e32 v132, v134
	v_mov_b32_e32 v133, v130
	v_mov_b32_e32 v130, v135
	v_pk_add_f32 v[130:131], v[132:133], v[130:131]
	v_mov_b32_e32 v132, v178
	v_mov_b32_e32 v133, v182
	v_mov_b32_e32 v182, v179
	v_mov_b32_e32 v134, v180
	v_mov_b32_e32 v135, v184
	v_mov_b32_e32 v184, v181
	v_pk_add_f32 v[128:129], v[236:237], v[128:129]
	v_pk_add_f32 v[132:133], v[132:133], v[182:183]
	v_pk_add_f32 v[134:135], v[134:135], v[184:185]
	v_pk_add_f32 v[128:129], v[128:129], v[130:131]
	v_pk_add_f32 v[130:131], v[132:133], v[134:135]
	v_mov_b32_e32 v133, v128
	v_mov_b32_e32 v132, v130
	v_and_b32_e32 v130, 64, v176
	v_add_u32_e32 v155, 64, v130
	v_xor_b32_e32 v130, 16, v176
	v_cmp_lt_i32_e32 vcc, v130, v155
	v_mov_b32_e32 v128, v131
	v_pk_add_f32 v[128:129], v[132:133], v[128:129]
	v_cndmask_b32_e32 v130, v176, v130, vcc
	v_lshlrev_b32_e32 v157, 2, v130
	ds_bpermute_b32 v131, v157, v129
	ds_bpermute_b32 v130, v157, v128
	v_mov_b32_e32 v178, v186
	v_mov_b32_e32 v179, v190
	v_mov_b32_e32 v190, v187
	v_mov_b32_e32 v186, v194
	s_waitcnt lgkmcnt(0)
	v_pk_add_f32 v[128:129], v[128:129], v[130:131]
	v_xor_b32_e32 v130, 32, v176
	v_cmp_lt_i32_e32 vcc, v130, v155
	v_mov_b32_e32 v187, v198
	v_mov_b32_e32 v198, v195
	v_cndmask_b32_e32 v130, v176, v130, vcc
	v_lshlrev_b32_e32 v155, 2, v130
	ds_bpermute_b32 v131, v155, v129
	ds_bpermute_b32 v130, v155, v128
	v_pk_add_f32 v[182:183], v[186:187], v[198:199]
	v_mov_b32_e32 v180, v188
	v_mov_b32_e32 v181, v192
	v_mov_b32_e32 v192, v189
	s_waitcnt lgkmcnt(0)
	v_pk_add_f32 v[128:129], v[128:129], v[130:131]
	v_mov_b64_e32 v[130:131], s[26:27]
	v_pk_fma_f32 v[128:129], v[128:129], s[24:25], v[130:131] op_sel_hi:[1,0,0]
	v_mov_b32_e32 v188, v196
	v_mul_f32_e32 v159, 0x4b800000, v129
	v_cmp_gt_f32_e32 vcc, s73, v129
	v_mov_b32_e32 v189, v200
	v_mov_b32_e32 v200, v197
	v_cndmask_b32_e32 v129, v129, v159, vcc
	v_rsq_f32_e32 v129, v129
	v_pk_add_f32 v[178:179], v[178:179], v[190:191]
	v_pk_add_f32 v[180:181], v[180:181], v[192:193]
	v_pk_add_f32 v[184:185], v[188:189], v[200:201]
	v_mul_f32_e32 v159, 0x45800000, v129
	v_cndmask_b32_e32 v198, v129, v159, vcc
	v_pk_mul_f32 v[126:127], v[126:127], v[198:199] op_sel_hi:[1,0]
	v_pk_mul_f32 v[124:125], v[124:125], v[198:199] op_sel_hi:[1,0]
	v_pk_mul_f32 v[122:123], v[122:123], v[198:199] op_sel_hi:[1,0]
	v_pk_mul_f32 v[120:121], v[120:121], v[198:199] op_sel_hi:[1,0]
	v_cvt_pk_bf16_f32 v124, v124, v125
	v_cvt_pk_bf16_f32 v125, v126, v127
	v_cvt_pk_bf16_f32 v127, v122, v123
	v_lshl_or_b32 v122, s5, 8, v172
	v_cvt_pk_bf16_f32 v126, v120, v121
	v_ashrrev_i32_e32 v123, 31, v122
	v_mov_b64_e32 v[120:121], s[2:3]
	v_mad_i64_i32 v[168:169], s[4:5], v168, s76, v[120:121]
	v_lshlrev_b64 v[122:123], 1, v[122:123]
	v_lshl_add_u64 v[168:169], v[168:169], 0, v[122:123]
	global_store_dwordx4 v[168:169], v[124:127], off
	v_mov_b32_e32 v194, v202
	v_mov_b32_e32 v195, v206
	v_pk_add_f32 v[124:125], v[178:179], v[180:181]
	v_pk_add_f32 v[126:127], v[182:183], v[184:185]
	v_mov_b32_e32 v179, v124
	v_mov_b32_e32 v178, v126
	v_mov_b32_e32 v124, v127
	v_pk_add_f32 v[124:125], v[178:179], v[124:125]
	ds_bpermute_b32 v127, v157, v125
	ds_bpermute_b32 v126, v157, v124
	v_mov_b32_e32 v206, v203
	v_mov_b32_e32 v196, v204
	v_mov_b32_e32 v197, v208
	v_mov_b32_e32 v208, v205
	v_mov_b32_e32 v202, v212
	v_mov_b32_e32 v203, v216
	v_mov_b32_e32 v216, v213
	v_mov_b32_e32 v204, v214
	v_mov_b32_e32 v205, v218
	v_mov_b32_e32 v218, v215
	v_pk_add_f32 v[186:187], v[194:195], v[206:207]
	v_pk_add_f32 v[188:189], v[196:197], v[208:209]
	v_pk_add_f32 v[190:191], v[202:203], v[216:217]
	v_pk_add_f32 v[192:193], v[204:205], v[218:219]
	v_pk_mul_f32 v[178:179], v[114:115], v[198:199] op_sel_hi:[1,0]
	s_waitcnt lgkmcnt(0)
; DI unsigned pack2(float lo, float hi) { f32x2 v = {lo, hi}; bf16v2 r = __builtin_convertvector(v, bf16v2); return __builtin_bit_cast(unsigned, r); }
; DI float row_rstd(const float* ssq, int row, int fq) {
;   const f32x4 a = *(const f32x4*)(ssq + (size_t)row * 32 + fq * 8), b = *(const f32x4*)(ssq + (size_t)row * 32 + fq * 8 + 4);
;   float sm = ((a[0] + a[1]) + (a[2] + a[3])) + ((b[0] + b[1]) + (b[2] + b[3]));
;   sm += __shfl_xor(sm, 16); sm += __shfl_xor(sm, 32);
;   return rsqrtf(sm * (1.0f / 2048.f) + 1e-6f);
; }
;   DI void operator()(const f32x4 (&acc)[2][2][4][2], const Unit& u, int wr, int wc, int fr, int fq) const {
;     const int row0 = u.pm * BM + wr * 64 + fr, col0 = u.pn * BM + wc * 32 + 8 * fq;
;     float rsv[2][4];
; #pragma unroll
;     for (int ai = 0; ai < 2; ++ai)
; #pragma unroll
;       for (int m = 0; m < 4; ++m) rsv[ai][m] = row_rstd(ssq, row0 + ai * HALF + m * 16, fq);
; #pragma unroll
;     for (int ai = 0; ai < 2; ++ai)
; #pragma unroll
;       for (int m = 0; m < 4; ++m) {
;         const int row = row0 + ai * HALF + m * 16;
;         const float rs = rsv[ai][m];
;         bf16_t* rowp = O + (size_t)row * ldc + col0;
; #pragma unroll
;         for (int bj = 0; bj < 2; ++bj) {
;           const f32x4 v0 = acc[ai][bj][m][0] * rs, v1 = acc[ai][bj][m][1] * rs;
;           u32x4 w; w.x = pack2(v0[0], v0[1]); w.y = pack2(v0[2], v0[3]); w.z = pack2(v1[0], v1[1]); w.w = pack2(v1[2], v1[3]);
;           *(u32x4*)(rowp + bj * HALF) = w;
;         }
;       }
	v_pk_add_f32 v[114:115], v[124:125], v[126:127]
	v_pk_add_f32 v[126:127], v[186:187], v[188:189]
	v_pk_add_f32 v[180:181], v[190:191], v[192:193]
	v_mov_b32_e32 v183, v126
	v_mov_b32_e32 v182, v180
	v_mov_b32_e32 v126, v181
	v_pk_add_f32 v[126:127], v[182:183], v[126:127]
	ds_bpermute_b32 v125, v155, v115
	ds_bpermute_b32 v124, v155, v114
	ds_bpermute_b32 v181, v157, v127
	ds_bpermute_b32 v180, v157, v126
	v_mul_f32_e32 v129, 0x4b800000, v128
	v_cmp_gt_f32_e32 vcc, s73, v128
	s_waitcnt lgkmcnt(2)
	v_pk_add_f32 v[114:115], v[114:115], v[124:125]
	v_mov_b32_e32 v194, v220
	s_waitcnt lgkmcnt(0)
	v_pk_add_f32 v[124:125], v[126:127], v[180:181]
	ds_bpermute_b32 v127, v155, v125
	ds_bpermute_b32 v126, v155, v124
	v_pk_fma_f32 v[114:115], v[114:115], s[24:25], v[130:131] op_sel_hi:[1,0,0]
	v_cndmask_b32_e32 v159, v128, v129, vcc
	v_mul_f32_e32 v128, 0x4b800000, v115
	v_cmp_gt_f32_e64 s[4:5], s73, v115
	v_cmp_gt_f32_e64 s[6:7], s73, v114
	v_mov_b32_e32 v195, v224
	v_cndmask_b32_e64 v161, v115, v128, s[4:5]
	v_mul_f32_e32 v115, 0x4b800000, v114
	v_mov_b32_e32 v224, v221
	v_mov_b32_e32 v196, v222
	v_mov_b32_e32 v197, v226
	v_mov_b32_e32 v226, v223
	v_cndmask_b32_e64 v163, v114, v115, s[6:7]
	s_waitcnt lgkmcnt(0)
	v_pk_add_f32 v[114:115], v[124:125], v[126:127]
	v_pk_add_f32 v[132:133], v[194:195], v[224:225]
	v_pk_add_f32 v[134:135], v[196:197], v[226:227]
	v_mov_b32_e32 v194, v228
	v_mov_b32_e32 v195, v232
	v_mov_b32_e32 v232, v229
	v_mov_b32_e32 v196, v230
	v_mov_b32_e32 v197, v234
	v_mov_b32_e32 v234, v231
	v_pk_fma_f32 v[114:115], v[114:115], s[24:25], v[130:131] op_sel_hi:[1,0,0]
	v_pk_add_f32 v[194:195], v[194:195], v[232:233]
	v_pk_add_f32 v[196:197], v[196:197], v[234:235]
	v_mul_f32_e32 v124, 0x4b800000, v115
	v_cmp_gt_f32_e64 s[8:9], s73, v115
	v_pk_add_f32 v[126:127], v[194:195], v[196:197]
	v_cmp_gt_f32_e64 s[10:11], s73, v114
	v_cndmask_b32_e64 v165, v115, v124, s[8:9]
	v_pk_add_f32 v[124:125], v[132:133], v[134:135]
	v_mov_b32_e32 v128, v126
	v_mov_b32_e32 v129, v124
	v_mov_b32_e32 v124, v127
	v_pk_add_f32 v[124:125], v[128:129], v[124:125]
	ds_bpermute_b32 v127, v157, v125
	ds_bpermute_b32 v126, v157, v124
	v_rsq_f32_e32 v128, v159
	v_mul_f32_e32 v115, 0x4b800000, v114
	v_cndmask_b32_e64 v129, v114, v115, s[10:11]
	v_pk_mul_f32 v[116:117], v[116:117], v[198:199] op_sel_hi:[1,0]
	s_waitcnt lgkmcnt(0)
	v_pk_add_f32 v[114:115], v[124:125], v[126:127]
	ds_bpermute_b32 v125, v155, v115
	ds_bpermute_b32 v124, v155, v114
	v_mul_f32_e32 v126, 0x45800000, v128
	v_rsq_f32_e32 v127, v161
	v_cndmask_b32_e32 v126, v128, v126, vcc
	v_rsq_f32_e32 v128, v163
	s_waitcnt lgkmcnt(0)
	v_pk_add_f32 v[114:115], v[114:115], v[124:125]
	v_mul_f32_e32 v124, 0x45800000, v127
	v_cndmask_b32_e64 v124, v127, v124, s[4:5]
	v_mul_f32_e32 v127, 0x45800000, v128
	v_pk_fma_f32 v[114:115], v[114:115], s[24:25], v[130:131] op_sel_hi:[1,0,0]
	v_rsq_f32_e32 v125, v165
	v_cndmask_b32_e64 v128, v128, v127, s[6:7]
	v_rsq_f32_e32 v127, v129
	v_mul_f32_e32 v129, 0x4b800000, v115
	v_cmp_gt_f32_e32 vcc, s73, v115
	v_cmp_gt_f32_e64 s[4:5], s73, v114
	v_pk_mul_f32 v[118:119], v[118:119], v[198:199] op_sel_hi:[1,0]
	v_cndmask_b32_e32 v129, v115, v129, vcc
	v_mul_f32_e32 v115, 0x4b800000, v114
	v_cndmask_b32_e64 v131, v114, v115, s[4:5]
	v_cvt_pk_bf16_f32 v114, v116, v117
	v_rsq_f32_e32 v117, v129
	v_cvt_pk_bf16_f32 v115, v118, v119
	v_rsq_f32_e32 v119, v131
	v_mul_f32_e32 v116, 0x45800000, v125
	v_pk_mul_f32 v[112:113], v[112:113], v[198:199] op_sel_hi:[1,0]
	v_cndmask_b32_e64 v118, v125, v116, s[8:9]
	v_mul_f32_e32 v116, 0x45800000, v127
	v_cndmask_b32_e64 v130, v127, v116, s[10:11]
	v_cvt_pk_bf16_f32 v116, v112, v113
	v_mul_f32_e32 v112, 0x45800000, v117
	v_cndmask_b32_e32 v132, v117, v112, vcc
	v_mul_f32_e32 v112, 0x45800000, v119
	v_cvt_pk_bf16_f32 v117, v178, v179
	v_cndmask_b32_e64 v112, v119, v112, s[4:5]
	global_store_dwordx4 v[168:169], v[114:117], off offset:256
	v_pk_mul_f32 v[110:111], v[110:111], v[126:127] op_sel_hi:[1,0]
	v_pk_mul_f32 v[108:109], v[108:109], v[126:127] op_sel_hi:[1,0]
	v_mad_i64_i32 v[114:115], s[4:5], v154, s76, v[120:121]
	v_pk_mul_f32 v[116:117], v[106:107], v[126:127] op_sel_hi:[1,0]
	v_pk_mul_f32 v[106:107], v[104:105], v[126:127] op_sel_hi:[1,0]
	v_lshl_add_u64 v[114:115], v[114:115], 0, v[122:123]
	v_cvt_pk_bf16_f32 v104, v108, v109
	v_cvt_pk_bf16_f32 v105, v110, v111
	v_cvt_pk_bf16_f32 v106, v106, v107
	v_cvt_pk_bf16_f32 v107, v116, v117
	global_store_dwordx4 v[114:115], v[104:107], off
	v_pk_mul_f32 v[98:99], v[98:99], v[126:127] op_sel_hi:[1,0]
	v_pk_mul_f32 v[96:97], v[96:97], v[126:127] op_sel_hi:[1,0]
	v_pk_mul_f32 v[104:105], v[90:91], v[126:127] op_sel_hi:[1,0]
	v_pk_mul_f32 v[90:91], v[88:89], v[126:127] op_sel_hi:[1,0]
	v_cvt_pk_bf16_f32 v88, v96, v97
	v_cvt_pk_bf16_f32 v89, v98, v99
	v_cvt_pk_bf16_f32 v90, v90, v91
	v_cvt_pk_bf16_f32 v91, v104, v105
	global_store_dwordx4 v[114:115], v[88:91], off offset:256
	v_pk_mul_f32 v[94:95], v[94:95], v[124:125] op_sel_hi:[1,0]
	v_pk_mul_f32 v[92:93], v[92:93], v[124:125] op_sel_hi:[1,0]
	v_mad_i64_i32 v[88:89], s[4:5], v160, s76, v[120:121]
	v_lshl_add_u64 v[96:97], v[88:89], 0, v[122:123]
	v_pk_mul_f32 v[90:91], v[102:103], v[124:125] op_sel_hi:[1,0]
	v_pk_mul_f32 v[88:89], v[100:101], v[124:125] op_sel_hi:[1,0]
	v_pk_mul_f32 v[82:83], v[82:83], v[124:125] op_sel_hi:[1,0]
	v_cvt_pk_bf16_f32 v88, v88, v89
	v_cvt_pk_bf16_f32 v89, v90, v91
	v_cvt_pk_bf16_f32 v90, v92, v93
; DI unsigned pack2(float lo, float hi) { f32x2 v = {lo, hi}; bf16v2 r = __builtin_convertvector(v, bf16v2); return __builtin_bit_cast(unsigned, r); }
; #define PG8_WAIT_V(n) asm volatile("s_waitcnt vmcnt(" #n ")" ::: "memory")
; #define PG8_BAR __builtin_amdgcn_s_barrier()
;   DI void operator()(const f32x4 (&acc)[2][2][4][2], const Unit& u, int wr, int wc, int fr, int fq) const {
;     ...
;       for (int m = 0; m < 4; ++m) {
;         const int row = row0 + ai * HALF + m * 16;
;         const float rs = rsv[ai][m];
;         bf16_t* rowp = O + (size_t)row * ldc + col0;
; #pragma unroll
;         for (int bj = 0; bj < 2; ++bj) {
;           const f32x4 v0 = acc[ai][bj][m][0] * rs, v1 = acc[ai][bj][m][1] * rs;
;           u32x4 w; w.x = pack2(v0[0], v0[1]); w.y = pack2(v0[2], v0[3]); w.z = pack2(v1[0], v1[1]); w.w = pack2(v1[2], v1[3]);
;           *(u32x4*)(rowp + bj * HALF) = w;
;         }
;       }
; template <class Epi, class Sched = StaticOrder>
; DI void gemm_phase(LAS unsigned char* lds, const Gemm g, const Sched& S, const Epi& E) {
;     ...
;     if (!has_next) break;
; #pragma unroll
;     for (int a = 0; a < 2; ++a)
; #pragma unroll
;       for (int b = 0; b < 2; ++b)
; #pragma unroll
;         for (int m = 0; m < 4; ++m)
; #pragma unroll
;           for (int n = 0; n < 2; ++n) acc[a][b][m][n] = (f32x4){0.f, 0.f, 0.f, 0.f};
;     cur = nxt; cA = nA; cB = nB; ++ui;
;   }
;   PG8_WAIT_V(0);
;   if (wr == 0) PG8_BAR;
;   PG8_BAR;
	v_cvt_pk_bf16_f32 v91, v94, v95
	global_store_dwordx4 v[96:97], v[88:91], off
	v_pk_mul_f32 v[80:81], v[80:81], v[124:125] op_sel_hi:[1,0]
	v_pk_mul_f32 v[78:79], v[78:79], v[128:129] op_sel_hi:[1,0]
	v_pk_mul_f32 v[88:89], v[74:75], v[124:125] op_sel_hi:[1,0]
	v_pk_mul_f32 v[74:75], v[72:73], v[124:125] op_sel_hi:[1,0]
	v_cvt_pk_bf16_f32 v72, v80, v81
	v_cvt_pk_bf16_f32 v73, v82, v83
	v_cvt_pk_bf16_f32 v74, v74, v75
	v_cvt_pk_bf16_f32 v75, v88, v89
	global_store_dwordx4 v[96:97], v[72:75], off offset:256
	v_pk_mul_f32 v[76:77], v[76:77], v[128:129] op_sel_hi:[1,0]
	v_pk_mul_f32 v[70:71], v[70:71], v[128:129] op_sel_hi:[1,0]
	v_mad_i64_i32 v[72:73], s[4:5], v156, s76, v[120:121]
	v_lshl_add_u64 v[80:81], v[72:73], 0, v[122:123]
	v_pk_mul_f32 v[74:75], v[86:87], v[128:129] op_sel_hi:[1,0]
	v_pk_mul_f32 v[72:73], v[84:85], v[128:129] op_sel_hi:[1,0]
	v_pk_mul_f32 v[68:69], v[68:69], v[128:129] op_sel_hi:[1,0]
	v_cvt_pk_bf16_f32 v72, v72, v73
	v_cvt_pk_bf16_f32 v73, v74, v75
	v_cvt_pk_bf16_f32 v74, v76, v77
	v_cvt_pk_bf16_f32 v75, v78, v79
	global_store_dwordx4 v[80:81], v[72:75], off
	v_pk_mul_f32 v[62:63], v[62:63], v[118:119] op_sel_hi:[1,0]
	v_pk_mul_f32 v[60:61], v[60:61], v[118:119] op_sel_hi:[1,0]
	v_pk_mul_f32 v[72:73], v[66:67], v[128:129] op_sel_hi:[1,0]
	v_pk_mul_f32 v[66:67], v[64:65], v[128:129] op_sel_hi:[1,0]
	v_cvt_pk_bf16_f32 v64, v68, v69
	v_cvt_pk_bf16_f32 v65, v70, v71
	v_cvt_pk_bf16_f32 v66, v66, v67
	v_cvt_pk_bf16_f32 v67, v72, v73
	global_store_dwordx4 v[80:81], v[64:67], off offset:256
	v_pk_mul_f32 v[50:51], v[50:51], v[118:119] op_sel_hi:[1,0]
	v_pk_mul_f32 v[48:49], v[48:49], v[118:119] op_sel_hi:[1,0]
	v_mad_i64_i32 v[64:65], s[4:5], v164, s76, v[120:121]
	v_pk_mul_f32 v[66:67], v[58:59], v[118:119] op_sel_hi:[1,0]
	v_pk_mul_f32 v[58:59], v[56:57], v[118:119] op_sel_hi:[1,0]
	v_lshl_add_u64 v[64:65], v[64:65], 0, v[122:123]
	v_cvt_pk_bf16_f32 v56, v60, v61
	v_cvt_pk_bf16_f32 v57, v62, v63
	v_cvt_pk_bf16_f32 v58, v58, v59
	v_cvt_pk_bf16_f32 v59, v66, v67
	global_store_dwordx4 v[64:65], v[56:59], off
	v_pk_mul_f32 v[46:47], v[46:47], v[130:131] op_sel_hi:[1,0]
	v_pk_mul_f32 v[44:45], v[44:45], v[130:131] op_sel_hi:[1,0]
	v_pk_mul_f32 v[56:57], v[42:43], v[118:119] op_sel_hi:[1,0]
	v_pk_mul_f32 v[42:43], v[40:41], v[118:119] op_sel_hi:[1,0]
	v_cvt_pk_bf16_f32 v40, v48, v49
	v_cvt_pk_bf16_f32 v41, v50, v51
	v_cvt_pk_bf16_f32 v42, v42, v43
	v_cvt_pk_bf16_f32 v43, v56, v57
	global_store_dwordx4 v[64:65], v[40:43], off offset:256
	v_pk_mul_f32 v[34:35], v[34:35], v[130:131] op_sel_hi:[1,0]
	v_pk_mul_f32 v[32:33], v[32:33], v[130:131] op_sel_hi:[1,0]
	v_mad_i64_i32 v[40:41], s[4:5], v158, s76, v[120:121]
	v_lshl_add_u64 v[48:49], v[40:41], 0, v[122:123]
	v_pk_mul_f32 v[42:43], v[54:55], v[130:131] op_sel_hi:[1,0]
	v_pk_mul_f32 v[40:41], v[52:53], v[130:131] op_sel_hi:[1,0]
	v_pk_mul_f32 v[30:31], v[30:31], v[132:133] op_sel_hi:[1,0]
	v_cvt_pk_bf16_f32 v40, v40, v41
	v_cvt_pk_bf16_f32 v41, v42, v43
	v_cvt_pk_bf16_f32 v42, v44, v45
	v_cvt_pk_bf16_f32 v43, v46, v47
	global_store_dwordx4 v[48:49], v[40:43], off
	v_pk_mul_f32 v[28:29], v[28:29], v[132:133] op_sel_hi:[1,0]
	v_pk_mul_f32 v[18:19], v[18:19], v[132:133] op_sel_hi:[1,0]
	v_pk_mul_f32 v[40:41], v[26:27], v[130:131] op_sel_hi:[1,0]
	v_pk_mul_f32 v[26:27], v[24:25], v[130:131] op_sel_hi:[1,0]
	v_cvt_pk_bf16_f32 v24, v32, v33
	v_cvt_pk_bf16_f32 v25, v34, v35
	v_cvt_pk_bf16_f32 v26, v26, v27
	v_cvt_pk_bf16_f32 v27, v40, v41
	global_store_dwordx4 v[48:49], v[24:27], off offset:256
	v_pk_mul_f32 v[16:17], v[16:17], v[132:133] op_sel_hi:[1,0]
	v_pk_mul_f32 v[14:15], v[14:15], v[112:113] op_sel_hi:[1,0]
	v_mad_i64_i32 v[24:25], s[4:5], v166, s76, v[120:121]
	v_lshl_add_u64 v[32:33], v[24:25], 0, v[122:123]
	v_pk_mul_f32 v[26:27], v[38:39], v[132:133] op_sel_hi:[1,0]
	v_pk_mul_f32 v[24:25], v[36:37], v[132:133] op_sel_hi:[1,0]
	v_pk_mul_f32 v[12:13], v[12:13], v[112:113] op_sel_hi:[1,0]
	v_cvt_pk_bf16_f32 v24, v24, v25
	v_cvt_pk_bf16_f32 v25, v26, v27
	v_cvt_pk_bf16_f32 v26, v28, v29
	v_cvt_pk_bf16_f32 v27, v30, v31
	global_store_dwordx4 v[32:33], v[24:27], off
	v_pk_mul_f32 v[6:7], v[6:7], v[112:113] op_sel_hi:[1,0]
	v_pk_mul_f32 v[4:5], v[4:5], v[112:113] op_sel_hi:[1,0]
	v_pk_mul_f32 v[24:25], v[10:11], v[132:133] op_sel_hi:[1,0]
	v_pk_mul_f32 v[10:11], v[8:9], v[132:133] op_sel_hi:[1,0]
	v_cvt_pk_bf16_f32 v8, v16, v17
	v_cvt_pk_bf16_f32 v9, v18, v19
	v_cvt_pk_bf16_f32 v10, v10, v11
	v_cvt_pk_bf16_f32 v11, v24, v25
	global_store_dwordx4 v[32:33], v[8:11], off offset:256
	s_and_b64 vcc, exec, s[0:1]
	s_mov_b64 s[8:9], s[36:37]
	v_mad_i64_i32 v[8:9], s[4:5], v162, s76, v[120:121]
	v_lshl_add_u64 v[16:17], v[8:9], 0, v[122:123]
	v_pk_mul_f32 v[10:11], v[22:23], v[112:113] op_sel_hi:[1,0]
	v_pk_mul_f32 v[8:9], v[20:21], v[112:113] op_sel_hi:[1,0]
	s_mov_b32 s5, s28
	v_cvt_pk_bf16_f32 v8, v8, v9
	v_cvt_pk_bf16_f32 v9, v10, v11
	v_cvt_pk_bf16_f32 v10, v12, v13
	v_cvt_pk_bf16_f32 v11, v14, v15
	global_store_dwordx4 v[16:17], v[8:11], off
	s_mov_b32 s4, s30
	s_mov_b64 s[6:7], s[34:35]
	v_pk_mul_f32 v[8:9], v[2:3], v[112:113] op_sel_hi:[1,0]
	v_pk_mul_f32 v[2:3], v[0:1], v[112:113] op_sel_hi:[1,0]
	v_cvt_pk_bf16_f32 v0, v4, v5
	v_cvt_pk_bf16_f32 v1, v6, v7
	v_cvt_pk_bf16_f32 v2, v2, v3
	v_cvt_pk_bf16_f32 v3, v8, v9
	global_store_dwordx4 v[16:17], v[0:3], off offset:256
	s_cbranch_vccz .LBB0_343
	s_waitcnt vmcnt(0)
	s_cmpk_gt_u32 s27, 0xff
	s_cbranch_scc1 .LBB0_350
	s_barrier

; #define PG8_STAGE(bufoff, gbase, voff) do { _Pragma("unroll") for (int _i = 0; _i < 2; ++_i) \
;     __builtin_amdgcn_global_load_lds((const unsigned*)((const char*)(gbase) + (voff)[_i]), (LAS unsigned*)(lds + (bufoff) + ldsw + _i * 8192), 16, 0, 0); } while (0)
; #define PG8_LDA(dst, b, h) do { _Pragma("unroll") for (int m = 0; m < 4; ++m) _Pragma("unroll") for (int k = 0; k < 2; ++k) dst[m][k] = *(const LAS bf16x8*)(lds + PG8_SA(b, h) + aoff + m * 2048 + k * 1024); } while (0)
; #define PG8_LDB(dst, b, h) do { _Pragma("unroll") for (int n = 0; n < 2; ++n) _Pragma("unroll") for (int k = 0; k < 2; ++k) dst[n][k] = *(const LAS bf16x8*)(lds + PG8_SB(b, h) + boff + n * 2048 + k * 1024); } while (0)
; #define PG8_MMA(ai, bj, At, Bt) do { __builtin_amdgcn_s_setprio(1); _Pragma("unroll") for (int m = 0; m < 4; ++m) _Pragma("unroll") for (int n = 0; n < 2; ++n) _Pragma("unroll") for (int k = 0; k < 2; ++k) \
;     acc[ai][bj][m][n] = __builtin_amdgcn_mfma_f32_16x16x32_bf16(Bt[n][k], At[m][k], acc[ai][bj][m][n], 0, 0, 0); __builtin_amdgcn_s_setprio(0); } while (0)
; #define PG8_WAIT_V(n) asm volatile("s_waitcnt vmcnt(" #n ")" ::: "memory")
; #define PG8_WAIT_L(n) asm volatile("s_waitcnt lgkmcnt(" #n ")" ::: "memory")
; #define PG8_BAR __builtin_amdgcn_s_barrier()
; #define PG8_SCHED __builtin_amdgcn_sched_barrier(0)
; template <class Epi, class Sched = StaticOrder>
; DI void gemm_phase(LAS unsigned char* lds, const Gemm g, const Sched& S, const Epi& E) {
;     ...
;       PG8_LDB(B0, 0, 0); PG8_SCHED; PG8_LDA(At, 0, 0); PG8_STAGE(PG8_SA(1, 1), a1 + hstep, voffA);
;       PG8_WAIT_L(8); PG8_BAR; PG8_WAIT_L(0); PG8_MMA(0, 0, At, B0); PG8_BAR; PG8_SCHED;
;       PG8_LDB(B1, 0, 1); PG8_STAGE(PG8_SB(0, 0), b2, voffB);
;       PG8_BAR; PG8_WAIT_L(0); PG8_MMA(0, 1, At, B1); PG8_BAR;
;       PG8_LDA(At, 0, 1); PG8_STAGE(PG8_SA(0, 0), a2, voffA);
;       PG8_BAR; PG8_WAIT_L(0); PG8_MMA(1, 0, At, B0); PG8_BAR; PG8_SCHED;
;       PG8_STAGE(PG8_SB(0, 1), b2 + hstep, voffB);
;       PG8_WAIT_V(6); PG8_BAR; PG8_MMA(1, 1, At, B1); PG8_BAR;
.LBB0_728:
	ds_read_b128 v[128:131], v207
	ds_read_b128 v[132:135], v207 offset:1024
	ds_read_b128 v[136:139], v207 offset:2048
	ds_read_b128 v[140:143], v207 offset:3072
	s_add_u32 s24, s22, 0xfff80080
	s_addc_u32 s25, s23, -1
	s_cmp_eq_u32 s53, 28
	s_cselect_b32 s27, s17, s25
	s_cselect_b32 s26, s43, s24
	s_cselect_b32 s25, s15, s52
	s_cselect_b32 s24, s44, s45
	s_add_i32 m0, s37, 0xc000
	ds_read_b128 v[144:147], v208
	ds_read_b128 v[148:151], v208 offset:1024
	ds_read_b128 v[152:155], v208 offset:2048
	ds_read_b128 v[156:159], v208 offset:3072
	ds_read_b128 v[160:163], v208 offset:4096
	ds_read_b128 v[164:167], v208 offset:5120
	ds_read_b128 v[168:171], v208 offset:6144
	ds_read_b128 v[172:175], v208 offset:7168
	global_load_lds_dwordx4 v184, s[22:23]
	s_add_i32 m0, s37, 0xe000
	s_nop 0
	global_load_lds_dwordx4 v186, s[22:23]
	ds_read_b128 v[192:195], v209
	ds_read_b128 v[196:199], v209 offset:1024
	ds_read_b128 v[200:203], v209 offset:2048
	ds_read_b128 v[212:215], v209 offset:3072
	s_waitcnt vmcnt(8)
	s_waitcnt lgkmcnt(4)
	s_setprio 1
	s_barrier
	v_mfma_f32_16x16x32_bf16 v[124:127], v[128:131], v[144:147], v[124:127]
	v_mfma_f32_16x16x32_bf16 v[120:123], v[136:139], v[144:147], v[120:123]
	v_mfma_f32_16x16x32_bf16 v[108:111], v[128:131], v[152:155], v[108:111]
	v_mfma_f32_16x16x32_bf16 v[104:107], v[136:139], v[152:155], v[104:107]
	v_mfma_f32_16x16x32_bf16 v[92:95], v[128:131], v[160:163], v[92:95]
	v_mfma_f32_16x16x32_bf16 v[88:91], v[136:139], v[160:163], v[88:91]
	v_mfma_f32_16x16x32_bf16 v[76:79], v[128:131], v[168:171], v[76:79]
	v_mfma_f32_16x16x32_bf16 v[72:75], v[136:139], v[168:171], v[72:75]
	v_mfma_f32_16x16x32_bf16 v[124:127], v[132:135], v[148:151], v[124:127]
	v_mfma_f32_16x16x32_bf16 v[120:123], v[140:143], v[148:151], v[120:123]
	v_mfma_f32_16x16x32_bf16 v[108:111], v[132:135], v[156:159], v[108:111]
	v_mfma_f32_16x16x32_bf16 v[104:107], v[140:143], v[156:159], v[104:107]
	v_mfma_f32_16x16x32_bf16 v[92:95], v[132:135], v[164:167], v[92:95]
	v_mfma_f32_16x16x32_bf16 v[88:91], v[140:143], v[164:167], v[88:91]
	v_mfma_f32_16x16x32_bf16 v[76:79], v[132:135], v[172:175], v[76:79]
	v_mfma_f32_16x16x32_bf16 v[72:75], v[140:143], v[172:175], v[72:75]
	s_waitcnt lgkmcnt(0)
	v_mfma_f32_16x16x32_bf16 v[116:119], v[192:195], v[144:147], v[116:119]
	v_mfma_f32_16x16x32_bf16 v[112:115], v[200:203], v[144:147], v[112:115]
	v_mfma_f32_16x16x32_bf16 v[100:103], v[192:195], v[152:155], v[100:103]
	v_mfma_f32_16x16x32_bf16 v[96:99], v[200:203], v[152:155], v[96:99]
	v_mfma_f32_16x16x32_bf16 v[84:87], v[192:195], v[160:163], v[84:87]
	v_mfma_f32_16x16x32_bf16 v[80:83], v[200:203], v[160:163], v[80:83]
	v_mfma_f32_16x16x32_bf16 v[68:71], v[192:195], v[168:171], v[68:71]
	v_mfma_f32_16x16x32_bf16 v[64:67], v[200:203], v[168:171], v[64:67]
	v_mfma_f32_16x16x32_bf16 v[116:119], v[196:199], v[148:151], v[116:119]
	v_mfma_f32_16x16x32_bf16 v[112:115], v[212:215], v[148:151], v[112:115]
	v_mfma_f32_16x16x32_bf16 v[100:103], v[196:199], v[156:159], v[100:103]
	v_mfma_f32_16x16x32_bf16 v[96:99], v[212:215], v[156:159], v[96:99]
	v_mfma_f32_16x16x32_bf16 v[84:87], v[196:199], v[164:167], v[84:87]
	v_mfma_f32_16x16x32_bf16 v[80:83], v[212:215], v[164:167], v[80:83]
	v_mfma_f32_16x16x32_bf16 v[68:71], v[196:199], v[172:175], v[68:71]
	v_mfma_f32_16x16x32_bf16 v[64:67], v[212:215], v[172:175], v[64:67]
	s_barrier
	s_setprio 0
	s_add_i32 s54, s50, s35
	s_add_u32 s98, s24, 0x80
	s_addc_u32 s99, s25, 0
	s_add_u32 s100, s26, 0x80
	s_addc_u32 s101, s27, 0
	ds_read_b128 v[144:147], v208 offset:16384
	ds_read_b128 v[148:151], v208 offset:17408
	ds_read_b128 v[152:155], v208 offset:18432
	ds_read_b128 v[156:159], v208 offset:19456
	ds_read_b128 v[160:163], v208 offset:20480
	ds_read_b128 v[164:167], v208 offset:21504
	ds_read_b128 v[168:171], v208 offset:22528
	ds_read_b128 v[172:175], v208 offset:23552
	s_mov_b32 m0, s54
	s_nop 0
	global_load_lds_dwordx4 v180, s[24:25]
	s_add_i32 m0, s54, 0x2000
	s_nop 0
	global_load_lds_dwordx4 v176, s[24:25]
	s_mov_b32 m0, s37
	s_nop 0
	global_load_lds_dwordx4 v182, s[26:27]
	s_mov_b32 m0, s38
	s_nop 0
	global_load_lds_dwordx4 v178, s[26:27]
	s_add_u32 s54, s24, 0x80000
	s_addc_u32 s55, s25, 0
	s_add_i32 s57, s51, s35
	s_waitcnt vmcnt(6)
	s_waitcnt lgkmcnt(0)
	s_setprio 1
	s_barrier
	v_mfma_f32_16x16x32_bf16 v[60:63], v[128:131], v[144:147], v[60:63]
	s_mov_b32 m0, s57
	v_mfma_f32_16x16x32_bf16 v[56:59], v[136:139], v[144:147], v[56:59]
	global_load_lds_dwordx4 v180, s[54:55]
	v_mfma_f32_16x16x32_bf16 v[44:47], v[128:131], v[152:155], v[44:47]
	s_bitset1_b32 m0, 13
	v_mfma_f32_16x16x32_bf16 v[40:43], v[136:139], v[152:155], v[40:43]
	global_load_lds_dwordx4 v176, s[54:55]
	v_mfma_f32_16x16x32_bf16 v[28:31], v[128:131], v[160:163], v[28:31]
	v_mfma_f32_16x16x32_bf16 v[24:27], v[136:139], v[160:163], v[24:27]
	v_mfma_f32_16x16x32_bf16 v[12:15], v[128:131], v[168:171], v[12:15]
	v_mfma_f32_16x16x32_bf16 v[8:11], v[136:139], v[168:171], v[8:11]
	v_mfma_f32_16x16x32_bf16 v[60:63], v[132:135], v[148:151], v[60:63]
	v_mfma_f32_16x16x32_bf16 v[56:59], v[140:143], v[148:151], v[56:59]
	v_mfma_f32_16x16x32_bf16 v[44:47], v[132:135], v[156:159], v[44:47]
	v_mfma_f32_16x16x32_bf16 v[40:43], v[140:143], v[156:159], v[40:43]
	v_mfma_f32_16x16x32_bf16 v[28:31], v[132:135], v[164:167], v[28:31]
	v_mfma_f32_16x16x32_bf16 v[24:27], v[140:143], v[164:167], v[24:27]
	v_mfma_f32_16x16x32_bf16 v[12:15], v[132:135], v[172:175], v[12:15]
	v_mfma_f32_16x16x32_bf16 v[8:11], v[140:143], v[172:175], v[8:11]
	v_mfma_f32_16x16x32_bf16 v[52:55], v[192:195], v[144:147], v[52:55]
	v_mfma_f32_16x16x32_bf16 v[48:51], v[200:203], v[144:147], v[48:51]
	v_mfma_f32_16x16x32_bf16 v[36:39], v[192:195], v[152:155], v[36:39]
	v_mfma_f32_16x16x32_bf16 v[32:35], v[200:203], v[152:155], v[32:35]
	v_mfma_f32_16x16x32_bf16 v[20:23], v[192:195], v[160:163], v[20:23]
	v_mfma_f32_16x16x32_bf16 v[16:19], v[200:203], v[160:163], v[16:19]
	v_mfma_f32_16x16x32_bf16 v[4:7], v[192:195], v[168:171], v[4:7]
	v_mfma_f32_16x16x32_bf16 v[0:3], v[200:203], v[168:171], v[0:3]
	v_mfma_f32_16x16x32_bf16 v[52:55], v[196:199], v[148:151], v[52:55]
	v_mfma_f32_16x16x32_bf16 v[48:51], v[212:215], v[148:151], v[48:51]
	v_mfma_f32_16x16x32_bf16 v[36:39], v[196:199], v[156:159], v[36:39]
	v_mfma_f32_16x16x32_bf16 v[32:35], v[212:215], v[156:159], v[32:35]
	v_mfma_f32_16x16x32_bf16 v[20:23], v[196:199], v[164:167], v[20:23]
	v_mfma_f32_16x16x32_bf16 v[16:19], v[212:215], v[164:167], v[16:19]
	v_mfma_f32_16x16x32_bf16 v[4:7], v[196:199], v[172:175], v[4:7]
	v_mfma_f32_16x16x32_bf16 v[0:3], v[212:215], v[172:175], v[0:3]
	s_barrier
; #define PG8_STAGE(bufoff, gbase, voff) do { _Pragma("unroll") for (int _i = 0; _i < 2; ++_i) \
;     __builtin_amdgcn_global_load_lds((const unsigned*)((const char*)(gbase) + (voff)[_i]), (LAS unsigned*)(lds + (bufoff) + ldsw + _i * 8192), 16, 0, 0); } while (0)
; #define PG8_LDA(dst, b, h) do { _Pragma("unroll") for (int m = 0; m < 4; ++m) _Pragma("unroll") for (int k = 0; k < 2; ++k) dst[m][k] = *(const LAS bf16x8*)(lds + PG8_SA(b, h) + aoff + m * 2048 + k * 1024); } while (0)
; #define PG8_LDB(dst, b, h) do { _Pragma("unroll") for (int n = 0; n < 2; ++n) _Pragma("unroll") for (int k = 0; k < 2; ++k) dst[n][k] = *(const LAS bf16x8*)(lds + PG8_SB(b, h) + boff + n * 2048 + k * 1024); } while (0)
; #define PG8_MMA(ai, bj, At, Bt) do { __builtin_amdgcn_s_setprio(1); _Pragma("unroll") for (int m = 0; m < 4; ++m) _Pragma("unroll") for (int n = 0; n < 2; ++n) _Pragma("unroll") for (int k = 0; k < 2; ++k) \
;     acc[ai][bj][m][n] = __builtin_amdgcn_mfma_f32_16x16x32_bf16(Bt[n][k], At[m][k], acc[ai][bj][m][n], 0, 0, 0); __builtin_amdgcn_s_setprio(0); } while (0)
; #define PG8_WAIT_V(n) asm volatile("s_waitcnt vmcnt(" #n ")" ::: "memory")
; #define PG8_WAIT_L(n) asm volatile("s_waitcnt lgkmcnt(" #n ")" ::: "memory")
; #define PG8_BAR __builtin_amdgcn_s_barrier()
; #define PG8_SCHED __builtin_amdgcn_sched_barrier(0)
; template <class Epi, class Sched = StaticOrder>
; DI void gemm_phase(LAS unsigned char* lds, const Gemm g, const Sched& S, const Epi& E) {
;     ...
;       PG8_LDB(B0, 1, 0); PG8_SCHED; PG8_LDA(At, 1, 0); PG8_STAGE(PG8_SA(0, 1), a2 + hstep, voffA);
;       PG8_WAIT_L(8); PG8_BAR; PG8_WAIT_L(0); PG8_MMA(0, 0, At, B0); PG8_BAR; PG8_SCHED;
;       PG8_LDB(B1, 1, 1); PG8_STAGE(PG8_SB(1, 0), b3, voffB);
;       PG8_BAR; PG8_WAIT_L(0); PG8_MMA(0, 1, At, B1); PG8_BAR;
;       PG8_LDA(At, 1, 1); PG8_STAGE(PG8_SA(1, 0), a3, voffA);
;       PG8_BAR; PG8_WAIT_L(0); PG8_MMA(1, 0, At, B0); PG8_BAR; PG8_SCHED;
;       PG8_STAGE(PG8_SB(1, 1), b3 + hstep, voffB);
;       PG8_WAIT_V(6); PG8_BAR; PG8_MMA(1, 1, At, B1); PG8_BAR;
	s_setprio 0
	s_add_i32 s54, 0, 0x18000
	v_add_u32_e32 v140, s54, v205
	ds_read_b128 v[128:131], v140
	ds_read_b128 v[132:135], v140 offset:1024
	ds_read_b128 v[136:139], v140 offset:2048
	ds_read_b128 v[140:143], v140 offset:3072
	s_add_u32 s26, s26, 0x80000
	s_addc_u32 s27, s27, 0
	s_mov_b32 m0, s39
	ds_read_b128 v[144:147], v208 offset:32768
	ds_read_b128 v[148:151], v208 offset:33792
	ds_read_b128 v[152:155], v208 offset:34816
	ds_read_b128 v[156:159], v208 offset:35840
	ds_read_b128 v[160:163], v208 offset:36864
	ds_read_b128 v[164:167], v208 offset:37888
	ds_read_b128 v[168:171], v208 offset:38912
	ds_read_b128 v[172:175], v208 offset:39936
	global_load_lds_dwordx4 v182, s[26:27]
	s_mov_b32 m0, s40
	s_nop 0
	global_load_lds_dwordx4 v178, s[26:27]
	s_add_i32 s26, 0, 0x1c000
	v_add_u32_e32 v212, s26, v205
	ds_read_b128 v[192:195], v212
	ds_read_b128 v[196:199], v212 offset:1024
	ds_read_b128 v[200:203], v212 offset:2048
	ds_read_b128 v[212:215], v212 offset:3072
	s_waitcnt vmcnt(8)
	s_waitcnt lgkmcnt(4)
	s_setprio 1
	s_barrier
	v_mfma_f32_16x16x32_bf16 v[124:127], v[128:131], v[144:147], v[124:127]
	v_mfma_f32_16x16x32_bf16 v[120:123], v[136:139], v[144:147], v[120:123]
	v_mfma_f32_16x16x32_bf16 v[108:111], v[128:131], v[152:155], v[108:111]
	v_mfma_f32_16x16x32_bf16 v[104:107], v[136:139], v[152:155], v[104:107]
	v_mfma_f32_16x16x32_bf16 v[92:95], v[128:131], v[160:163], v[92:95]
	v_mfma_f32_16x16x32_bf16 v[88:91], v[136:139], v[160:163], v[88:91]
	v_mfma_f32_16x16x32_bf16 v[76:79], v[128:131], v[168:171], v[76:79]
	v_mfma_f32_16x16x32_bf16 v[72:75], v[136:139], v[168:171], v[72:75]
	v_mfma_f32_16x16x32_bf16 v[124:127], v[132:135], v[148:151], v[124:127]
	v_mfma_f32_16x16x32_bf16 v[120:123], v[140:143], v[148:151], v[120:123]
	v_mfma_f32_16x16x32_bf16 v[108:111], v[132:135], v[156:159], v[108:111]
	v_mfma_f32_16x16x32_bf16 v[104:107], v[140:143], v[156:159], v[104:107]
	v_mfma_f32_16x16x32_bf16 v[92:95], v[132:135], v[164:167], v[92:95]
	v_mfma_f32_16x16x32_bf16 v[88:91], v[140:143], v[164:167], v[88:91]
	v_mfma_f32_16x16x32_bf16 v[76:79], v[132:135], v[172:175], v[76:79]
	v_mfma_f32_16x16x32_bf16 v[72:75], v[140:143], v[172:175], v[72:75]
	s_waitcnt lgkmcnt(0)
	v_mfma_f32_16x16x32_bf16 v[116:119], v[192:195], v[144:147], v[116:119]
	v_mfma_f32_16x16x32_bf16 v[112:115], v[200:203], v[144:147], v[112:115]
	v_mfma_f32_16x16x32_bf16 v[100:103], v[192:195], v[152:155], v[100:103]
	v_mfma_f32_16x16x32_bf16 v[96:99], v[200:203], v[152:155], v[96:99]
	v_mfma_f32_16x16x32_bf16 v[84:87], v[192:195], v[160:163], v[84:87]
	v_mfma_f32_16x16x32_bf16 v[80:83], v[200:203], v[160:163], v[80:83]
	v_mfma_f32_16x16x32_bf16 v[68:71], v[192:195], v[168:171], v[68:71]
	v_mfma_f32_16x16x32_bf16 v[64:67], v[200:203], v[168:171], v[64:67]
	v_mfma_f32_16x16x32_bf16 v[116:119], v[196:199], v[148:151], v[116:119]
	v_mfma_f32_16x16x32_bf16 v[112:115], v[212:215], v[148:151], v[112:115]
	v_mfma_f32_16x16x32_bf16 v[100:103], v[196:199], v[156:159], v[100:103]
	v_mfma_f32_16x16x32_bf16 v[96:99], v[212:215], v[156:159], v[96:99]
	v_mfma_f32_16x16x32_bf16 v[84:87], v[196:199], v[164:167], v[84:87]
	v_mfma_f32_16x16x32_bf16 v[80:83], v[212:215], v[164:167], v[80:83]
	v_mfma_f32_16x16x32_bf16 v[68:71], v[196:199], v[172:175], v[68:71]
	v_mfma_f32_16x16x32_bf16 v[64:67], v[212:215], v[172:175], v[64:67]
	s_barrier
	s_setprio 0
	s_add_i32 s27, s54, s35
	ds_read_b128 v[144:147], v208 offset:49152
	ds_read_b128 v[148:151], v208 offset:50176
	ds_read_b128 v[152:155], v208 offset:51200
	ds_read_b128 v[156:159], v208 offset:52224
	ds_read_b128 v[160:163], v208 offset:53248
	ds_read_b128 v[164:167], v208 offset:54272
	ds_read_b128 v[168:171], v208 offset:55296
	ds_read_b128 v[172:175], v208 offset:56320
	s_mov_b32 m0, s27
	s_nop 0
	global_load_lds_dwordx4 v180, s[98:99]
	s_add_i32 m0, s27, 0x2000
	s_nop 0
	global_load_lds_dwordx4 v176, s[98:99]
	s_mov_b32 m0, s46
	s_nop 0
	global_load_lds_dwordx4 v182, s[100:101]
	s_mov_b32 m0, s47
	s_nop 0
	global_load_lds_dwordx4 v178, s[100:101]
	s_add_u32 s24, s24, 0x80080
	s_addc_u32 s25, s25, 0
	s_add_i32 s26, s26, s35
	s_add_i32 s53, s53, 2
	s_add_u32 s22, s22, 0x100
	s_addc_u32 s23, s23, 0
	s_add_u32 s45, s45, 0x100
	s_addc_u32 s52, s52, 0
	s_cmp_gt_u32 s53, 29
	s_waitcnt vmcnt(6)
	s_waitcnt lgkmcnt(0)
	s_setprio 1
	s_barrier
	v_mfma_f32_16x16x32_bf16 v[60:63], v[128:131], v[144:147], v[60:63]
	s_mov_b32 m0, s26
	v_mfma_f32_16x16x32_bf16 v[56:59], v[136:139], v[144:147], v[56:59]
	global_load_lds_dwordx4 v180, s[24:25]
	v_mfma_f32_16x16x32_bf16 v[44:47], v[128:131], v[152:155], v[44:47]
	s_bitset1_b32 m0, 13
	v_mfma_f32_16x16x32_bf16 v[40:43], v[136:139], v[152:155], v[40:43]
	global_load_lds_dwordx4 v176, s[24:25]
	v_mfma_f32_16x16x32_bf16 v[28:31], v[128:131], v[160:163], v[28:31]
	v_mfma_f32_16x16x32_bf16 v[24:27], v[136:139], v[160:163], v[24:27]
	v_mfma_f32_16x16x32_bf16 v[12:15], v[128:131], v[168:171], v[12:15]
	v_mfma_f32_16x16x32_bf16 v[8:11], v[136:139], v[168:171], v[8:11]
	v_mfma_f32_16x16x32_bf16 v[60:63], v[132:135], v[148:151], v[60:63]
	v_mfma_f32_16x16x32_bf16 v[56:59], v[140:143], v[148:151], v[56:59]
	v_mfma_f32_16x16x32_bf16 v[44:47], v[132:135], v[156:159], v[44:47]
	v_mfma_f32_16x16x32_bf16 v[40:43], v[140:143], v[156:159], v[40:43]
	v_mfma_f32_16x16x32_bf16 v[28:31], v[132:135], v[164:167], v[28:31]
	v_mfma_f32_16x16x32_bf16 v[24:27], v[140:143], v[164:167], v[24:27]
	v_mfma_f32_16x16x32_bf16 v[12:15], v[132:135], v[172:175], v[12:15]
	v_mfma_f32_16x16x32_bf16 v[8:11], v[140:143], v[172:175], v[8:11]
	v_mfma_f32_16x16x32_bf16 v[52:55], v[192:195], v[144:147], v[52:55]
	v_mfma_f32_16x16x32_bf16 v[48:51], v[200:203], v[144:147], v[48:51]
	v_mfma_f32_16x16x32_bf16 v[36:39], v[192:195], v[152:155], v[36:39]
	v_mfma_f32_16x16x32_bf16 v[32:35], v[200:203], v[152:155], v[32:35]
	v_mfma_f32_16x16x32_bf16 v[20:23], v[192:195], v[160:163], v[20:23]
	v_mfma_f32_16x16x32_bf16 v[16:19], v[200:203], v[160:163], v[16:19]
	v_mfma_f32_16x16x32_bf16 v[4:7], v[192:195], v[168:171], v[4:7]
	v_mfma_f32_16x16x32_bf16 v[0:3], v[200:203], v[168:171], v[0:3]
	v_mfma_f32_16x16x32_bf16 v[52:55], v[196:199], v[148:151], v[52:55]
	v_mfma_f32_16x16x32_bf16 v[48:51], v[212:215], v[148:151], v[48:51]
	v_mfma_f32_16x16x32_bf16 v[36:39], v[196:199], v[156:159], v[36:39]
	v_mfma_f32_16x16x32_bf16 v[32:35], v[212:215], v[156:159], v[32:35]
	v_mfma_f32_16x16x32_bf16 v[20:23], v[196:199], v[164:167], v[20:23]
	v_mfma_f32_16x16x32_bf16 v[16:19], v[212:215], v[164:167], v[16:19]
	v_mfma_f32_16x16x32_bf16 v[4:7], v[196:199], v[172:175], v[4:7]
	v_mfma_f32_16x16x32_bf16 v[0:3], v[212:215], v[172:175], v[0:3]
	s_barrier
; DI unsigned pack2(float lo, float hi) { f32x2 v = {lo, hi}; bf16v2 r = __builtin_convertvector(v, bf16v2); return __builtin_bit_cast(unsigned, r); }
;   DI void operator()(const f32x4 (&acc)[2][2][4][2], const Unit& u, int wr, int wc, int fr, int fq) const {
;     const int row0 = u.pm * BM + wr * 64 + fr, col0 = u.pn * BM + wc * 32 + 8 * fq;
; #pragma unroll
;     for (int ai = 0; ai < 2; ++ai) {
;       f32x4 bv[4][2][2];
; #pragma unroll
;       for (int m = 0; m < 4; ++m)
; #pragma unroll
;         for (int bj = 0; bj < 2; ++bj) {
;           const float* bp = base + (size_t)(row0 + ai * HALF + m * 16) * 2048 + col0 + bj * HALF;
;           bv[m][bj][0] = *(const f32x4*)bp; bv[m][bj][1] = *(const f32x4*)(bp + 4);
;         }
; #pragma unroll
;       for (int m = 0; m < 4; ++m) {
;         const int row = row0 + ai * HALF + m * 16;
;         const size_t off = (size_t)row * 2048 + col0;
;         float ss = 0.f;
; #pragma unroll
;         for (int bj = 0; bj < 2; ++bj) {
;           const f32x4 v0 = acc[ai][bj][m][0] + bv[m][bj][0], v1 = acc[ai][bj][m][1] + bv[m][bj][1];
;           *(f32x4*)(C + off + bj * HALF) = v0; *(f32x4*)(C + off + bj * HALF + 4) = v1;
;           if (xb) {
;             u32x4 w; w.x = pack2(v0[0], v0[1]); w.y = pack2(v0[2], v0[3]); w.z = pack2(v1[0], v1[1]); w.w = pack2(v1[2], v1[3]);
;             *(u32x4*)(xb + off + bj * HALF) = w;
;             ss += v0[0] * v0[0] + v0[1] * v0[1] + v0[2] * v0[2] + v0[3] * v0[3] + v1[0] * v1[0] + v1[1] * v1[1] + v1[2] * v1[2] + v1[3] * v1[3];
;           }
;         }
;         if (xb) {
;           ss += __shfl_xor(ss, 16); ss += __shfl_xor(ss, 32);
;           if (fq == 0) ssq[(size_t)row * 32 + u.pn * 4 + wc] = ss;
;         }
	s_setprio 0
	s_cbranch_scc0 .LBB0_728
	v_lshl_add_u32 v196, s12, 8, v204
	v_lshl_or_b32 v192, s42, 8, v206
	v_ashrrev_i32_e32 v193, 31, v192
	v_ashrrev_i32_e32 v197, 31, v196
	v_lshl_add_u64 v[194:195], v[192:193], 2, s[60:61]
	v_lshlrev_b64 v[128:129], 13, v[196:197]
	v_lshl_add_u64 v[128:129], v[194:195], 0, v[128:129]
	global_load_dwordx4 v[214:217], v[128:129], off
	global_load_dwordx4 v[218:221], v[128:129], off offset:16
	global_load_dwordx4 v[222:225], v[128:129], off offset:512
	global_load_dwordx4 v[226:229], v[128:129], off offset:528
	v_or_b32_e32 v202, 16, v196
	v_or_b32_e32 v200, 32, v196
	v_or_b32_e32 v198, 48, v196
	v_ashrrev_i32_e32 v203, 31, v202
	v_ashrrev_i32_e32 v201, 31, v200
	v_ashrrev_i32_e32 v199, 31, v198
	v_lshlrev_b64 v[128:129], 13, v[202:203]
	v_lshlrev_b64 v[130:131], 13, v[200:201]
	v_lshlrev_b64 v[132:133], 13, v[198:199]
	v_lshl_add_u64 v[128:129], v[194:195], 0, v[128:129]
	v_lshl_add_u64 v[130:131], v[194:195], 0, v[130:131]
	v_lshl_add_u64 v[132:133], v[194:195], 0, v[132:133]
	global_load_dwordx4 v[168:171], v[128:129], off offset:16
	global_load_dwordx4 v[172:175], v[128:129], off
	global_load_dwordx4 v[160:163], v[128:129], off offset:528
	global_load_dwordx4 v[164:167], v[128:129], off offset:512
	global_load_dwordx4 v[152:155], v[130:131], off offset:16
	global_load_dwordx4 v[156:159], v[130:131], off
	global_load_dwordx4 v[144:147], v[130:131], off offset:528
	global_load_dwordx4 v[148:151], v[130:131], off offset:512
	global_load_dwordx4 v[136:139], v[132:133], off offset:16
	global_load_dwordx4 v[140:143], v[132:133], off
	s_nop 0
	global_load_dwordx4 v[128:131], v[132:133], off offset:528
	s_nop 0
	global_load_dwordx4 v[132:135], v[132:133], off offset:512
	v_and_b32_e32 v212, 64, v211
	v_xor_b32_e32 v230, 16, v211
	v_add_u32_e32 v232, 64, v212
	v_xor_b32_e32 v231, 32, v211
	v_cmp_lt_i32_e32 vcc, v230, v232
	v_lshlrev_b64 v[212:213], 11, v[196:197]
	v_readlane_b32 s64, v243, 3
	v_cndmask_b32_e32 v233, v211, v230, vcc
	v_cmp_lt_i32_e32 vcc, v231, v232
	v_readlane_b32 s78, v243, 17
	v_readlane_b32 s79, v243, 18
	v_cndmask_b32_e32 v234, v211, v231, vcc
	v_lshl_add_u64 v[230:231], v[212:213], 0, v[192:193]
	v_lshlrev_b32_e32 v212, 2, v233
	v_lshl_add_u64 v[232:233], v[230:231], 2, s[78:79]
	v_lshl_add_u64 v[230:231], v[230:231], 1, s[2:3]
	s_lshl_b32 s22, s42, 2
	s_ashr_i32 s23, s22, 31
	v_readlane_b32 s65, v243, 4
	v_readlane_b32 s66, v243, 5
	v_readlane_b32 s67, v243, 6
	v_readlane_b32 s68, v243, 7
	v_readlane_b32 s69, v243, 8
	v_readlane_b32 s70, v243, 9
	v_readlane_b32 s71, v243, 10
	v_readlane_b32 s72, v243, 11
	v_readlane_b32 s73, v243, 12
	v_readlane_b32 s74, v243, 13
	v_readlane_b32 s75, v243, 14
	v_readlane_b32 s76, v243, 15
	v_readlane_b32 s77, v243, 16
	s_waitcnt vmcnt(0)
	v_pk_add_f32 v[126:127], v[126:127], v[216:217]
	v_pk_add_f32 v[124:125], v[124:125], v[214:215]
	v_pk_add_f32 v[116:117], v[116:117], v[222:223]
	v_pk_add_f32 v[122:123], v[122:123], v[220:221]
	v_pk_add_f32 v[120:121], v[120:121], v[218:219]
	v_pk_add_f32 v[214:215], v[112:113], v[226:227]
	global_store_dwordx4 v[232:233], v[124:127], off
	global_store_dwordx4 v[232:233], v[120:123], off offset:16
	v_cvt_pk_bf16_f32 v112, v124, v125
	v_mul_f32_e32 v125, v125, v125
	v_mul_f32_e32 v213, v117, v117
	v_pk_add_f32 v[118:119], v[118:119], v[224:225]
	v_fmac_f32_e32 v125, v124, v124
	v_fmac_f32_e32 v213, v116, v116
	v_fmac_f32_e32 v125, v126, v126
	v_fmac_f32_e32 v213, v118, v118
	v_fmac_f32_e32 v125, v127, v127
	v_fmac_f32_e32 v213, v119, v119
	v_fmac_f32_e32 v125, v120, v120
	v_fmac_f32_e32 v213, v214, v214
	v_pk_add_f32 v[216:217], v[114:115], v[228:229]
	v_fmac_f32_e32 v125, v121, v121
	v_fmac_f32_e32 v213, v215, v215
	v_fmac_f32_e32 v125, v122, v122
	v_fmac_f32_e32 v213, v216, v216
	v_fmac_f32_e32 v125, v123, v123
	v_fmac_f32_e32 v213, v217, v217
	v_cvt_pk_bf16_f32 v114, v120, v121
	v_add_f32_e32 v120, v125, v213
	ds_bpermute_b32 v121, v212, v120
	v_cvt_pk_bf16_f32 v113, v126, v127
	v_cvt_pk_bf16_f32 v115, v122, v123
	global_store_dwordx4 v[230:231], v[112:115], off
	global_store_dwordx4 v[232:233], v[116:119], off offset:512
	global_store_dwordx4 v[232:233], v[214:217], off offset:528
	v_cvt_pk_bf16_f32 v122, v116, v117
	s_waitcnt lgkmcnt(0)
	v_add_f32_e32 v112, v120, v121
	v_lshlrev_b32_e32 v120, 2, v234
	ds_bpermute_b32 v113, v120, v112
	v_cvt_pk_bf16_f32 v123, v118, v119
	v_cvt_pk_bf16_f32 v124, v214, v215
	v_cvt_pk_bf16_f32 v125, v216, v217
	global_store_dwordx4 v[230:231], v[122:125], off offset:256
	s_and_saveexec_b64 s[24:25], s[0:1]
	s_cbranch_execz .LBB0_731
	s_waitcnt lgkmcnt(0)
	v_add_f32_e32 v114, v112, v113
	v_lshlrev_b64 v[112:113], 7, v[196:197]
	v_lshl_add_u64 v[112:113], s[8:9], 0, v[112:113]
	v_lshl_add_u64 v[112:113], s[22:23], 2, v[112:113]
	s_lshl_b32 s12, s41, 2
	v_lshl_add_u64 v[112:113], v[112:113], 0, s[12:13]
	global_store_dword v[112:113], v114, off

; #define PG8_STAGE(bufoff, gbase, voff) do { _Pragma("unroll") for (int _i = 0; _i < 2; ++_i) \
;     __builtin_amdgcn_global_load_lds((const unsigned*)((const char*)(gbase) + (voff)[_i]), (LAS unsigned*)(lds + (bufoff) + ldsw + _i * 8192), 16, 0, 0); } while (0)
; #define PG8_LDA(dst, b, h) do { _Pragma("unroll") for (int m = 0; m < 4; ++m) _Pragma("unroll") for (int k = 0; k < 2; ++k) dst[m][k] = *(const LAS bf16x8*)(lds + PG8_SA(b, h) + aoff + m * 2048 + k * 1024); } while (0)
; #define PG8_LDB(dst, b, h) do { _Pragma("unroll") for (int n = 0; n < 2; ++n) _Pragma("unroll") for (int k = 0; k < 2; ++k) dst[n][k] = *(const LAS bf16x8*)(lds + PG8_SB(b, h) + boff + n * 2048 + k * 1024); } while (0)
; #define PG8_MMA(ai, bj, At, Bt) do { __builtin_amdgcn_s_setprio(1); _Pragma("unroll") for (int m = 0; m < 4; ++m) _Pragma("unroll") for (int n = 0; n < 2; ++n) _Pragma("unroll") for (int k = 0; k < 2; ++k) \
;     acc[ai][bj][m][n] = __builtin_amdgcn_mfma_f32_16x16x32_bf16(Bt[n][k], At[m][k], acc[ai][bj][m][n], 0, 0, 0); __builtin_amdgcn_s_setprio(0); } while (0)
; #define PG8_WAIT_V(n) asm volatile("s_waitcnt vmcnt(" #n ")" ::: "memory")
; #define PG8_WAIT_L(n) asm volatile("s_waitcnt lgkmcnt(" #n ")" ::: "memory")
; #define PG8_BAR __builtin_amdgcn_s_barrier()
; #define PG8_SCHED __builtin_amdgcn_sched_barrier(0)
; template <class Epi, class Sched = StaticOrder>
; DI void gemm_phase(LAS unsigned char* lds, const Gemm g, const Sched& S, const Epi& E) {
;     ...
;       PG8_LDB(B0, 0, 0); PG8_SCHED; PG8_LDA(At, 0, 0); PG8_STAGE(PG8_SA(1, 1), a1 + hstep, voffA);
;       PG8_WAIT_L(8); PG8_BAR; PG8_WAIT_L(0); PG8_MMA(0, 0, At, B0); PG8_BAR; PG8_SCHED;
;       PG8_LDB(B1, 0, 1); PG8_STAGE(PG8_SB(0, 0), b2, voffB);
;       PG8_BAR; PG8_WAIT_L(0); PG8_MMA(0, 1, At, B1); PG8_BAR;
;       PG8_LDA(At, 0, 1); PG8_STAGE(PG8_SA(0, 0), a2, voffA);
;       PG8_BAR; PG8_WAIT_L(0); PG8_MMA(1, 0, At, B0); PG8_BAR; PG8_SCHED;
;       PG8_STAGE(PG8_SB(0, 1), b2 + hstep, voffB);
;       PG8_WAIT_V(6); PG8_BAR; PG8_MMA(1, 1, At, B1); PG8_BAR;
.LBB0_811:
	ds_read_b128 v[64:67], v201
	ds_read_b128 v[68:71], v201 offset:1024
	ds_read_b128 v[72:75], v201 offset:2048
	ds_read_b128 v[76:79], v201 offset:3072
	s_add_u32 s46, s14, 0xfff80080
	s_addc_u32 s47, s15, -1
	s_cmp_eq_u32 s52, 28
	s_cselect_b32 s49, s37, s47
	s_cselect_b32 s48, s42, s46
	s_cselect_b32 s47, s35, s45
	s_cselect_b32 s46, s43, s44
	s_add_i32 m0, s62, 0xc000
	ds_read_b128 v[80:83], v202
	ds_read_b128 v[84:87], v202 offset:1024
	ds_read_b128 v[92:95], v202 offset:2048
	ds_read_b128 v[96:99], v202 offset:3072
	ds_read_b128 v[180:183], v202 offset:4096
	ds_read_b128 v[184:187], v202 offset:5120
	ds_read_b128 v[188:191], v202 offset:6144
	ds_read_b128 v[192:195], v202 offset:7168
	global_load_lds_dwordx4 v170, s[14:15]
	s_add_i32 m0, s62, 0xe000
	s_nop 0
	global_load_lds_dwordx4 v172, s[14:15]
	ds_read_b128 v[206:209], v203
	ds_read_b128 v[212:215], v203 offset:1024
	ds_read_b128 v[216:219], v203 offset:2048
	ds_read_b128 v[220:223], v203 offset:3072
	s_waitcnt vmcnt(8)
	s_waitcnt lgkmcnt(4)
	s_setprio 1
	s_barrier
	v_mfma_f32_16x16x32_bf16 v[156:159], v[64:67], v[80:83], v[156:159]
	v_mfma_f32_16x16x32_bf16 v[144:147], v[72:75], v[80:83], v[144:147]
	v_mfma_f32_16x16x32_bf16 v[140:143], v[64:67], v[92:95], v[140:143]
	v_mfma_f32_16x16x32_bf16 v[132:135], v[72:75], v[92:95], v[132:135]
	v_mfma_f32_16x16x32_bf16 v[124:127], v[64:67], v[180:183], v[124:127]
	v_mfma_f32_16x16x32_bf16 v[116:119], v[72:75], v[180:183], v[116:119]
	v_mfma_f32_16x16x32_bf16 v[112:115], v[64:67], v[188:191], v[112:115]
	v_mfma_f32_16x16x32_bf16 v[108:111], v[72:75], v[188:191], v[108:111]
	v_mfma_f32_16x16x32_bf16 v[156:159], v[68:71], v[84:87], v[156:159]
	v_mfma_f32_16x16x32_bf16 v[144:147], v[76:79], v[84:87], v[144:147]
	v_mfma_f32_16x16x32_bf16 v[140:143], v[68:71], v[96:99], v[140:143]
	v_mfma_f32_16x16x32_bf16 v[132:135], v[76:79], v[96:99], v[132:135]
	v_mfma_f32_16x16x32_bf16 v[124:127], v[68:71], v[184:187], v[124:127]
	v_mfma_f32_16x16x32_bf16 v[116:119], v[76:79], v[184:187], v[116:119]
	v_mfma_f32_16x16x32_bf16 v[112:115], v[68:71], v[192:195], v[112:115]
	v_mfma_f32_16x16x32_bf16 v[108:111], v[76:79], v[192:195], v[108:111]
	s_waitcnt lgkmcnt(0)
	v_mfma_f32_16x16x32_bf16 v[152:155], v[206:209], v[80:83], v[152:155]
	v_mfma_f32_16x16x32_bf16 v[80:83], v[216:219], v[80:83], v[148:151]
	v_mfma_f32_16x16x32_bf16 v[152:155], v[212:215], v[84:87], v[152:155]
	v_mfma_f32_16x16x32_bf16 v[80:83], v[220:223], v[84:87], v[80:83]
	v_mfma_f32_16x16x32_bf16 v[84:87], v[206:209], v[92:95], v[136:139]
	v_mfma_f32_16x16x32_bf16 v[92:95], v[216:219], v[92:95], v[128:131]
	v_mfma_f32_16x16x32_bf16 v[104:107], v[216:219], v[180:183], v[104:107]
	v_mfma_f32_16x16x32_bf16 v[100:103], v[206:209], v[188:191], v[100:103]
	v_mfma_f32_16x16x32_bf16 v[88:91], v[216:219], v[188:191], v[88:91]
	v_mfma_f32_16x16x32_bf16 v[84:87], v[212:215], v[96:99], v[84:87]
	v_mfma_f32_16x16x32_bf16 v[92:95], v[220:223], v[96:99], v[92:95]
	v_mfma_f32_16x16x32_bf16 v[96:99], v[206:209], v[180:183], v[120:123]
	v_mfma_f32_16x16x32_bf16 v[104:107], v[220:223], v[184:187], v[104:107]
	v_mfma_f32_16x16x32_bf16 v[100:103], v[212:215], v[192:195], v[100:103]
	v_mfma_f32_16x16x32_bf16 v[88:91], v[220:223], v[192:195], v[88:91]
	v_mfma_f32_16x16x32_bf16 v[96:99], v[212:215], v[184:187], v[96:99]
	s_barrier
	s_setprio 0
	s_add_i32 s53, s72, s60
	s_add_u32 s98, s46, 0x80
	s_addc_u32 s99, s47, 0
	s_add_u32 s100, s48, 0x80
	s_addc_u32 s101, s49, 0
	ds_read_b128 v[120:123], v202 offset:16384
	ds_read_b128 v[128:131], v202 offset:17408
	ds_read_b128 v[136:139], v202 offset:18432
	ds_read_b128 v[148:151], v202 offset:19456
	ds_read_b128 v[180:183], v202 offset:20480
	ds_read_b128 v[184:187], v202 offset:21504
	ds_read_b128 v[188:191], v202 offset:22528
	ds_read_b128 v[192:195], v202 offset:23552
	s_mov_b32 m0, s53
	s_nop 0
	global_load_lds_dwordx4 v164, s[46:47]
	s_add_i32 m0, s53, 0x2000
	s_nop 0
	global_load_lds_dwordx4 v160, s[46:47]
	s_mov_b32 m0, s62
	s_nop 0
	global_load_lds_dwordx4 v166, s[48:49]
	s_mov_b32 m0, s63
	s_nop 0
	global_load_lds_dwordx4 v162, s[48:49]
	s_add_u32 s54, s46, 0x80000
	s_addc_u32 s55, s47, 0
	s_add_i32 s53, s73, s60
	s_waitcnt vmcnt(6)
	s_waitcnt lgkmcnt(0)
	s_setprio 1
	s_barrier
	v_mfma_f32_16x16x32_bf16 v[60:63], v[64:67], v[120:123], v[60:63]
	s_mov_b32 m0, s53
	v_mfma_f32_16x16x32_bf16 v[48:51], v[72:75], v[120:123], v[48:51]
	global_load_lds_dwordx4 v164, s[54:55]
	v_mfma_f32_16x16x32_bf16 v[44:47], v[64:67], v[136:139], v[44:47]
	s_bitset1_b32 m0, 13
	v_mfma_f32_16x16x32_bf16 v[36:39], v[72:75], v[136:139], v[36:39]
	global_load_lds_dwordx4 v160, s[54:55]
	v_mfma_f32_16x16x32_bf16 v[28:31], v[64:67], v[180:183], v[28:31]
	v_mfma_f32_16x16x32_bf16 v[20:23], v[72:75], v[180:183], v[20:23]
	v_mfma_f32_16x16x32_bf16 v[16:19], v[64:67], v[188:191], v[16:19]
	v_mfma_f32_16x16x32_bf16 v[12:15], v[72:75], v[188:191], v[12:15]
	v_mfma_f32_16x16x32_bf16 v[60:63], v[68:71], v[128:131], v[60:63]
	v_mfma_f32_16x16x32_bf16 v[48:51], v[76:79], v[128:131], v[48:51]
	v_mfma_f32_16x16x32_bf16 v[44:47], v[68:71], v[148:151], v[44:47]
	v_mfma_f32_16x16x32_bf16 v[36:39], v[76:79], v[148:151], v[36:39]
	v_mfma_f32_16x16x32_bf16 v[28:31], v[68:71], v[184:187], v[28:31]
	v_mfma_f32_16x16x32_bf16 v[20:23], v[76:79], v[184:187], v[20:23]
	v_mfma_f32_16x16x32_bf16 v[16:19], v[68:71], v[192:195], v[16:19]
	v_mfma_f32_16x16x32_bf16 v[12:15], v[76:79], v[192:195], v[12:15]
	v_mfma_f32_16x16x32_bf16 v[56:59], v[206:209], v[120:123], v[56:59]
	v_mfma_f32_16x16x32_bf16 v[52:55], v[216:219], v[120:123], v[52:55]
	v_mfma_f32_16x16x32_bf16 v[40:43], v[206:209], v[136:139], v[40:43]
	v_mfma_f32_16x16x32_bf16 v[32:35], v[216:219], v[136:139], v[32:35]
	v_mfma_f32_16x16x32_bf16 v[24:27], v[206:209], v[180:183], v[24:27]
	v_mfma_f32_16x16x32_bf16 v[8:11], v[216:219], v[180:183], v[8:11]
	v_mfma_f32_16x16x32_bf16 v[4:7], v[206:209], v[188:191], v[4:7]
	v_mfma_f32_16x16x32_bf16 v[0:3], v[216:219], v[188:191], v[0:3]
	v_mfma_f32_16x16x32_bf16 v[56:59], v[212:215], v[128:131], v[56:59]
	v_mfma_f32_16x16x32_bf16 v[52:55], v[220:223], v[128:131], v[52:55]
	v_mfma_f32_16x16x32_bf16 v[40:43], v[212:215], v[148:151], v[40:43]
	v_mfma_f32_16x16x32_bf16 v[32:35], v[220:223], v[148:151], v[32:35]
	v_mfma_f32_16x16x32_bf16 v[24:27], v[212:215], v[184:187], v[24:27]
	v_mfma_f32_16x16x32_bf16 v[8:11], v[220:223], v[184:187], v[8:11]
	v_mfma_f32_16x16x32_bf16 v[4:7], v[212:215], v[192:195], v[4:7]
	v_mfma_f32_16x16x32_bf16 v[0:3], v[220:223], v[192:195], v[0:3]
	s_barrier
; #define PG8_STAGE(bufoff, gbase, voff) do { _Pragma("unroll") for (int _i = 0; _i < 2; ++_i) \
;     __builtin_amdgcn_global_load_lds((const unsigned*)((const char*)(gbase) + (voff)[_i]), (LAS unsigned*)(lds + (bufoff) + ldsw + _i * 8192), 16, 0, 0); } while (0)
; #define PG8_LDA(dst, b, h) do { _Pragma("unroll") for (int m = 0; m < 4; ++m) _Pragma("unroll") for (int k = 0; k < 2; ++k) dst[m][k] = *(const LAS bf16x8*)(lds + PG8_SA(b, h) + aoff + m * 2048 + k * 1024); } while (0)
; #define PG8_LDB(dst, b, h) do { _Pragma("unroll") for (int n = 0; n < 2; ++n) _Pragma("unroll") for (int k = 0; k < 2; ++k) dst[n][k] = *(const LAS bf16x8*)(lds + PG8_SB(b, h) + boff + n * 2048 + k * 1024); } while (0)
; #define PG8_MMA(ai, bj, At, Bt) do { __builtin_amdgcn_s_setprio(1); _Pragma("unroll") for (int m = 0; m < 4; ++m) _Pragma("unroll") for (int n = 0; n < 2; ++n) _Pragma("unroll") for (int k = 0; k < 2; ++k) \
;     acc[ai][bj][m][n] = __builtin_amdgcn_mfma_f32_16x16x32_bf16(Bt[n][k], At[m][k], acc[ai][bj][m][n], 0, 0, 0); __builtin_amdgcn_s_setprio(0); } while (0)
; #define PG8_WAIT_V(n) asm volatile("s_waitcnt vmcnt(" #n ")" ::: "memory")
; #define PG8_WAIT_L(n) asm volatile("s_waitcnt lgkmcnt(" #n ")" ::: "memory")
; #define PG8_BAR __builtin_amdgcn_s_barrier()
; #define PG8_SCHED __builtin_amdgcn_sched_barrier(0)
; template <class Epi, class Sched = StaticOrder>
; DI void gemm_phase(LAS unsigned char* lds, const Gemm g, const Sched& S, const Epi& E) {
;     ...
;       PG8_LDB(B0, 1, 0); PG8_SCHED; PG8_LDA(At, 1, 0); PG8_STAGE(PG8_SA(0, 1), a2 + hstep, voffA);
;       PG8_WAIT_L(8); PG8_BAR; PG8_WAIT_L(0); PG8_MMA(0, 0, At, B0); PG8_BAR; PG8_SCHED;
;       PG8_LDB(B1, 1, 1); PG8_STAGE(PG8_SB(1, 0), b3, voffB);
;       PG8_BAR; PG8_WAIT_L(0); PG8_MMA(0, 1, At, B1); PG8_BAR;
;       PG8_LDA(At, 1, 1); PG8_STAGE(PG8_SA(1, 0), a3, voffA);
;       PG8_BAR; PG8_WAIT_L(0); PG8_MMA(1, 0, At, B0); PG8_BAR; PG8_SCHED;
;       PG8_STAGE(PG8_SB(1, 1), b3 + hstep, voffB);
;       PG8_WAIT_V(6); PG8_BAR; PG8_MMA(1, 1, At, B1); PG8_BAR;
	s_setprio 0
	s_add_i32 s53, 0, 0x18000
	v_add_u32_e32 v76, s53, v198
	ds_read_b128 v[64:67], v76
	ds_read_b128 v[68:71], v76 offset:1024
	ds_read_b128 v[72:75], v76 offset:2048
	ds_read_b128 v[76:79], v76 offset:3072
	s_add_u32 s48, s48, 0x80000
	s_addc_u32 s49, s49, 0
	s_mov_b32 m0, s64
	ds_read_b128 v[120:123], v202 offset:32768
	ds_read_b128 v[128:131], v202 offset:33792
	ds_read_b128 v[180:183], v202 offset:34816
	ds_read_b128 v[184:187], v202 offset:35840
	ds_read_b128 v[188:191], v202 offset:36864
	ds_read_b128 v[192:195], v202 offset:37888
	ds_read_b128 v[206:209], v202 offset:38912
	ds_read_b128 v[212:215], v202 offset:39936
	global_load_lds_dwordx4 v166, s[48:49]
	s_mov_b32 m0, s65
	s_nop 0
	global_load_lds_dwordx4 v162, s[48:49]
	s_add_i32 s48, 0, 0x1c000
	v_add_u32_e32 v244, s48, v198
	ds_read_b128 v[216:219], v244
	ds_read_b128 v[220:223], v244 offset:1024
	ds_read_b128 v[224:227], v244 offset:2048
	ds_read_b128 v[228:231], v244 offset:3072
	s_waitcnt vmcnt(8)
	s_waitcnt lgkmcnt(4)
	s_setprio 1
	s_barrier
	v_mfma_f32_16x16x32_bf16 v[136:139], v[64:67], v[120:123], v[156:159]
	v_mfma_f32_16x16x32_bf16 v[156:159], v[68:71], v[128:131], v[136:139]
	v_mfma_f32_16x16x32_bf16 v[136:139], v[72:75], v[120:123], v[144:147]
	v_mfma_f32_16x16x32_bf16 v[144:147], v[76:79], v[128:131], v[136:139]
	v_mfma_f32_16x16x32_bf16 v[136:139], v[64:67], v[180:183], v[140:143]
	v_mfma_f32_16x16x32_bf16 v[132:135], v[72:75], v[180:183], v[132:135]
	v_mfma_f32_16x16x32_bf16 v[124:127], v[64:67], v[188:191], v[124:127]
	v_mfma_f32_16x16x32_bf16 v[116:119], v[72:75], v[188:191], v[116:119]
	v_mfma_f32_16x16x32_bf16 v[112:115], v[64:67], v[206:209], v[112:115]
	v_mfma_f32_16x16x32_bf16 v[108:111], v[72:75], v[206:209], v[108:111]
	v_mfma_f32_16x16x32_bf16 v[140:143], v[68:71], v[184:187], v[136:139]
	v_mfma_f32_16x16x32_bf16 v[132:135], v[76:79], v[184:187], v[132:135]
	v_mfma_f32_16x16x32_bf16 v[124:127], v[68:71], v[192:195], v[124:127]
	v_mfma_f32_16x16x32_bf16 v[116:119], v[76:79], v[192:195], v[116:119]
	v_mfma_f32_16x16x32_bf16 v[112:115], v[68:71], v[212:215], v[112:115]
	v_mfma_f32_16x16x32_bf16 v[108:111], v[76:79], v[212:215], v[108:111]
	s_waitcnt lgkmcnt(0)
	v_mfma_f32_16x16x32_bf16 v[80:83], v[224:227], v[120:123], v[80:83]
	v_mfma_f32_16x16x32_bf16 v[136:139], v[216:219], v[120:123], v[152:155]
	v_mfma_f32_16x16x32_bf16 v[148:151], v[228:231], v[128:131], v[80:83]
	v_mfma_f32_16x16x32_bf16 v[80:83], v[216:219], v[180:183], v[84:87]
	v_mfma_f32_16x16x32_bf16 v[152:155], v[220:223], v[128:131], v[136:139]
	v_mfma_f32_16x16x32_bf16 v[136:139], v[220:223], v[184:187], v[80:83]
	v_mfma_f32_16x16x32_bf16 v[80:83], v[224:227], v[180:183], v[92:95]
	v_mfma_f32_16x16x32_bf16 v[128:131], v[228:231], v[184:187], v[80:83]
	v_mfma_f32_16x16x32_bf16 v[80:83], v[216:219], v[188:191], v[96:99]
	v_mfma_f32_16x16x32_bf16 v[120:123], v[220:223], v[192:195], v[80:83]
	v_mfma_f32_16x16x32_bf16 v[80:83], v[224:227], v[188:191], v[104:107]
	v_mfma_f32_16x16x32_bf16 v[104:107], v[228:231], v[192:195], v[80:83]
	v_mfma_f32_16x16x32_bf16 v[80:83], v[216:219], v[206:209], v[100:103]
	v_mfma_f32_16x16x32_bf16 v[100:103], v[220:223], v[212:215], v[80:83]
	v_mfma_f32_16x16x32_bf16 v[80:83], v[224:227], v[206:209], v[88:91]
	v_mfma_f32_16x16x32_bf16 v[88:91], v[228:231], v[212:215], v[80:83]
	s_barrier
	s_setprio 0
	s_add_i32 s49, s53, s60
	s_nop 2
	ds_read_b128 v[80:83], v202 offset:49152
	ds_read_b128 v[84:87], v202 offset:50176
	ds_read_b128 v[92:95], v202 offset:51200
	ds_read_b128 v[96:99], v202 offset:52224
	ds_read_b128 v[180:183], v202 offset:53248
	ds_read_b128 v[184:187], v202 offset:54272
	ds_read_b128 v[188:191], v202 offset:55296
	ds_read_b128 v[192:195], v202 offset:56320
	s_mov_b32 m0, s49
	s_nop 0
	global_load_lds_dwordx4 v164, s[98:99]
	s_add_i32 m0, s49, 0x2000
	s_nop 0
	global_load_lds_dwordx4 v160, s[98:99]
	s_mov_b32 m0, s67
	s_nop 0
	global_load_lds_dwordx4 v166, s[100:101]
	s_mov_b32 m0, s68
	s_nop 0
	global_load_lds_dwordx4 v162, s[100:101]
	s_add_u32 s46, s46, 0x80080
	s_addc_u32 s47, s47, 0
	s_add_i32 s48, s48, s60
	s_add_i32 s52, s52, 2
	s_add_u32 s14, s14, 0x100
	s_addc_u32 s15, s15, 0
	s_add_u32 s44, s44, 0x100
	s_addc_u32 s45, s45, 0
	s_cmp_gt_u32 s52, 29
	s_waitcnt vmcnt(6)
	s_waitcnt lgkmcnt(0)
	s_setprio 1
	s_barrier
	v_mfma_f32_16x16x32_bf16 v[60:63], v[64:67], v[80:83], v[60:63]
	s_mov_b32 m0, s48
	v_mfma_f32_16x16x32_bf16 v[48:51], v[72:75], v[80:83], v[48:51]
	global_load_lds_dwordx4 v164, s[46:47]
	v_mfma_f32_16x16x32_bf16 v[44:47], v[64:67], v[92:95], v[44:47]
	s_bitset1_b32 m0, 13
	v_mfma_f32_16x16x32_bf16 v[36:39], v[72:75], v[92:95], v[36:39]
	global_load_lds_dwordx4 v160, s[46:47]
	v_mfma_f32_16x16x32_bf16 v[28:31], v[64:67], v[180:183], v[28:31]
	v_mfma_f32_16x16x32_bf16 v[20:23], v[72:75], v[180:183], v[20:23]
	v_mfma_f32_16x16x32_bf16 v[16:19], v[64:67], v[188:191], v[16:19]
	v_mfma_f32_16x16x32_bf16 v[12:15], v[72:75], v[188:191], v[12:15]
	v_mfma_f32_16x16x32_bf16 v[60:63], v[68:71], v[84:87], v[60:63]
	v_mfma_f32_16x16x32_bf16 v[48:51], v[76:79], v[84:87], v[48:51]
	v_mfma_f32_16x16x32_bf16 v[44:47], v[68:71], v[96:99], v[44:47]
	v_mfma_f32_16x16x32_bf16 v[36:39], v[76:79], v[96:99], v[36:39]
	v_mfma_f32_16x16x32_bf16 v[28:31], v[68:71], v[184:187], v[28:31]
	v_mfma_f32_16x16x32_bf16 v[20:23], v[76:79], v[184:187], v[20:23]
	v_mfma_f32_16x16x32_bf16 v[16:19], v[68:71], v[192:195], v[16:19]
	v_mfma_f32_16x16x32_bf16 v[12:15], v[76:79], v[192:195], v[12:15]
	v_mfma_f32_16x16x32_bf16 v[56:59], v[216:219], v[80:83], v[56:59]
	v_mfma_f32_16x16x32_bf16 v[52:55], v[224:227], v[80:83], v[52:55]
	v_mfma_f32_16x16x32_bf16 v[40:43], v[216:219], v[92:95], v[40:43]
	v_mfma_f32_16x16x32_bf16 v[32:35], v[224:227], v[92:95], v[32:35]
	v_mfma_f32_16x16x32_bf16 v[24:27], v[216:219], v[180:183], v[24:27]
	v_mfma_f32_16x16x32_bf16 v[8:11], v[224:227], v[180:183], v[8:11]
	v_mfma_f32_16x16x32_bf16 v[4:7], v[216:219], v[188:191], v[4:7]
	v_mfma_f32_16x16x32_bf16 v[0:3], v[224:227], v[188:191], v[0:3]
	v_mfma_f32_16x16x32_bf16 v[56:59], v[220:223], v[84:87], v[56:59]
	v_mfma_f32_16x16x32_bf16 v[52:55], v[228:231], v[84:87], v[52:55]
	v_mfma_f32_16x16x32_bf16 v[40:43], v[220:223], v[96:99], v[40:43]
	v_mfma_f32_16x16x32_bf16 v[32:35], v[228:231], v[96:99], v[32:35]
	v_mfma_f32_16x16x32_bf16 v[24:27], v[220:223], v[184:187], v[24:27]
	v_mfma_f32_16x16x32_bf16 v[8:11], v[228:231], v[184:187], v[8:11]
	v_mfma_f32_16x16x32_bf16 v[4:7], v[220:223], v[192:195], v[4:7]
	v_mfma_f32_16x16x32_bf16 v[0:3], v[228:231], v[192:195], v[0:3]
	s_barrier
; DI float row_rstd(const float* ssq, int row, int fq) {
;   const f32x4 a = *(const f32x4*)(ssq + (size_t)row * 32 + fq * 8), b = *(const f32x4*)(ssq + (size_t)row * 32 + fq * 8 + 4);
;   float sm = ((a[0] + a[1]) + (a[2] + a[3])) + ((b[0] + b[1]) + (b[2] + b[3]));
;   sm += __shfl_xor(sm, 16); sm += __shfl_xor(sm, 32);
;   return rsqrtf(sm * (1.0f / 2048.f) + 1e-6f);
;   DI void operator()(const f32x4 (&acc)[2][2][4][2], const Unit& u, int wr, int wc, int fr, int fq) const {
;     const int col = u.pn * 128 + wc * 32 + 8 * fq;
;     float w0[8], w1[8], w2[8], bb[8];
; #pragma unroll
;     for (int e = 0; e < 8; ++e) { w0[e] = cw[col + e]; w1[e] = cw[5632 + col + e]; w2[e] = cw[2 * 5632 + col + e]; bb[e] = cb[col + e]; }
; #pragma unroll
;     for (int ai = 0; ai < 2; ++ai) {
;       const int row0 = u.pm * BM + ai * HALF + wr * 64, span = row0 >> 6;
;       float rsv[4];
; #pragma unroll
;       for (int m = 0; m < 4; ++m) rsv[m] = row_rstd(ssq, row0 + 16 * m + fr, fq);
	s_setprio 0
	s_cbranch_scc0 .LBB0_811
	s_lshl_b32 s35, s12, 8
	s_add_i32 s35, s35, s66
	v_or_b32_e32 v190, s35, v179
	v_ashrrev_i32_e32 v191, 31, v190
	v_lshlrev_b64 v[64:65], 7, v[190:191]
	v_or_b32_e32 v188, 16, v190
	v_lshl_add_u64 v[64:65], v[168:169], 0, v[64:65]
	v_ashrrev_i32_e32 v189, 31, v188
	global_load_dwordx4 v[192:195], v[64:65], off
	global_load_dwordx4 v[206:209], v[64:65], off offset:16
	v_lshlrev_b64 v[64:65], 7, v[188:189]
	v_lshl_add_u64 v[64:65], v[168:169], 0, v[64:65]
	global_load_dwordx4 v[212:215], v[64:65], off
	global_load_dwordx4 v[216:219], v[64:65], off offset:16
	v_or_b32_e32 v186, 32, v190
	v_ashrrev_i32_e32 v187, 31, v186
	v_lshlrev_b64 v[64:65], 7, v[186:187]
	v_or_b32_e32 v184, 48, v190
	v_lshl_add_u64 v[64:65], v[168:169], 0, v[64:65]
	v_ashrrev_i32_e32 v185, 31, v184
	global_load_dwordx4 v[220:223], v[64:65], off
	global_load_dwordx4 v[224:227], v[64:65], off offset:16
	v_lshlrev_b64 v[64:65], 7, v[184:185]
	v_lshl_add_u64 v[64:65], v[168:169], 0, v[64:65]
	global_load_dwordx4 v[228:231], v[64:65], off
	global_load_dwordx4 v[232:235], v[64:65], off offset:16
	v_lshl_or_b32 v180, s13, 7, v200
	v_and_b32_e32 v65, 64, v204
	v_xor_b32_e32 v64, 16, v204
	v_ashrrev_i32_e32 v181, 31, v180
	v_add_u32_e32 v65, 64, v65
	v_readlane_b32 s44, v243, 3
	v_xor_b32_e32 v66, 32, v204
	v_lshlrev_b64 v[182:183], 2, v[180:181]
	v_cmp_lt_i32_e32 vcc, v64, v65
	v_readlane_b32 s52, v243, 11
	v_readlane_b32 s53, v243, 12
	v_cndmask_b32_e32 v64, v204, v64, vcc
	v_cmp_lt_i32_e32 vcc, v66, v65
	v_lshl_add_u64 v[92:93], s[52:53], 0, v[182:183]
	v_readlane_b32 s54, v243, 13
	v_cndmask_b32_e32 v65, v204, v66, vcc
	v_add_co_u32_e32 v94, vcc, 0x5000, v92
	v_readlane_b32 s55, v243, 14
	s_nop 0
	v_addc_co_u32_e32 v95, vcc, 0, v93, vcc
	v_add_co_u32_e32 v96, vcc, 0xb000, v92
	v_lshl_add_u64 v[72:73], s[54:55], 0, v[182:183]
	v_lshl_add_u64 v[74:75], v[92:93], 0, s[26:27]
	v_lshl_add_u64 v[76:77], v[92:93], 0, s[28:29]
	v_addc_co_u32_e32 v97, vcc, 0, v93, vcc
	v_lshlrev_b32_e32 v187, 2, v64
	v_lshlrev_b32_e32 v185, 2, v65
	global_load_dwordx4 v[64:67], v[92:93], off offset:16
	global_load_dwordx4 v[80:83], v[92:93], off
	global_load_dwordx4 v[68:71], v[72:73], off offset:16
	global_load_dwordx4 v[84:87], v[72:73], off
	s_nop 0
	global_load_dwordx4 v[72:75], v[74:75], off offset:16
	s_nop 0
	global_load_dwordx4 v[76:79], v[76:77], off offset:16
	s_nop 0
	global_load_dwordx4 v[92:95], v[94:95], off offset:2048
	s_nop 0
	global_load_dwordx4 v[96:99], v[96:97], off
	v_mov_b32_e32 v211, 0
	v_mov_b32_e32 v205, 0
	v_readlane_b32 s45, v243, 4
	v_readlane_b32 s46, v243, 5
	v_readlane_b32 s47, v243, 6
	v_readlane_b32 s48, v243, 7
	v_readlane_b32 s49, v243, 8
	v_readlane_b32 s50, v243, 9
	v_readlane_b32 s51, v243, 10
	v_readlane_b32 s56, v243, 15
	v_readlane_b32 s57, v243, 16
	v_readlane_b32 s58, v243, 17
	v_readlane_b32 s59, v243, 18
	s_waitcnt vmcnt(0)
	v_mov_b32_e32 v196, v192
	v_mov_b32_e32 v197, v206
	v_mov_b32_e32 v206, v193
	v_mov_b32_e32 v192, v194
	v_mov_b32_e32 v193, v208
	v_mov_b32_e32 v208, v195
	v_pk_add_f32 v[194:195], v[196:197], v[206:207]
	v_pk_add_f32 v[192:193], v[192:193], v[208:209]
	v_mov_b32_e32 v196, v212
	v_mov_b32_e32 v197, v216
	v_mov_b32_e32 v216, v213
	v_mov_b32_e32 v206, v214
	v_mov_b32_e32 v207, v218
	v_mov_b32_e32 v218, v215
	v_pk_add_f32 v[192:193], v[194:195], v[192:193]
	v_pk_add_f32 v[194:195], v[196:197], v[216:217]
	v_pk_add_f32 v[196:197], v[206:207], v[218:219]
	v_mov_b32_e32 v208, v220
	v_pk_add_f32 v[194:195], v[194:195], v[196:197]
	v_mov_b32_e32 v197, v192
	v_mov_b32_e32 v196, v194
	v_mov_b32_e32 v192, v195
	v_pk_add_f32 v[192:193], v[196:197], v[192:193]
	ds_bpermute_b32 v195, v187, v193
	ds_bpermute_b32 v194, v187, v192
	v_mov_b32_e32 v209, v224
	v_mov_b32_e32 v224, v221
	v_mov_b32_e32 v212, v222
	v_mov_b32_e32 v213, v226
	s_waitcnt lgkmcnt(0)
	v_pk_add_f32 v[192:193], v[192:193], v[194:195]
	ds_bpermute_b32 v195, v185, v193
	ds_bpermute_b32 v194, v185, v192
	v_mov_b32_e32 v226, v223
	v_mov_b32_e32 v196, v228
	v_mov_b32_e32 v197, v232
	v_mov_b32_e32 v232, v229
	s_waitcnt lgkmcnt(0)
; DI unsigned pack2(float lo, float hi) { f32x2 v = {lo, hi}; bf16v2 r = __builtin_convertvector(v, bf16v2); return __builtin_bit_cast(unsigned, r); }
; DI float silu_f(float x) { return x * sigmoid_f(x); }
; DI float dpp_ror1(float v) { return __int_as_float(__builtin_amdgcn_update_dpp(0, __float_as_int(v), 0x121, 0xf, 0xf, false)); }
; DI float dpp_ror2(float v) { return __int_as_float(__builtin_amdgcn_update_dpp(0, __float_as_int(v), 0x122, 0xf, 0xf, false)); }
;   DI void operator()(const f32x4 (&acc)[2][2][4][2], const Unit& u, int wr, int wc, int fr, int fq) const {
;     ...
;       for (int m = 0; m < 4; ++m) rsv[m] = row_rstd(ssq, row0 + 16 * m + fr, fq);
;       float p1[8], p2[8];
; #pragma unroll
;       for (int e = 0; e < 8; ++e) { p1[e] = 0.f; p2[e] = 0.f; }
; #pragma unroll
;       for (int m = 0; m < 4; ++m) {
;         float g[8], uu[8], a[8];
;         const float rs = rsv[m];
; #pragma unroll
;         for (int e = 0; e < 4; ++e) { g[e] = acc[ai][0][m][0][e] * rs; g[4 + e] = acc[ai][0][m][1][e] * rs; uu[e] = acc[ai][1][m][0][e] * rs; uu[4 + e] = acc[ai][1][m][1][e] * rs; }
; #pragma unroll
;         for (int e = 0; e < 8; ++e) {
;           const float x1 = dpp_ror1(g[e]), x2 = dpp_ror2(g[e]);
;           const float pr1 = (fr == 0) ? p1[e] : x1, pr2 = (fr < 2) ? p2[e] : x2;
;           a[e] = w2[e] * g[e] + w1[e] * pr1 + w0[e] * pr2 + bb[e];
;           p1[e] = x1; p2[e] = x2;
;         }
;         if (m == 0 && fr < 2) {
;           float* ha = headA + (size_t)(span * 2 + fr) * 5632 + col; float* hu = headU + (size_t)(span * 2 + fr) * 5632 + col;
;           *(f32x4*)ha = (f32x4){a[0], a[1], a[2], a[3]}; *(f32x4*)(ha + 4) = (f32x4){a[4], a[5], a[6], a[7]};
;           *(f32x4*)hu = (f32x4){uu[0], uu[1], uu[2], uu[3]}; *(f32x4*)(hu + 4) = (f32x4){uu[4], uu[5], uu[6], uu[7]};
;         } else {
;           u32x4 w;
;           w.x = pack2(silu_f(a[0]) * uu[0], silu_f(a[1]) * uu[1]);
;           w.y = pack2(silu_f(a[2]) * uu[2], silu_f(a[3]) * uu[3]);
;           w.z = pack2(silu_f(a[4]) * uu[4], silu_f(a[5]) * uu[5]);
;           w.w = pack2(silu_f(a[6]) * uu[6], silu_f(a[7]) * uu[7]);
;           *(u32x4*)(H + (size_t)(row0 + 16 * m + fr) * 5632 + col) = w;
	v_pk_add_f32 v[192:193], v[192:193], v[194:195]
	v_mov_b32_e32 v206, v230
	v_pk_fma_f32 v[192:193], v[192:193], s[30:31], v[178:179] op_sel_hi:[1,0,0]
	v_mov_b32_e32 v207, v234
	v_mul_f32_e32 v189, 0x4b800000, v193
	v_cmp_gt_f32_e64 s[12:13], s74, v193
	v_mov_b32_e32 v234, v231
	v_pk_add_f32 v[208:209], v[208:209], v[224:225]
	v_cndmask_b32_e64 v189, v193, v189, s[12:13]
	v_rsq_f32_e32 v189, v189
	v_pk_add_f32 v[212:213], v[212:213], v[226:227]
	v_pk_add_f32 v[196:197], v[196:197], v[232:233]
	v_pk_add_f32 v[194:195], v[206:207], v[234:235]
	v_mul_f32_e32 v191, 0x45800000, v189
	v_cndmask_b32_e64 v220, v189, v191, s[12:13]
	v_pk_add_f32 v[208:209], v[208:209], v[212:213]
	v_pk_add_f32 v[194:195], v[196:197], v[194:195]
	v_pk_mul_f32 v[156:157], v[156:157], v[220:221] op_sel_hi:[1,0]
	v_mov_b32_e32 v216, 0
	v_mov_b32_e32 v218, 0
	v_mov_b32_e32 v196, v194
	v_mov_b32_e32 v197, v208
	v_mov_b32_e32 v208, v195
	v_mov_b32_dpp v216, v156 row_ror:1 row_mask:0xf bank_mask:0xf
	v_mov_b32_dpp v218, v157 row_ror:1 row_mask:0xf bank_mask:0xf
	v_pk_add_f32 v[194:195], v[196:197], v[208:209]
	v_cndmask_b32_e64 v207, v218, 0, s[0:1]
	v_cndmask_b32_e64 v206, v216, 0, s[0:1]
	v_pk_mul_f32 v[158:159], v[158:159], v[220:221] op_sel_hi:[1,0]
	v_mov_b32_e32 v212, 0
	v_mov_b32_e32 v214, 0
	ds_bpermute_b32 v197, v187, v195
	ds_bpermute_b32 v196, v187, v194
	v_mov_b32_e32 v215, 0
	v_mov_b32_e32 v217, 0
	v_pk_mul_f32 v[206:207], v[92:93], v[206:207]
	v_mov_b32_dpp v212, v158 row_ror:1 row_mask:0xf bank_mask:0xf
	v_mov_b32_dpp v214, v159 row_ror:1 row_mask:0xf bank_mask:0xf
	v_mov_b32_dpp v215, v156 row_ror:2 row_mask:0xf bank_mask:0xf
	v_mov_b32_dpp v217, v157 row_ror:2 row_mask:0xf bank_mask:0xf
	v_pk_fma_f32 v[156:157], v[96:97], v[156:157], v[206:207]
	v_mov_b32_e32 v213, 0
	v_cndmask_b32_e64 v207, v214, 0, s[0:1]
	v_cndmask_b32_e64 v206, v212, 0, s[0:1]
	v_cndmask_b32_e64 v209, v217, 0, s[4:5]
	v_cndmask_b32_e64 v208, v215, 0, s[4:5]
	v_mov_b32_dpp v211, v158 row_ror:2 row_mask:0xf bank_mask:0xf
	v_mov_b32_dpp v213, v159 row_ror:2 row_mask:0xf bank_mask:0xf
	v_pk_mul_f32 v[206:207], v[94:95], v[206:207]
	v_pk_fma_f32 v[156:157], v[80:81], v[208:209], v[156:157]
	v_cndmask_b32_e64 v209, v213, 0, s[4:5]
	v_cndmask_b32_e64 v208, v211, 0, s[4:5]
	v_pk_fma_f32 v[158:159], v[98:99], v[158:159], v[206:207]
	v_pk_mul_f32 v[144:145], v[144:145], v[220:221] op_sel_hi:[1,0]
	v_pk_fma_f32 v[158:159], v[82:83], v[208:209], v[158:159]
	v_mov_b32_e32 v207, 0
	v_mov_b32_e32 v209, 0
	v_pk_mul_f32 v[146:147], v[146:147], v[220:221] op_sel_hi:[1,0]
	v_mov_b32_e32 v191, 0
	s_waitcnt lgkmcnt(0)
	v_pk_add_f32 v[194:195], v[194:195], v[196:197]
	v_mov_b32_dpp v207, v144 row_ror:1 row_mask:0xf bank_mask:0xf
	v_mov_b32_dpp v209, v145 row_ror:1 row_mask:0xf bank_mask:0xf
	v_mov_b32_dpp v191, v146 row_ror:1 row_mask:0xf bank_mask:0xf
	v_mov_b32_dpp v205, v147 row_ror:1 row_mask:0xf bank_mask:0xf
	ds_bpermute_b32 v197, v185, v195
	ds_bpermute_b32 v196, v185, v194
	v_pk_mul_f32 v[152:153], v[152:153], v[220:221] op_sel_hi:[1,0]
	v_pk_mul_f32 v[148:149], v[148:149], v[220:221] op_sel_hi:[1,0]
	v_pk_mul_f32 v[154:155], v[154:155], v[220:221] op_sel_hi:[1,0]
	v_pk_mul_f32 v[150:151], v[150:151], v[220:221] op_sel_hi:[1,0]
	v_mov_b32_e32 v206, 0
	v_mov_b32_e32 v208, 0
	v_cndmask_b32_e64 v223, v209, 0, s[0:1]
	v_cndmask_b32_e64 v222, v207, 0, s[0:1]
	v_mov_b32_e32 v189, 0
	v_mov_b32_e32 v193, 0
	v_cndmask_b32_e64 v221, v205, 0, s[0:1]
	v_cndmask_b32_e64 v220, v191, 0, s[0:1]
	v_mov_b32_dpp v206, v144 row_ror:2 row_mask:0xf bank_mask:0xf
	v_mov_b32_dpp v208, v145 row_ror:2 row_mask:0xf bank_mask:0xf
	v_pk_mul_f32 v[222:223], v[72:73], v[222:223]
	v_mov_b32_dpp v189, v146 row_ror:2 row_mask:0xf bank_mask:0xf
	v_mov_b32_dpp v193, v147 row_ror:2 row_mask:0xf bank_mask:0xf
	v_pk_mul_f32 v[220:221], v[74:75], v[220:221]
	v_cndmask_b32_e64 v225, v208, 0, s[4:5]
	v_cndmask_b32_e64 v224, v206, 0, s[4:5]
	v_pk_fma_f32 v[144:145], v[76:77], v[144:145], v[222:223]
	v_cndmask_b32_e64 v223, v193, 0, s[4:5]
	v_cndmask_b32_e64 v222, v189, 0, s[4:5]
	v_pk_fma_f32 v[146:147], v[78:79], v[146:147], v[220:221]
	v_pk_fma_f32 v[144:145], v[64:65], v[224:225], v[144:145]
	v_pk_fma_f32 v[146:147], v[66:67], v[222:223], v[146:147]
	v_cmp_gt_f32_e32 vcc, s74, v192
	v_pk_add_f32 v[156:157], v[84:85], v[156:157]
	v_pk_add_f32 v[158:159], v[86:87], v[158:159]
	v_pk_add_f32 v[144:145], v[68:69], v[144:145]
	v_pk_add_f32 v[146:147], v[70:71], v[146:147]
	s_and_saveexec_b64 s[12:13], s[10:11]
	s_xor_b64 s[12:13], exec, s[12:13]
	s_cbranch_execz .LBB0_814
	v_mul_f32_e32 v219, 0xbfb8aa3b, v156
	v_exp_f32_e32 v219, v219
	v_mul_f32_e32 v220, 0xbfb8aa3b, v157
	v_exp_f32_e32 v220, v220
	v_mul_f32_e32 v222, 0xbfb8aa3b, v159
	v_add_f32_e32 v219, 1.0, v219
	v_exp_f32_e32 v223, v222
	v_add_f32_e32 v221, 1.0, v220
	v_rcp_f32_e32 v220, v219
	v_mul_f32_e32 v219, 0xbfb8aa3b, v158
	v_exp_f32_e32 v219, v219
	v_rcp_f32_e32 v221, v221
	v_add_f32_e32 v219, 1.0, v219
	v_rcp_f32_e32 v222, v219
	v_add_f32_e32 v219, 1.0, v223
	v_rcp_f32_e32 v223, v219
	v_pk_mul_f32 v[156:157], v[156:157], v[220:221]
	s_nop 0
	v_pk_mul_f32 v[152:153], v[152:153], v[156:157]
	v_pk_mul_f32 v[156:157], v[158:159], v[222:223]
	v_cvt_pk_bf16_f32 v152, v152, v153
	v_mul_f32_e32 v153, 0xbfb8aa3b, v144
	v_pk_mul_f32 v[154:155], v[154:155], v[156:157]
	v_exp_f32_e32 v156, v153
	v_mul_f32_e32 v153, 0xbfb8aa3b, v145
	v_exp_f32_e32 v157, v153
	v_cvt_pk_bf16_f32 v153, v154, v155
	v_add_f32_e32 v154, 1.0, v156
	v_mul_f32_e32 v156, 0xbfb8aa3b, v146
	v_add_f32_e32 v155, 1.0, v157
	v_mul_f32_e32 v157, 0xbfb8aa3b, v147
	v_exp_f32_e32 v156, v156
	v_exp_f32_e32 v157, v157
	v_rcp_f32_e32 v154, v154
	v_rcp_f32_e32 v155, v155
	v_add_f32_e32 v156, 1.0, v156
	v_add_f32_e32 v157, 1.0, v157
	v_rcp_f32_e32 v156, v156
	v_rcp_f32_e32 v157, v157
	v_pk_mul_f32 v[144:145], v[144:145], v[154:155]
	s_nop 0
	v_pk_mul_f32 v[144:145], v[148:149], v[144:145]
	s_nop 0
	v_cvt_pk_bf16_f32 v154, v144, v145
	v_pk_mul_f32 v[144:145], v[146:147], v[156:157]
	s_nop 0
	v_pk_mul_f32 v[144:145], v[150:151], v[144:145]
	s_nop 0
	v_cvt_pk_bf16_f32 v155, v144, v145
	v_mov_b64_e32 v[144:145], s[16:17]
	v_mad_i64_i32 v[144:145], s[14:15], v190, s75, v[144:145]
	v_lshl_add_u64 v[144:145], v[180:181], 1, v[144:145]
	global_store_dwordx4 v[144:145], v[152:155], off

; #define PG8_STAGE(bufoff, gbase, voff) do { _Pragma("unroll") for (int _i = 0; _i < 2; ++_i) \
;     __builtin_amdgcn_global_load_lds((const unsigned*)((const char*)(gbase) + (voff)[_i]), (LAS unsigned*)(lds + (bufoff) + ldsw + _i * 8192), 16, 0, 0); } while (0)
; #define PG8_LDA(dst, b, h) do { _Pragma("unroll") for (int m = 0; m < 4; ++m) _Pragma("unroll") for (int k = 0; k < 2; ++k) dst[m][k] = *(const LAS bf16x8*)(lds + PG8_SA(b, h) + aoff + m * 2048 + k * 1024); } while (0)
; #define PG8_LDB(dst, b, h) do { _Pragma("unroll") for (int n = 0; n < 2; ++n) _Pragma("unroll") for (int k = 0; k < 2; ++k) dst[n][k] = *(const LAS bf16x8*)(lds + PG8_SB(b, h) + boff + n * 2048 + k * 1024); } while (0)
; #define PG8_MMA(ai, bj, At, Bt) do { __builtin_amdgcn_s_setprio(1); _Pragma("unroll") for (int m = 0; m < 4; ++m) _Pragma("unroll") for (int n = 0; n < 2; ++n) _Pragma("unroll") for (int k = 0; k < 2; ++k) \
;     acc[ai][bj][m][n] = __builtin_amdgcn_mfma_f32_16x16x32_bf16(Bt[n][k], At[m][k], acc[ai][bj][m][n], 0, 0, 0); __builtin_amdgcn_s_setprio(0); } while (0)
; #define PG8_WAIT_V(n) asm volatile("s_waitcnt vmcnt(" #n ")" ::: "memory")
; #define PG8_WAIT_L(n) asm volatile("s_waitcnt lgkmcnt(" #n ")" ::: "memory")
; #define PG8_BAR __builtin_amdgcn_s_barrier()
; #define PG8_SCHED __builtin_amdgcn_sched_barrier(0)
; template <class Epi, class Sched = StaticOrder>
; DI void gemm_phase(LAS unsigned char* lds, const Gemm g, const Sched& S, const Epi& E) {
;     ...
;       PG8_LDB(B0, 0, 0); PG8_SCHED; PG8_LDA(At, 0, 0); PG8_STAGE(PG8_SA(1, 1), a1 + hstep, voffA);
;       PG8_WAIT_L(8); PG8_BAR; PG8_WAIT_L(0); PG8_MMA(0, 0, At, B0); PG8_BAR; PG8_SCHED;
;       PG8_LDB(B1, 0, 1); PG8_STAGE(PG8_SB(0, 0), b2, voffB);
;       PG8_BAR; PG8_WAIT_L(0); PG8_MMA(0, 1, At, B1); PG8_BAR;
;       PG8_LDA(At, 0, 1); PG8_STAGE(PG8_SA(0, 0), a2, voffA);
;       PG8_BAR; PG8_WAIT_L(0); PG8_MMA(1, 0, At, B0); PG8_BAR; PG8_SCHED;
;       PG8_STAGE(PG8_SB(0, 1), b2 + hstep, voffB);
;       PG8_WAIT_V(6); PG8_BAR; PG8_MMA(1, 1, At, B1); PG8_BAR;
.LBB0_961:
	ds_read_b128 v[128:131], v214
	ds_read_b128 v[132:135], v214 offset:1024
	ds_read_b128 v[136:139], v214 offset:2048
	ds_read_b128 v[140:143], v214 offset:3072
	s_add_u32 s20, s18, 0xffea0080
	s_addc_u32 s21, s19, -1
	s_cmpk_eq_i32 s44, 0x54
	s_cselect_b32 s23, s5, s21
	s_cselect_b32 s22, s4, s20
	s_cselect_b32 s21, s7, s43
	s_cselect_b32 s20, s6, s42
	s_add_i32 m0, s31, 0xc000
	ds_read_b128 v[144:147], v215
	ds_read_b128 v[148:151], v215 offset:1024
	ds_read_b128 v[152:155], v215 offset:2048
	ds_read_b128 v[156:159], v215 offset:3072
	ds_read_b128 v[160:163], v215 offset:4096
	ds_read_b128 v[164:167], v215 offset:5120
	ds_read_b128 v[168:171], v215 offset:6144
	ds_read_b128 v[172:175], v215 offset:7168
	global_load_lds_dwordx4 v184, s[18:19]
	s_add_i32 m0, s31, 0xe000
	s_nop 0
	global_load_lds_dwordx4 v186, s[18:19]
	ds_read_b128 v[192:195], v216
	ds_read_b128 v[196:199], v216 offset:1024
	ds_read_b128 v[200:203], v216 offset:2048
	ds_read_b128 v[204:207], v216 offset:3072
	s_waitcnt vmcnt(8)
	s_waitcnt lgkmcnt(4)
	s_setprio 1
	s_barrier
	v_mfma_f32_16x16x32_bf16 v[124:127], v[128:131], v[144:147], v[124:127]
	v_mfma_f32_16x16x32_bf16 v[120:123], v[136:139], v[144:147], v[120:123]
	v_mfma_f32_16x16x32_bf16 v[108:111], v[128:131], v[152:155], v[108:111]
	v_mfma_f32_16x16x32_bf16 v[104:107], v[136:139], v[152:155], v[104:107]
	v_mfma_f32_16x16x32_bf16 v[92:95], v[128:131], v[160:163], v[92:95]
	v_mfma_f32_16x16x32_bf16 v[88:91], v[136:139], v[160:163], v[88:91]
	v_mfma_f32_16x16x32_bf16 v[76:79], v[128:131], v[168:171], v[76:79]
	v_mfma_f32_16x16x32_bf16 v[72:75], v[136:139], v[168:171], v[72:75]
	v_mfma_f32_16x16x32_bf16 v[124:127], v[132:135], v[148:151], v[124:127]
	v_mfma_f32_16x16x32_bf16 v[120:123], v[140:143], v[148:151], v[120:123]
	v_mfma_f32_16x16x32_bf16 v[108:111], v[132:135], v[156:159], v[108:111]
	v_mfma_f32_16x16x32_bf16 v[104:107], v[140:143], v[156:159], v[104:107]
	v_mfma_f32_16x16x32_bf16 v[92:95], v[132:135], v[164:167], v[92:95]
	v_mfma_f32_16x16x32_bf16 v[88:91], v[140:143], v[164:167], v[88:91]
	v_mfma_f32_16x16x32_bf16 v[76:79], v[132:135], v[172:175], v[76:79]
	v_mfma_f32_16x16x32_bf16 v[72:75], v[140:143], v[172:175], v[72:75]
	s_waitcnt lgkmcnt(0)
	v_mfma_f32_16x16x32_bf16 v[116:119], v[192:195], v[144:147], v[116:119]
	v_mfma_f32_16x16x32_bf16 v[112:115], v[200:203], v[144:147], v[112:115]
	v_mfma_f32_16x16x32_bf16 v[100:103], v[192:195], v[152:155], v[100:103]
	v_mfma_f32_16x16x32_bf16 v[96:99], v[200:203], v[152:155], v[96:99]
	v_mfma_f32_16x16x32_bf16 v[84:87], v[192:195], v[160:163], v[84:87]
	v_mfma_f32_16x16x32_bf16 v[80:83], v[200:203], v[160:163], v[80:83]
	v_mfma_f32_16x16x32_bf16 v[68:71], v[192:195], v[168:171], v[68:71]
	v_mfma_f32_16x16x32_bf16 v[64:67], v[200:203], v[168:171], v[64:67]
	v_mfma_f32_16x16x32_bf16 v[116:119], v[196:199], v[148:151], v[116:119]
	v_mfma_f32_16x16x32_bf16 v[112:115], v[204:207], v[148:151], v[112:115]
	v_mfma_f32_16x16x32_bf16 v[100:103], v[196:199], v[156:159], v[100:103]
	v_mfma_f32_16x16x32_bf16 v[96:99], v[204:207], v[156:159], v[96:99]
	v_mfma_f32_16x16x32_bf16 v[84:87], v[196:199], v[164:167], v[84:87]
	v_mfma_f32_16x16x32_bf16 v[80:83], v[204:207], v[164:167], v[80:83]
	v_mfma_f32_16x16x32_bf16 v[68:71], v[196:199], v[172:175], v[68:71]
	v_mfma_f32_16x16x32_bf16 v[64:67], v[204:207], v[172:175], v[64:67]
	s_barrier
	s_setprio 0
	s_add_i32 s45, s46, s30
	s_add_u32 s98, s20, 0x80
	s_addc_u32 s99, s21, 0
	s_add_u32 s100, s22, 0x80
	s_addc_u32 s101, s23, 0
	ds_read_b128 v[144:147], v215 offset:16384
	ds_read_b128 v[148:151], v215 offset:17408
	ds_read_b128 v[152:155], v215 offset:18432
	ds_read_b128 v[156:159], v215 offset:19456
	ds_read_b128 v[160:163], v215 offset:20480
	ds_read_b128 v[164:167], v215 offset:21504
	ds_read_b128 v[168:171], v215 offset:22528
	ds_read_b128 v[172:175], v215 offset:23552
	s_mov_b32 m0, s45
	s_nop 0
	global_load_lds_dwordx4 v178, s[20:21]
	s_add_i32 m0, s45, 0x2000
	s_nop 0
	global_load_lds_dwordx4 v182, s[20:21]
	s_mov_b32 m0, s31
	s_nop 0
	global_load_lds_dwordx4 v176, s[22:23]
	s_mov_b32 m0, s33
	s_nop 0
	global_load_lds_dwordx4 v180, s[22:23]
	s_add_u32 s52, s20, 0x160000
	s_addc_u32 s53, s21, 0
	s_add_i32 s45, s47, s30
	s_waitcnt vmcnt(6)
	s_waitcnt lgkmcnt(0)
	s_setprio 1
	s_barrier
	v_mfma_f32_16x16x32_bf16 v[60:63], v[128:131], v[144:147], v[60:63]
	s_mov_b32 m0, s45
	v_mfma_f32_16x16x32_bf16 v[56:59], v[136:139], v[144:147], v[56:59]
	global_load_lds_dwordx4 v178, s[52:53]
	v_mfma_f32_16x16x32_bf16 v[44:47], v[128:131], v[152:155], v[44:47]
	s_bitset1_b32 m0, 13
	v_mfma_f32_16x16x32_bf16 v[40:43], v[136:139], v[152:155], v[40:43]
	global_load_lds_dwordx4 v182, s[52:53]
	v_mfma_f32_16x16x32_bf16 v[28:31], v[128:131], v[160:163], v[28:31]
	v_mfma_f32_16x16x32_bf16 v[24:27], v[136:139], v[160:163], v[24:27]
	v_mfma_f32_16x16x32_bf16 v[12:15], v[128:131], v[168:171], v[12:15]
	v_mfma_f32_16x16x32_bf16 v[8:11], v[136:139], v[168:171], v[8:11]
	v_mfma_f32_16x16x32_bf16 v[60:63], v[132:135], v[148:151], v[60:63]
	v_mfma_f32_16x16x32_bf16 v[56:59], v[140:143], v[148:151], v[56:59]
	v_mfma_f32_16x16x32_bf16 v[44:47], v[132:135], v[156:159], v[44:47]
	v_mfma_f32_16x16x32_bf16 v[40:43], v[140:143], v[156:159], v[40:43]
	v_mfma_f32_16x16x32_bf16 v[28:31], v[132:135], v[164:167], v[28:31]
	v_mfma_f32_16x16x32_bf16 v[24:27], v[140:143], v[164:167], v[24:27]
	v_mfma_f32_16x16x32_bf16 v[12:15], v[132:135], v[172:175], v[12:15]
	v_mfma_f32_16x16x32_bf16 v[8:11], v[140:143], v[172:175], v[8:11]
	v_mfma_f32_16x16x32_bf16 v[52:55], v[192:195], v[144:147], v[52:55]
	v_mfma_f32_16x16x32_bf16 v[48:51], v[200:203], v[144:147], v[48:51]
	v_mfma_f32_16x16x32_bf16 v[36:39], v[192:195], v[152:155], v[36:39]
	v_mfma_f32_16x16x32_bf16 v[32:35], v[200:203], v[152:155], v[32:35]
	v_mfma_f32_16x16x32_bf16 v[20:23], v[192:195], v[160:163], v[20:23]
	v_mfma_f32_16x16x32_bf16 v[16:19], v[200:203], v[160:163], v[16:19]
	v_mfma_f32_16x16x32_bf16 v[4:7], v[192:195], v[168:171], v[4:7]
	v_mfma_f32_16x16x32_bf16 v[0:3], v[200:203], v[168:171], v[0:3]
	v_mfma_f32_16x16x32_bf16 v[52:55], v[196:199], v[148:151], v[52:55]
	v_mfma_f32_16x16x32_bf16 v[48:51], v[204:207], v[148:151], v[48:51]
	v_mfma_f32_16x16x32_bf16 v[36:39], v[196:199], v[156:159], v[36:39]
	v_mfma_f32_16x16x32_bf16 v[32:35], v[204:207], v[156:159], v[32:35]
	v_mfma_f32_16x16x32_bf16 v[20:23], v[196:199], v[164:167], v[20:23]
	v_mfma_f32_16x16x32_bf16 v[16:19], v[204:207], v[164:167], v[16:19]
	v_mfma_f32_16x16x32_bf16 v[4:7], v[196:199], v[172:175], v[4:7]
	v_mfma_f32_16x16x32_bf16 v[0:3], v[204:207], v[172:175], v[0:3]
	s_barrier
; #define PG8_STAGE(bufoff, gbase, voff) do { _Pragma("unroll") for (int _i = 0; _i < 2; ++_i) \
;     __builtin_amdgcn_global_load_lds((const unsigned*)((const char*)(gbase) + (voff)[_i]), (LAS unsigned*)(lds + (bufoff) + ldsw + _i * 8192), 16, 0, 0); } while (0)
; #define PG8_LDA(dst, b, h) do { _Pragma("unroll") for (int m = 0; m < 4; ++m) _Pragma("unroll") for (int k = 0; k < 2; ++k) dst[m][k] = *(const LAS bf16x8*)(lds + PG8_SA(b, h) + aoff + m * 2048 + k * 1024); } while (0)
; #define PG8_LDB(dst, b, h) do { _Pragma("unroll") for (int n = 0; n < 2; ++n) _Pragma("unroll") for (int k = 0; k < 2; ++k) dst[n][k] = *(const LAS bf16x8*)(lds + PG8_SB(b, h) + boff + n * 2048 + k * 1024); } while (0)
; #define PG8_MMA(ai, bj, At, Bt) do { __builtin_amdgcn_s_setprio(1); _Pragma("unroll") for (int m = 0; m < 4; ++m) _Pragma("unroll") for (int n = 0; n < 2; ++n) _Pragma("unroll") for (int k = 0; k < 2; ++k) \
;     acc[ai][bj][m][n] = __builtin_amdgcn_mfma_f32_16x16x32_bf16(Bt[n][k], At[m][k], acc[ai][bj][m][n], 0, 0, 0); __builtin_amdgcn_s_setprio(0); } while (0)
; #define PG8_WAIT_V(n) asm volatile("s_waitcnt vmcnt(" #n ")" ::: "memory")
; #define PG8_WAIT_L(n) asm volatile("s_waitcnt lgkmcnt(" #n ")" ::: "memory")
; #define PG8_BAR __builtin_amdgcn_s_barrier()
; #define PG8_SCHED __builtin_amdgcn_sched_barrier(0)
; template <class Epi, class Sched = StaticOrder>
; DI void gemm_phase(LAS unsigned char* lds, const Gemm g, const Sched& S, const Epi& E) {
;     ...
;       PG8_LDB(B0, 1, 0); PG8_SCHED; PG8_LDA(At, 1, 0); PG8_STAGE(PG8_SA(0, 1), a2 + hstep, voffA);
;       PG8_WAIT_L(8); PG8_BAR; PG8_WAIT_L(0); PG8_MMA(0, 0, At, B0); PG8_BAR; PG8_SCHED;
;       PG8_LDB(B1, 1, 1); PG8_STAGE(PG8_SB(1, 0), b3, voffB);
;       PG8_BAR; PG8_WAIT_L(0); PG8_MMA(0, 1, At, B1); PG8_BAR;
;       PG8_LDA(At, 1, 1); PG8_STAGE(PG8_SA(1, 0), a3, voffA);
;       PG8_BAR; PG8_WAIT_L(0); PG8_MMA(1, 0, At, B0); PG8_BAR; PG8_SCHED;
;       PG8_STAGE(PG8_SB(1, 1), b3 + hstep, voffB);
;       PG8_WAIT_V(6); PG8_BAR; PG8_MMA(1, 1, At, B1); PG8_BAR;
	s_setprio 0
	s_add_i32 s45, 0, 0x18000
	v_add_u32_e32 v140, s45, v212
	ds_read_b128 v[128:131], v140
	ds_read_b128 v[132:135], v140 offset:1024
	ds_read_b128 v[136:139], v140 offset:2048
	ds_read_b128 v[140:143], v140 offset:3072
	s_add_u32 s22, s22, 0x160000
	s_addc_u32 s23, s23, 0
	s_mov_b32 m0, s34
	ds_read_b128 v[144:147], v215 offset:32768
	ds_read_b128 v[148:151], v215 offset:33792
	ds_read_b128 v[152:155], v215 offset:34816
	ds_read_b128 v[156:159], v215 offset:35840
	ds_read_b128 v[160:163], v215 offset:36864
	ds_read_b128 v[164:167], v215 offset:37888
	ds_read_b128 v[168:171], v215 offset:38912
	ds_read_b128 v[172:175], v215 offset:39936
	global_load_lds_dwordx4 v176, s[22:23]
	s_mov_b32 m0, s35
	s_nop 0
	global_load_lds_dwordx4 v180, s[22:23]
	s_add_i32 s22, 0, 0x1c000
	v_add_u32_e32 v204, s22, v212
	ds_read_b128 v[192:195], v204
	ds_read_b128 v[196:199], v204 offset:1024
	ds_read_b128 v[200:203], v204 offset:2048
	ds_read_b128 v[204:207], v204 offset:3072
	s_waitcnt vmcnt(8)
	s_waitcnt lgkmcnt(4)
	s_setprio 1
	s_barrier
	v_mfma_f32_16x16x32_bf16 v[124:127], v[128:131], v[144:147], v[124:127]
	v_mfma_f32_16x16x32_bf16 v[120:123], v[136:139], v[144:147], v[120:123]
	v_mfma_f32_16x16x32_bf16 v[108:111], v[128:131], v[152:155], v[108:111]
	v_mfma_f32_16x16x32_bf16 v[104:107], v[136:139], v[152:155], v[104:107]
	v_mfma_f32_16x16x32_bf16 v[92:95], v[128:131], v[160:163], v[92:95]
	v_mfma_f32_16x16x32_bf16 v[88:91], v[136:139], v[160:163], v[88:91]
	v_mfma_f32_16x16x32_bf16 v[76:79], v[128:131], v[168:171], v[76:79]
	v_mfma_f32_16x16x32_bf16 v[72:75], v[136:139], v[168:171], v[72:75]
	v_mfma_f32_16x16x32_bf16 v[124:127], v[132:135], v[148:151], v[124:127]
	v_mfma_f32_16x16x32_bf16 v[120:123], v[140:143], v[148:151], v[120:123]
	v_mfma_f32_16x16x32_bf16 v[108:111], v[132:135], v[156:159], v[108:111]
	v_mfma_f32_16x16x32_bf16 v[104:107], v[140:143], v[156:159], v[104:107]
	v_mfma_f32_16x16x32_bf16 v[92:95], v[132:135], v[164:167], v[92:95]
	v_mfma_f32_16x16x32_bf16 v[88:91], v[140:143], v[164:167], v[88:91]
	v_mfma_f32_16x16x32_bf16 v[76:79], v[132:135], v[172:175], v[76:79]
	v_mfma_f32_16x16x32_bf16 v[72:75], v[140:143], v[172:175], v[72:75]
	s_waitcnt lgkmcnt(0)
	v_mfma_f32_16x16x32_bf16 v[116:119], v[192:195], v[144:147], v[116:119]
	v_mfma_f32_16x16x32_bf16 v[112:115], v[200:203], v[144:147], v[112:115]
	v_mfma_f32_16x16x32_bf16 v[100:103], v[192:195], v[152:155], v[100:103]
	v_mfma_f32_16x16x32_bf16 v[96:99], v[200:203], v[152:155], v[96:99]
	v_mfma_f32_16x16x32_bf16 v[84:87], v[192:195], v[160:163], v[84:87]
	v_mfma_f32_16x16x32_bf16 v[80:83], v[200:203], v[160:163], v[80:83]
	v_mfma_f32_16x16x32_bf16 v[68:71], v[192:195], v[168:171], v[68:71]
	v_mfma_f32_16x16x32_bf16 v[64:67], v[200:203], v[168:171], v[64:67]
	v_mfma_f32_16x16x32_bf16 v[116:119], v[196:199], v[148:151], v[116:119]
	v_mfma_f32_16x16x32_bf16 v[112:115], v[204:207], v[148:151], v[112:115]
	v_mfma_f32_16x16x32_bf16 v[100:103], v[196:199], v[156:159], v[100:103]
	v_mfma_f32_16x16x32_bf16 v[96:99], v[204:207], v[156:159], v[96:99]
	v_mfma_f32_16x16x32_bf16 v[84:87], v[196:199], v[164:167], v[84:87]
	v_mfma_f32_16x16x32_bf16 v[80:83], v[204:207], v[164:167], v[80:83]
	v_mfma_f32_16x16x32_bf16 v[68:71], v[196:199], v[172:175], v[68:71]
	v_mfma_f32_16x16x32_bf16 v[64:67], v[204:207], v[172:175], v[64:67]
	s_barrier
	s_setprio 0
	s_add_i32 s23, s45, s30
	ds_read_b128 v[144:147], v215 offset:49152
	ds_read_b128 v[148:151], v215 offset:50176
	ds_read_b128 v[152:155], v215 offset:51200
	ds_read_b128 v[156:159], v215 offset:52224
	ds_read_b128 v[160:163], v215 offset:53248
	ds_read_b128 v[164:167], v215 offset:54272
	ds_read_b128 v[168:171], v215 offset:55296
	ds_read_b128 v[172:175], v215 offset:56320
	s_mov_b32 m0, s23
	s_nop 0
	global_load_lds_dwordx4 v178, s[98:99]
	s_add_i32 m0, s23, 0x2000
	s_nop 0
	global_load_lds_dwordx4 v182, s[98:99]
	s_mov_b32 m0, s37
	s_nop 0
	global_load_lds_dwordx4 v176, s[100:101]
	s_mov_b32 m0, s38
	s_nop 0
	global_load_lds_dwordx4 v180, s[100:101]
	s_add_u32 s20, s20, 0x160080
	s_addc_u32 s21, s21, 0
	s_add_i32 s22, s22, s30
	s_add_i32 s44, s44, 2
	s_add_u32 s18, s18, 0x100
	s_addc_u32 s19, s19, 0
	s_add_u32 s42, s42, 0x100
	s_addc_u32 s43, s43, 0
	s_cmpk_gt_u32 s44, 0x55
	s_waitcnt vmcnt(6)
	s_waitcnt lgkmcnt(0)
	s_setprio 1
	s_barrier
	v_mfma_f32_16x16x32_bf16 v[60:63], v[128:131], v[144:147], v[60:63]
	s_mov_b32 m0, s22
	v_mfma_f32_16x16x32_bf16 v[56:59], v[136:139], v[144:147], v[56:59]
	global_load_lds_dwordx4 v178, s[20:21]
	v_mfma_f32_16x16x32_bf16 v[44:47], v[128:131], v[152:155], v[44:47]
	s_bitset1_b32 m0, 13
	v_mfma_f32_16x16x32_bf16 v[40:43], v[136:139], v[152:155], v[40:43]
	global_load_lds_dwordx4 v182, s[20:21]
	v_mfma_f32_16x16x32_bf16 v[28:31], v[128:131], v[160:163], v[28:31]
	v_mfma_f32_16x16x32_bf16 v[24:27], v[136:139], v[160:163], v[24:27]
	v_mfma_f32_16x16x32_bf16 v[12:15], v[128:131], v[168:171], v[12:15]
	v_mfma_f32_16x16x32_bf16 v[8:11], v[136:139], v[168:171], v[8:11]
	v_mfma_f32_16x16x32_bf16 v[60:63], v[132:135], v[148:151], v[60:63]
	v_mfma_f32_16x16x32_bf16 v[56:59], v[140:143], v[148:151], v[56:59]
	v_mfma_f32_16x16x32_bf16 v[44:47], v[132:135], v[156:159], v[44:47]
	v_mfma_f32_16x16x32_bf16 v[40:43], v[140:143], v[156:159], v[40:43]
	v_mfma_f32_16x16x32_bf16 v[28:31], v[132:135], v[164:167], v[28:31]
	v_mfma_f32_16x16x32_bf16 v[24:27], v[140:143], v[164:167], v[24:27]
	v_mfma_f32_16x16x32_bf16 v[12:15], v[132:135], v[172:175], v[12:15]
	v_mfma_f32_16x16x32_bf16 v[8:11], v[140:143], v[172:175], v[8:11]
	v_mfma_f32_16x16x32_bf16 v[52:55], v[192:195], v[144:147], v[52:55]
	v_mfma_f32_16x16x32_bf16 v[48:51], v[200:203], v[144:147], v[48:51]
	v_mfma_f32_16x16x32_bf16 v[36:39], v[192:195], v[152:155], v[36:39]
	v_mfma_f32_16x16x32_bf16 v[32:35], v[200:203], v[152:155], v[32:35]
	v_mfma_f32_16x16x32_bf16 v[20:23], v[192:195], v[160:163], v[20:23]
	v_mfma_f32_16x16x32_bf16 v[16:19], v[200:203], v[160:163], v[16:19]
	v_mfma_f32_16x16x32_bf16 v[4:7], v[192:195], v[168:171], v[4:7]
	v_mfma_f32_16x16x32_bf16 v[0:3], v[200:203], v[168:171], v[0:3]
	v_mfma_f32_16x16x32_bf16 v[52:55], v[196:199], v[148:151], v[52:55]
	v_mfma_f32_16x16x32_bf16 v[48:51], v[204:207], v[148:151], v[48:51]
	v_mfma_f32_16x16x32_bf16 v[36:39], v[196:199], v[156:159], v[36:39]
	v_mfma_f32_16x16x32_bf16 v[32:35], v[204:207], v[156:159], v[32:35]
	v_mfma_f32_16x16x32_bf16 v[20:23], v[196:199], v[164:167], v[20:23]
	v_mfma_f32_16x16x32_bf16 v[16:19], v[204:207], v[164:167], v[16:19]
	v_mfma_f32_16x16x32_bf16 v[4:7], v[196:199], v[172:175], v[4:7]
	v_mfma_f32_16x16x32_bf16 v[0:3], v[204:207], v[172:175], v[0:3]
	s_barrier
; DI unsigned pack2(float lo, float hi) { f32x2 v = {lo, hi}; bf16v2 r = __builtin_convertvector(v, bf16v2); return __builtin_bit_cast(unsigned, r); }
;   DI void operator()(const f32x4 (&acc)[2][2][4][2], const Unit& u, int wr, int wc, int fr, int fq) const {
;     const int row0 = u.pm * BM + wr * 64 + fr, col0 = u.pn * BM + wc * 32 + 8 * fq;
; #pragma unroll
;     for (int ai = 0; ai < 2; ++ai) {
;       f32x4 bv[4][2][2];
; #pragma unroll
;       for (int m = 0; m < 4; ++m)
; #pragma unroll
;         for (int bj = 0; bj < 2; ++bj) {
;           const float* bp = base + (size_t)(row0 + ai * HALF + m * 16) * 2048 + col0 + bj * HALF;
;           bv[m][bj][0] = *(const f32x4*)bp; bv[m][bj][1] = *(const f32x4*)(bp + 4);
;         }
; #pragma unroll
;       for (int m = 0; m < 4; ++m) {
;         const int row = row0 + ai * HALF + m * 16;
;         const size_t off = (size_t)row * 2048 + col0;
;         float ss = 0.f;
; #pragma unroll
;         for (int bj = 0; bj < 2; ++bj) {
;           const f32x4 v0 = acc[ai][bj][m][0] + bv[m][bj][0], v1 = acc[ai][bj][m][1] + bv[m][bj][1];
;           *(f32x4*)(C + off + bj * HALF) = v0; *(f32x4*)(C + off + bj * HALF + 4) = v1;
;           if (xb) {
;             u32x4 w; w.x = pack2(v0[0], v0[1]); w.y = pack2(v0[2], v0[3]); w.z = pack2(v1[0], v1[1]); w.w = pack2(v1[2], v1[3]);
;             *(u32x4*)(xb + off + bj * HALF) = w;
;             ss += v0[0] * v0[0] + v0[1] * v0[1] + v0[2] * v0[2] + v0[3] * v0[3] + v1[0] * v1[0] + v1[1] * v1[1] + v1[2] * v1[2] + v1[3] * v1[3];
;           }
;         }
;         if (xb) {
;           ss += __shfl_xor(ss, 16); ss += __shfl_xor(ss, 32);
;           if (fq == 0) ssq[(size_t)row * 32 + u.pn * 4 + wc] = ss;
;         }
	s_setprio 0
	s_cbranch_scc0 .LBB0_961
	v_lshl_add_u32 v194, s51, 8, v211
	v_lshl_or_b32 v192, s2, 8, v213
	v_readlane_b32 s52, v243, 3
	v_ashrrev_i32_e32 v193, 31, v192
	v_readlane_b32 s66, v243, 17
	v_readlane_b32 s67, v243, 18
	v_ashrrev_i32_e32 v195, 31, v194
	v_lshlrev_b64 v[128:129], 13, v[194:195]
	v_lshl_add_u64 v[196:197], v[192:193], 2, s[66:67]
	v_lshl_add_u64 v[236:237], v[196:197], 0, v[128:129]
	global_load_dwordx4 v[220:223], v[236:237], off
	global_load_dwordx4 v[224:227], v[236:237], off offset:16
	global_load_dwordx4 v[228:231], v[236:237], off offset:512
	global_load_dwordx4 v[232:235], v[236:237], off offset:528
	v_or_b32_e32 v206, 16, v194
	v_or_b32_e32 v202, 32, v194
	v_or_b32_e32 v198, 48, v194
	v_ashrrev_i32_e32 v207, 31, v206
	v_ashrrev_i32_e32 v203, 31, v202
	v_ashrrev_i32_e32 v199, 31, v198
	v_lshlrev_b64 v[128:129], 13, v[206:207]
	v_lshlrev_b64 v[130:131], 13, v[202:203]
	v_lshlrev_b64 v[132:133], 13, v[198:199]
	v_lshl_add_u64 v[208:209], v[196:197], 0, v[128:129]
	v_lshl_add_u64 v[204:205], v[196:197], 0, v[130:131]
	v_lshl_add_u64 v[200:201], v[196:197], 0, v[132:133]
	global_load_dwordx4 v[168:171], v[208:209], off offset:16
	global_load_dwordx4 v[172:175], v[208:209], off
	global_load_dwordx4 v[160:163], v[208:209], off offset:528
	global_load_dwordx4 v[164:167], v[208:209], off offset:512
	global_load_dwordx4 v[152:155], v[204:205], off offset:16
	global_load_dwordx4 v[156:159], v[204:205], off
	global_load_dwordx4 v[144:147], v[204:205], off offset:528
	global_load_dwordx4 v[148:151], v[204:205], off offset:512
	global_load_dwordx4 v[136:139], v[200:201], off offset:16
	global_load_dwordx4 v[140:143], v[200:201], off
	global_load_dwordx4 v[128:131], v[200:201], off offset:528
	global_load_dwordx4 v[132:135], v[200:201], off offset:512
	v_and_b32_e32 v218, 64, v217
	v_xor_b32_e32 v238, 16, v217
	v_add_u32_e32 v240, 64, v218
	v_xor_b32_e32 v239, 32, v217
	v_cmp_lt_i32_e32 vcc, v238, v240
	v_lshlrev_b64 v[218:219], 11, v[194:195]
	s_lshl_b32 s18, s2, 2
	v_cndmask_b32_e32 v241, v217, v238, vcc
	v_cmp_lt_i32_e32 vcc, v239, v240
	s_ashr_i32 s19, s18, 31
	v_readlane_b32 s53, v243, 4
	v_cndmask_b32_e32 v240, v217, v239, vcc
	v_lshl_add_u64 v[238:239], v[218:219], 0, v[192:193]
	v_lshlrev_b32_e32 v218, 2, v241
	v_lshl_add_u64 v[238:239], v[238:239], 1, s[12:13]
	v_readlane_b32 s54, v243, 5
	v_readlane_b32 s55, v243, 6
	v_readlane_b32 s56, v243, 7
	v_readlane_b32 s57, v243, 8
	v_readlane_b32 s58, v243, 9
	v_readlane_b32 s59, v243, 10
	v_readlane_b32 s60, v243, 11
	v_readlane_b32 s61, v243, 12
	v_readlane_b32 s62, v243, 13
	v_readlane_b32 s63, v243, 14
	v_readlane_b32 s64, v243, 15
	v_readlane_b32 s65, v243, 16
	s_waitcnt vmcnt(0)
	v_pk_add_f32 v[126:127], v[126:127], v[222:223]
	v_pk_add_f32 v[124:125], v[124:125], v[220:221]
	v_pk_add_f32 v[116:117], v[116:117], v[228:229]
	v_pk_add_f32 v[122:123], v[122:123], v[226:227]
	v_pk_add_f32 v[120:121], v[120:121], v[224:225]
	v_pk_add_f32 v[220:221], v[112:113], v[232:233]
	global_store_dwordx4 v[236:237], v[124:127], off
	global_store_dwordx4 v[236:237], v[120:123], off offset:16
	v_cvt_pk_bf16_f32 v112, v124, v125
	v_mul_f32_e32 v125, v125, v125
	v_mul_f32_e32 v219, v117, v117
	v_pk_add_f32 v[118:119], v[118:119], v[230:231]
	v_fmac_f32_e32 v125, v124, v124
	v_fmac_f32_e32 v219, v116, v116
	v_fmac_f32_e32 v125, v126, v126
	v_fmac_f32_e32 v219, v118, v118
	v_fmac_f32_e32 v125, v127, v127
	v_fmac_f32_e32 v219, v119, v119
	v_fmac_f32_e32 v125, v120, v120
	v_fmac_f32_e32 v219, v220, v220
	v_pk_add_f32 v[222:223], v[114:115], v[234:235]
	v_fmac_f32_e32 v125, v121, v121
	v_fmac_f32_e32 v219, v221, v221
	v_fmac_f32_e32 v125, v122, v122
	v_fmac_f32_e32 v219, v222, v222
	v_fmac_f32_e32 v125, v123, v123
	v_fmac_f32_e32 v219, v223, v223
	v_cvt_pk_bf16_f32 v114, v120, v121
	v_add_f32_e32 v121, v125, v219
	v_cvt_pk_bf16_f32 v115, v122, v123
	ds_bpermute_b32 v122, v218, v121
	v_cvt_pk_bf16_f32 v113, v126, v127
	global_store_dwordx4 v[238:239], v[112:115], off
	global_store_dwordx4 v[236:237], v[116:119], off offset:512
	global_store_dwordx4 v[236:237], v[220:223], off offset:528
	v_lshlrev_b32_e32 v126, 2, v240
	v_cvt_pk_bf16_f32 v120, v116, v117
	s_waitcnt lgkmcnt(0)
	v_add_f32_e32 v112, v121, v122
	ds_bpermute_b32 v113, v126, v112
	v_cvt_pk_bf16_f32 v121, v118, v119
	v_cvt_pk_bf16_f32 v122, v220, v221
	v_cvt_pk_bf16_f32 v123, v222, v223
	global_store_dwordx4 v[238:239], v[120:123], off offset:256
	s_and_saveexec_b64 s[20:21], s[0:1]
	s_cbranch_execz .LBB0_964
	s_waitcnt lgkmcnt(0)
	v_add_f32_e32 v114, v112, v113
	v_lshlrev_b64 v[112:113], 7, v[194:195]
	v_lshl_add_u64 v[112:113], s[14:15], 0, v[112:113]
	v_lshl_add_u64 v[112:113], s[18:19], 2, v[112:113]
	s_lshl_b32 s2, s36, 2
	v_lshl_add_u64 v[112:113], v[112:113], 0, s[2:3]
	global_store_dword v[112:113], v114, off

; #define PG8_STAGE(bufoff, gbase, voff) do { _Pragma("unroll") for (int _i = 0; _i < 2; ++_i) \
;     __builtin_amdgcn_global_load_lds((const unsigned*)((const char*)(gbase) + (voff)[_i]), (LAS unsigned*)(lds + (bufoff) + ldsw + _i * 8192), 16, 0, 0); } while (0)
; #define PG8_LDA(dst, b, h) do { _Pragma("unroll") for (int m = 0; m < 4; ++m) _Pragma("unroll") for (int k = 0; k < 2; ++k) dst[m][k] = *(const LAS bf16x8*)(lds + PG8_SA(b, h) + aoff + m * 2048 + k * 1024); } while (0)
; #define PG8_LDB(dst, b, h) do { _Pragma("unroll") for (int n = 0; n < 2; ++n) _Pragma("unroll") for (int k = 0; k < 2; ++k) dst[n][k] = *(const LAS bf16x8*)(lds + PG8_SB(b, h) + boff + n * 2048 + k * 1024); } while (0)
; #define PG8_MMA(ai, bj, At, Bt) do { __builtin_amdgcn_s_setprio(1); _Pragma("unroll") for (int m = 0; m < 4; ++m) _Pragma("unroll") for (int n = 0; n < 2; ++n) _Pragma("unroll") for (int k = 0; k < 2; ++k) \
;     acc[ai][bj][m][n] = __builtin_amdgcn_mfma_f32_16x16x32_bf16(Bt[n][k], At[m][k], acc[ai][bj][m][n], 0, 0, 0); __builtin_amdgcn_s_setprio(0); } while (0)
; #define PG8_WAIT_V(n) asm volatile("s_waitcnt vmcnt(" #n ")" ::: "memory")
; #define PG8_WAIT_L(n) asm volatile("s_waitcnt lgkmcnt(" #n ")" ::: "memory")
; #define PG8_BAR __builtin_amdgcn_s_barrier()
; #define PG8_SCHED __builtin_amdgcn_sched_barrier(0)
; template <class Epi, class Sched = StaticOrder>
; DI void gemm_phase(LAS unsigned char* lds, const Gemm g, const Sched& S, const Epi& E) {
;     ...
;       PG8_LDB(B0, 0, 0); PG8_SCHED; PG8_LDA(At, 0, 0); PG8_STAGE(PG8_SA(1, 1), a1 + hstep, voffA);
;       PG8_WAIT_L(8); PG8_BAR; PG8_WAIT_L(0); PG8_MMA(0, 0, At, B0); PG8_BAR; PG8_SCHED;
;       PG8_LDB(B1, 0, 1); PG8_STAGE(PG8_SB(0, 0), b2, voffB);
;       PG8_BAR; PG8_WAIT_L(0); PG8_MMA(0, 1, At, B1); PG8_BAR;
;       PG8_LDA(At, 0, 1); PG8_STAGE(PG8_SA(0, 0), a2, voffA);
;       PG8_BAR; PG8_WAIT_L(0); PG8_MMA(1, 0, At, B0); PG8_BAR; PG8_SCHED;
;       PG8_STAGE(PG8_SB(0, 1), b2 + hstep, voffB);
;       PG8_WAIT_V(6); PG8_BAR; PG8_MMA(1, 1, At, B1); PG8_BAR;
.LBB0_1052:
	ds_read_b128 v[128:131], v203
	ds_read_b128 v[132:135], v203 offset:1024
	ds_read_b128 v[136:139], v203 offset:2048
	ds_read_b128 v[140:143], v203 offset:3072
	s_add_u32 s12, s10, 0xfff80080
	s_addc_u32 s13, s11, -1
	s_cmp_eq_u32 s52, 28
	s_cselect_b32 s65, s41, s13
	s_cselect_b32 s64, s42, s12
	s_cselect_b32 s13, s43, s49
	s_cselect_b32 s12, s44, s45
	s_add_i32 m0, s61, 0xc000
	ds_read_b128 v[144:147], v204
	ds_read_b128 v[148:151], v204 offset:1024
	ds_read_b128 v[152:155], v204 offset:2048
	ds_read_b128 v[156:159], v204 offset:3072
	ds_read_b128 v[178:181], v204 offset:4096
	ds_read_b128 v[182:185], v204 offset:5120
	ds_read_b128 v[186:189], v204 offset:6144
	ds_read_b128 v[190:193], v204 offset:7168
	global_load_lds_dwordx4 v172, s[10:11]
	s_add_i32 m0, s61, 0xe000
	s_nop 0
	global_load_lds_dwordx4 v174, s[10:11]
	ds_read_b128 v[194:197], v205
	ds_read_b128 v[212:215], v205 offset:1024
	ds_read_b128 v[216:219], v205 offset:2048
	ds_read_b128 v[220:223], v205 offset:3072
	s_waitcnt vmcnt(8)
	s_waitcnt lgkmcnt(4)
	s_setprio 1
	s_barrier
	v_mfma_f32_16x16x32_bf16 v[124:127], v[128:131], v[144:147], v[124:127]
	v_mfma_f32_16x16x32_bf16 v[120:123], v[136:139], v[144:147], v[120:123]
	v_mfma_f32_16x16x32_bf16 v[116:119], v[128:131], v[152:155], v[116:119]
	v_mfma_f32_16x16x32_bf16 v[104:107], v[136:139], v[152:155], v[104:107]
	v_mfma_f32_16x16x32_bf16 v[92:95], v[128:131], v[178:181], v[92:95]
	v_mfma_f32_16x16x32_bf16 v[88:91], v[136:139], v[178:181], v[88:91]
	v_mfma_f32_16x16x32_bf16 v[84:87], v[128:131], v[186:189], v[84:87]
	v_mfma_f32_16x16x32_bf16 v[72:75], v[136:139], v[186:189], v[72:75]
	v_mfma_f32_16x16x32_bf16 v[124:127], v[132:135], v[148:151], v[124:127]
	v_mfma_f32_16x16x32_bf16 v[120:123], v[140:143], v[148:151], v[120:123]
	v_mfma_f32_16x16x32_bf16 v[116:119], v[132:135], v[156:159], v[116:119]
	v_mfma_f32_16x16x32_bf16 v[104:107], v[140:143], v[156:159], v[104:107]
	v_mfma_f32_16x16x32_bf16 v[92:95], v[132:135], v[182:185], v[92:95]
	v_mfma_f32_16x16x32_bf16 v[88:91], v[140:143], v[182:185], v[88:91]
	v_mfma_f32_16x16x32_bf16 v[84:87], v[132:135], v[190:193], v[84:87]
	v_mfma_f32_16x16x32_bf16 v[72:75], v[140:143], v[190:193], v[72:75]
	s_waitcnt lgkmcnt(0)
	v_mfma_f32_16x16x32_bf16 v[112:115], v[194:197], v[144:147], v[112:115]
	v_mfma_f32_16x16x32_bf16 v[108:111], v[216:219], v[144:147], v[108:111]
	v_mfma_f32_16x16x32_bf16 v[100:103], v[194:197], v[152:155], v[100:103]
	v_mfma_f32_16x16x32_bf16 v[96:99], v[216:219], v[152:155], v[96:99]
	v_mfma_f32_16x16x32_bf16 v[80:83], v[194:197], v[178:181], v[80:83]
	v_mfma_f32_16x16x32_bf16 v[76:79], v[216:219], v[178:181], v[76:79]
	v_mfma_f32_16x16x32_bf16 v[68:71], v[194:197], v[186:189], v[68:71]
	v_mfma_f32_16x16x32_bf16 v[64:67], v[216:219], v[186:189], v[64:67]
	v_mfma_f32_16x16x32_bf16 v[112:115], v[212:215], v[148:151], v[112:115]
	v_mfma_f32_16x16x32_bf16 v[108:111], v[220:223], v[148:151], v[108:111]
	v_mfma_f32_16x16x32_bf16 v[100:103], v[212:215], v[156:159], v[100:103]
	v_mfma_f32_16x16x32_bf16 v[96:99], v[220:223], v[156:159], v[96:99]
	v_mfma_f32_16x16x32_bf16 v[80:83], v[212:215], v[182:185], v[80:83]
	v_mfma_f32_16x16x32_bf16 v[76:79], v[220:223], v[182:185], v[76:79]
	v_mfma_f32_16x16x32_bf16 v[68:71], v[212:215], v[190:193], v[68:71]
	v_mfma_f32_16x16x32_bf16 v[64:67], v[220:223], v[190:193], v[64:67]
	s_barrier
	s_setprio 0
	s_add_i32 s53, s80, s70
	s_add_u32 s98, s12, 0x80
	s_addc_u32 s99, s13, 0
	s_add_u32 s100, s64, 0x80
	s_addc_u32 s101, s65, 0
	ds_read_b128 v[144:147], v204 offset:16384
	ds_read_b128 v[148:151], v204 offset:17408
	ds_read_b128 v[152:155], v204 offset:18432
	ds_read_b128 v[156:159], v204 offset:19456
	ds_read_b128 v[178:181], v204 offset:20480
	ds_read_b128 v[182:185], v204 offset:21504
	ds_read_b128 v[186:189], v204 offset:22528
	ds_read_b128 v[190:193], v204 offset:23552
	s_mov_b32 m0, s53
	s_nop 0
	global_load_lds_dwordx4 v162, s[12:13]
	s_add_i32 m0, s53, 0x2000
	s_nop 0
	global_load_lds_dwordx4 v166, s[12:13]
	s_mov_b32 m0, s61
	s_nop 0
	global_load_lds_dwordx4 v160, s[64:65]
	s_mov_b32 m0, s63
	s_nop 0
	global_load_lds_dwordx4 v164, s[64:65]
	s_add_u32 s54, s12, 0x80000
	s_addc_u32 s55, s13, 0
	s_add_i32 s53, s81, s70
	s_waitcnt vmcnt(6)
	s_waitcnt lgkmcnt(0)
	s_setprio 1
	s_barrier
	v_mfma_f32_16x16x32_bf16 v[60:63], v[128:131], v[144:147], v[60:63]
	s_mov_b32 m0, s53
	v_mfma_f32_16x16x32_bf16 v[56:59], v[136:139], v[144:147], v[56:59]
	global_load_lds_dwordx4 v162, s[54:55]
	v_mfma_f32_16x16x32_bf16 v[48:51], v[128:131], v[152:155], v[48:51]
	s_bitset1_b32 m0, 13
	v_mfma_f32_16x16x32_bf16 v[40:43], v[136:139], v[152:155], v[40:43]
	global_load_lds_dwordx4 v166, s[54:55]
	v_mfma_f32_16x16x32_bf16 v[28:31], v[128:131], v[178:181], v[28:31]
	v_mfma_f32_16x16x32_bf16 v[24:27], v[136:139], v[178:181], v[24:27]
	v_mfma_f32_16x16x32_bf16 v[12:15], v[128:131], v[186:189], v[12:15]
	v_mfma_f32_16x16x32_bf16 v[8:11], v[136:139], v[186:189], v[8:11]
	v_mfma_f32_16x16x32_bf16 v[60:63], v[132:135], v[148:151], v[60:63]
	v_mfma_f32_16x16x32_bf16 v[56:59], v[140:143], v[148:151], v[56:59]
	v_mfma_f32_16x16x32_bf16 v[48:51], v[132:135], v[156:159], v[48:51]
	v_mfma_f32_16x16x32_bf16 v[40:43], v[140:143], v[156:159], v[40:43]
	v_mfma_f32_16x16x32_bf16 v[28:31], v[132:135], v[182:185], v[28:31]
	v_mfma_f32_16x16x32_bf16 v[24:27], v[140:143], v[182:185], v[24:27]
	v_mfma_f32_16x16x32_bf16 v[12:15], v[132:135], v[190:193], v[12:15]
	v_mfma_f32_16x16x32_bf16 v[8:11], v[140:143], v[190:193], v[8:11]
	v_mfma_f32_16x16x32_bf16 v[52:55], v[194:197], v[144:147], v[52:55]
	v_mfma_f32_16x16x32_bf16 v[44:47], v[216:219], v[144:147], v[44:47]
	v_mfma_f32_16x16x32_bf16 v[36:39], v[194:197], v[152:155], v[36:39]
	v_mfma_f32_16x16x32_bf16 v[32:35], v[216:219], v[152:155], v[32:35]
	v_mfma_f32_16x16x32_bf16 v[20:23], v[194:197], v[178:181], v[20:23]
	v_mfma_f32_16x16x32_bf16 v[16:19], v[216:219], v[178:181], v[16:19]
	v_mfma_f32_16x16x32_bf16 v[4:7], v[194:197], v[186:189], v[4:7]
	v_mfma_f32_16x16x32_bf16 v[0:3], v[216:219], v[186:189], v[0:3]
	v_mfma_f32_16x16x32_bf16 v[52:55], v[212:215], v[148:151], v[52:55]
	v_mfma_f32_16x16x32_bf16 v[44:47], v[220:223], v[148:151], v[44:47]
	v_mfma_f32_16x16x32_bf16 v[36:39], v[212:215], v[156:159], v[36:39]
	v_mfma_f32_16x16x32_bf16 v[32:35], v[220:223], v[156:159], v[32:35]
	v_mfma_f32_16x16x32_bf16 v[20:23], v[212:215], v[182:185], v[20:23]
	v_mfma_f32_16x16x32_bf16 v[16:19], v[220:223], v[182:185], v[16:19]
	v_mfma_f32_16x16x32_bf16 v[4:7], v[212:215], v[190:193], v[4:7]
	v_mfma_f32_16x16x32_bf16 v[0:3], v[220:223], v[190:193], v[0:3]
	s_barrier
; #define PG8_STAGE(bufoff, gbase, voff) do { _Pragma("unroll") for (int _i = 0; _i < 2; ++_i) \
;     __builtin_amdgcn_global_load_lds((const unsigned*)((const char*)(gbase) + (voff)[_i]), (LAS unsigned*)(lds + (bufoff) + ldsw + _i * 8192), 16, 0, 0); } while (0)
; #define PG8_LDA(dst, b, h) do { _Pragma("unroll") for (int m = 0; m < 4; ++m) _Pragma("unroll") for (int k = 0; k < 2; ++k) dst[m][k] = *(const LAS bf16x8*)(lds + PG8_SA(b, h) + aoff + m * 2048 + k * 1024); } while (0)
; #define PG8_LDB(dst, b, h) do { _Pragma("unroll") for (int n = 0; n < 2; ++n) _Pragma("unroll") for (int k = 0; k < 2; ++k) dst[n][k] = *(const LAS bf16x8*)(lds + PG8_SB(b, h) + boff + n * 2048 + k * 1024); } while (0)
; #define PG8_MMA(ai, bj, At, Bt) do { __builtin_amdgcn_s_setprio(1); _Pragma("unroll") for (int m = 0; m < 4; ++m) _Pragma("unroll") for (int n = 0; n < 2; ++n) _Pragma("unroll") for (int k = 0; k < 2; ++k) \
;     acc[ai][bj][m][n] = __builtin_amdgcn_mfma_f32_16x16x32_bf16(Bt[n][k], At[m][k], acc[ai][bj][m][n], 0, 0, 0); __builtin_amdgcn_s_setprio(0); } while (0)
; #define PG8_WAIT_V(n) asm volatile("s_waitcnt vmcnt(" #n ")" ::: "memory")
; #define PG8_WAIT_L(n) asm volatile("s_waitcnt lgkmcnt(" #n ")" ::: "memory")
; #define PG8_BAR __builtin_amdgcn_s_barrier()
; #define PG8_SCHED __builtin_amdgcn_sched_barrier(0)
; template <class Epi, class Sched = StaticOrder>
; DI void gemm_phase(LAS unsigned char* lds, const Gemm g, const Sched& S, const Epi& E) {
;     ...
;       PG8_LDB(B0, 1, 0); PG8_SCHED; PG8_LDA(At, 1, 0); PG8_STAGE(PG8_SA(0, 1), a2 + hstep, voffA);
;       PG8_WAIT_L(8); PG8_BAR; PG8_WAIT_L(0); PG8_MMA(0, 0, At, B0); PG8_BAR; PG8_SCHED;
;       PG8_LDB(B1, 1, 1); PG8_STAGE(PG8_SB(1, 0), b3, voffB);
;       PG8_BAR; PG8_WAIT_L(0); PG8_MMA(0, 1, At, B1); PG8_BAR;
;       PG8_LDA(At, 1, 1); PG8_STAGE(PG8_SA(1, 0), a3, voffA);
;       PG8_BAR; PG8_WAIT_L(0); PG8_MMA(1, 0, At, B0); PG8_BAR; PG8_SCHED;
;       PG8_STAGE(PG8_SB(1, 1), b3 + hstep, voffB);
;       PG8_WAIT_V(6); PG8_BAR; PG8_MMA(1, 1, At, B1); PG8_BAR;
	s_setprio 0
	s_add_i32 s53, 0, 0x18000
	v_add_u32_e32 v140, s53, v199
	ds_read_b128 v[128:131], v140
	ds_read_b128 v[132:135], v140 offset:1024
	ds_read_b128 v[136:139], v140 offset:2048
	ds_read_b128 v[140:143], v140 offset:3072
	s_add_u32 s54, s64, 0x80000
	s_addc_u32 s55, s65, 0
	s_mov_b32 m0, s71
	ds_read_b128 v[144:147], v204 offset:32768
	ds_read_b128 v[148:151], v204 offset:33792
	ds_read_b128 v[152:155], v204 offset:34816
	ds_read_b128 v[156:159], v204 offset:35840
	ds_read_b128 v[178:181], v204 offset:36864
	ds_read_b128 v[182:185], v204 offset:37888
	ds_read_b128 v[186:189], v204 offset:38912
	ds_read_b128 v[190:193], v204 offset:39936
	global_load_lds_dwordx4 v160, s[54:55]
	s_mov_b32 m0, s72
	s_nop 0
	global_load_lds_dwordx4 v164, s[54:55]
	s_add_i32 s54, 0, 0x1c000
	v_add_u32_e32 v168, s54, v199
	ds_read_b128 v[194:197], v168
	ds_read_b128 v[212:215], v168 offset:1024
	ds_read_b128 v[216:219], v168 offset:2048
	ds_read_b128 v[220:223], v168 offset:3072
	s_waitcnt vmcnt(8)
	s_waitcnt lgkmcnt(4)
	s_setprio 1
	s_barrier
	v_mfma_f32_16x16x32_bf16 v[124:127], v[128:131], v[144:147], v[124:127]
	v_mfma_f32_16x16x32_bf16 v[120:123], v[136:139], v[144:147], v[120:123]
	v_mfma_f32_16x16x32_bf16 v[116:119], v[128:131], v[152:155], v[116:119]
	v_mfma_f32_16x16x32_bf16 v[104:107], v[136:139], v[152:155], v[104:107]
	v_mfma_f32_16x16x32_bf16 v[92:95], v[128:131], v[178:181], v[92:95]
	v_mfma_f32_16x16x32_bf16 v[88:91], v[136:139], v[178:181], v[88:91]
	v_mfma_f32_16x16x32_bf16 v[84:87], v[128:131], v[186:189], v[84:87]
	v_mfma_f32_16x16x32_bf16 v[72:75], v[136:139], v[186:189], v[72:75]
	v_mfma_f32_16x16x32_bf16 v[124:127], v[132:135], v[148:151], v[124:127]
	v_mfma_f32_16x16x32_bf16 v[120:123], v[140:143], v[148:151], v[120:123]
	v_mfma_f32_16x16x32_bf16 v[116:119], v[132:135], v[156:159], v[116:119]
	v_mfma_f32_16x16x32_bf16 v[104:107], v[140:143], v[156:159], v[104:107]
	v_mfma_f32_16x16x32_bf16 v[92:95], v[132:135], v[182:185], v[92:95]
	v_mfma_f32_16x16x32_bf16 v[88:91], v[140:143], v[182:185], v[88:91]
	v_mfma_f32_16x16x32_bf16 v[84:87], v[132:135], v[190:193], v[84:87]
	v_mfma_f32_16x16x32_bf16 v[72:75], v[140:143], v[190:193], v[72:75]
	s_waitcnt lgkmcnt(0)
	v_mfma_f32_16x16x32_bf16 v[112:115], v[194:197], v[144:147], v[112:115]
	v_mfma_f32_16x16x32_bf16 v[108:111], v[216:219], v[144:147], v[108:111]
	v_mfma_f32_16x16x32_bf16 v[100:103], v[194:197], v[152:155], v[100:103]
	v_mfma_f32_16x16x32_bf16 v[96:99], v[216:219], v[152:155], v[96:99]
	v_mfma_f32_16x16x32_bf16 v[80:83], v[194:197], v[178:181], v[80:83]
	v_mfma_f32_16x16x32_bf16 v[76:79], v[216:219], v[178:181], v[76:79]
	v_mfma_f32_16x16x32_bf16 v[68:71], v[194:197], v[186:189], v[68:71]
	v_mfma_f32_16x16x32_bf16 v[64:67], v[216:219], v[186:189], v[64:67]
	v_mfma_f32_16x16x32_bf16 v[112:115], v[212:215], v[148:151], v[112:115]
	v_mfma_f32_16x16x32_bf16 v[108:111], v[220:223], v[148:151], v[108:111]
	v_mfma_f32_16x16x32_bf16 v[100:103], v[212:215], v[156:159], v[100:103]
	v_mfma_f32_16x16x32_bf16 v[96:99], v[220:223], v[156:159], v[96:99]
	v_mfma_f32_16x16x32_bf16 v[80:83], v[212:215], v[182:185], v[80:83]
	v_mfma_f32_16x16x32_bf16 v[76:79], v[220:223], v[182:185], v[76:79]
	v_mfma_f32_16x16x32_bf16 v[68:71], v[212:215], v[190:193], v[68:71]
	v_mfma_f32_16x16x32_bf16 v[64:67], v[220:223], v[190:193], v[64:67]
	s_barrier
	s_setprio 0
	s_add_i32 s53, s53, s70
	ds_read_b128 v[144:147], v204 offset:49152
	ds_read_b128 v[148:151], v204 offset:50176
	ds_read_b128 v[152:155], v204 offset:51200
	ds_read_b128 v[156:159], v204 offset:52224
	ds_read_b128 v[178:181], v204 offset:53248
	ds_read_b128 v[182:185], v204 offset:54272
	ds_read_b128 v[186:189], v204 offset:55296
	ds_read_b128 v[190:193], v204 offset:56320
	s_mov_b32 m0, s53
	s_nop 0
	global_load_lds_dwordx4 v162, s[98:99]
	s_add_i32 m0, s53, 0x2000
	s_nop 0
	global_load_lds_dwordx4 v166, s[98:99]
	s_mov_b32 m0, s76
	s_nop 0
	global_load_lds_dwordx4 v160, s[100:101]
	s_mov_b32 m0, s77
	s_nop 0
	global_load_lds_dwordx4 v164, s[100:101]
	s_add_u32 s12, s12, 0x80080
	s_addc_u32 s13, s13, 0
	s_add_i32 s53, s54, s70
	s_add_i32 s52, s52, 2
	s_add_u32 s10, s10, 0x100
	s_addc_u32 s11, s11, 0
	s_add_u32 s45, s45, 0x100
	s_addc_u32 s49, s49, 0
	s_cmp_gt_u32 s52, 29
	s_waitcnt vmcnt(6)
	s_waitcnt lgkmcnt(0)
	s_setprio 1
	s_barrier
	v_mfma_f32_16x16x32_bf16 v[60:63], v[128:131], v[144:147], v[60:63]
	s_mov_b32 m0, s53
	v_mfma_f32_16x16x32_bf16 v[56:59], v[136:139], v[144:147], v[56:59]
	global_load_lds_dwordx4 v162, s[12:13]
	v_mfma_f32_16x16x32_bf16 v[48:51], v[128:131], v[152:155], v[48:51]
	s_bitset1_b32 m0, 13
	v_mfma_f32_16x16x32_bf16 v[40:43], v[136:139], v[152:155], v[40:43]
	global_load_lds_dwordx4 v166, s[12:13]
	v_mfma_f32_16x16x32_bf16 v[28:31], v[128:131], v[178:181], v[28:31]
	v_mfma_f32_16x16x32_bf16 v[24:27], v[136:139], v[178:181], v[24:27]
	v_mfma_f32_16x16x32_bf16 v[12:15], v[128:131], v[186:189], v[12:15]
	v_mfma_f32_16x16x32_bf16 v[8:11], v[136:139], v[186:189], v[8:11]
	v_mfma_f32_16x16x32_bf16 v[60:63], v[132:135], v[148:151], v[60:63]
	v_mfma_f32_16x16x32_bf16 v[56:59], v[140:143], v[148:151], v[56:59]
	v_mfma_f32_16x16x32_bf16 v[48:51], v[132:135], v[156:159], v[48:51]
	v_mfma_f32_16x16x32_bf16 v[40:43], v[140:143], v[156:159], v[40:43]
	v_mfma_f32_16x16x32_bf16 v[28:31], v[132:135], v[182:185], v[28:31]
	v_mfma_f32_16x16x32_bf16 v[24:27], v[140:143], v[182:185], v[24:27]
	v_mfma_f32_16x16x32_bf16 v[12:15], v[132:135], v[190:193], v[12:15]
	v_mfma_f32_16x16x32_bf16 v[8:11], v[140:143], v[190:193], v[8:11]
	v_mfma_f32_16x16x32_bf16 v[52:55], v[194:197], v[144:147], v[52:55]
	v_mfma_f32_16x16x32_bf16 v[44:47], v[216:219], v[144:147], v[44:47]
	v_mfma_f32_16x16x32_bf16 v[36:39], v[194:197], v[152:155], v[36:39]
	v_mfma_f32_16x16x32_bf16 v[32:35], v[216:219], v[152:155], v[32:35]
	v_mfma_f32_16x16x32_bf16 v[20:23], v[194:197], v[178:181], v[20:23]
	v_mfma_f32_16x16x32_bf16 v[16:19], v[216:219], v[178:181], v[16:19]
	v_mfma_f32_16x16x32_bf16 v[4:7], v[194:197], v[186:189], v[4:7]
	v_mfma_f32_16x16x32_bf16 v[0:3], v[216:219], v[186:189], v[0:3]
	v_mfma_f32_16x16x32_bf16 v[52:55], v[212:215], v[148:151], v[52:55]
	v_mfma_f32_16x16x32_bf16 v[44:47], v[220:223], v[148:151], v[44:47]
	v_mfma_f32_16x16x32_bf16 v[36:39], v[212:215], v[156:159], v[36:39]
	v_mfma_f32_16x16x32_bf16 v[32:35], v[220:223], v[156:159], v[32:35]
	v_mfma_f32_16x16x32_bf16 v[20:23], v[212:215], v[182:185], v[20:23]
	v_mfma_f32_16x16x32_bf16 v[16:19], v[220:223], v[182:185], v[16:19]
	v_mfma_f32_16x16x32_bf16 v[4:7], v[212:215], v[190:193], v[4:7]
	v_mfma_f32_16x16x32_bf16 v[0:3], v[220:223], v[190:193], v[0:3]
	s_barrier
; DI float row_rstd(const float* ssq, int row, int fq) {
;   const f32x4 a = *(const f32x4*)(ssq + (size_t)row * 32 + fq * 8), b = *(const f32x4*)(ssq + (size_t)row * 32 + fq * 8 + 4);
;   float sm = ((a[0] + a[1]) + (a[2] + a[3])) + ((b[0] + b[1]) + (b[2] + b[3]));
;   sm += __shfl_xor(sm, 16); sm += __shfl_xor(sm, 32);
;   return rsqrtf(sm * (1.0f / 2048.f) + 1e-6f);
;   DI void operator()(const f32x4 (&acc)[2][2][4][2], const Unit& u, int wr, int wc, int fr, int fq) const {
;     ...
;     const int col = u.pn * 128 + wc * 32 + 8 * fq;
;     float w0[8], w1[8], w2[8];
; #pragma unroll
;     for (int e = 0; e < 8; ++e) { w0[e] = cw[col + e]; w1[e] = cw[2048 + col + e]; w2[e] = cw[4096 + col + e]; }
; #pragma unroll
;     for (int ai = 0; ai < 2; ++ai) {
;       const int row0 = u.pm * BM + ai * HALF + wr * 64, span = row0 >> 6;
;       float rsv[4];
; #pragma unroll
;       for (int m = 0; m < 4; ++m) rsv[m] = row_rstd(ssq, row0 + 16 * m + fr, fq);
	s_setprio 0
	s_cbranch_scc0 .LBB0_1052
	s_cmp_lt_i32 s62, 16
	s_mov_b64 s[10:11], -1
	s_cbranch_scc0 .LBB0_1067
	s_lshl_b32 s41, s60, 8
	s_add_i32 s41, s41, s75
	v_or_b32_e32 v186, s41, v177
	v_ashrrev_i32_e32 v187, 31, v186
	v_lshlrev_b64 v[128:129], 7, v[186:187]
	v_or_b32_e32 v180, 16, v186
	v_lshl_add_u64 v[128:129], v[170:171], 0, v[128:129]
	v_ashrrev_i32_e32 v181, 31, v180
	global_load_dwordx4 v[152:155], v[128:129], off
	global_load_dwordx4 v[156:159], v[128:129], off offset:16
	v_lshlrev_b64 v[128:129], 7, v[180:181]
	v_lshl_add_u64 v[128:129], v[170:171], 0, v[128:129]
	global_load_dwordx4 v[188:191], v[128:129], off
	global_load_dwordx4 v[192:195], v[128:129], off offset:16
	v_or_b32_e32 v184, 32, v186
	v_ashrrev_i32_e32 v185, 31, v184
	v_lshlrev_b64 v[128:129], 7, v[184:185]
	v_or_b32_e32 v182, 48, v186
	v_lshl_add_u64 v[128:129], v[170:171], 0, v[128:129]
	v_ashrrev_i32_e32 v183, 31, v182
	global_load_dwordx4 v[212:215], v[128:129], off
	global_load_dwordx4 v[216:219], v[128:129], off offset:16
	v_lshlrev_b64 v[128:129], 7, v[182:183]
	v_lshl_add_u64 v[128:129], v[170:171], 0, v[128:129]
	global_load_dwordx4 v[220:223], v[128:129], off
	global_load_dwordx4 v[224:227], v[128:129], off offset:16
	v_and_b32_e32 v129, 64, v206
	v_lshl_or_b32 v178, s62, 7, v200
	v_xor_b32_e32 v128, 16, v206
	v_add_u32_e32 v129, 64, v129
	v_readlane_b32 s44, v243, 3
	v_xor_b32_e32 v130, 32, v206
	v_ashrrev_i32_e32 v179, 31, v178
	v_readlane_b32 s45, v243, 4
	v_cmp_lt_i32_e32 vcc, v128, v129
	s_movk_i32 s10, 0x2000
	v_lshl_add_u64 v[144:145], v[178:179], 2, s[44:45]
	v_cndmask_b32_e32 v134, v206, v128, vcc
	v_cmp_lt_i32_e32 vcc, v130, v129
	v_lshl_add_u64 v[132:133], v[144:145], 0, s[26:27]
	v_lshl_add_u64 v[136:137], v[144:145], 0, s[28:29]
	v_cndmask_b32_e32 v135, v206, v130, vcc
	v_add_co_u32_e32 v146, vcc, s10, v144
	global_load_dwordx4 v[128:131], v[144:145], off offset:16
	global_load_dwordx4 v[140:143], v[144:145], off
	v_addc_co_u32_e32 v147, vcc, 0, v145, vcc
	v_add_co_u32_e32 v148, vcc, s74, v144
	v_lshlrev_b32_e32 v196, 2, v134
	s_nop 0
	v_addc_co_u32_e32 v149, vcc, 0, v145, vcc
	v_lshlrev_b32_e32 v207, 2, v135
	global_load_dwordx4 v[132:135], v[132:133], off offset:16
	s_nop 0
	global_load_dwordx4 v[136:139], v[136:137], off offset:16
	s_nop 0
	global_load_dwordx4 v[144:147], v[146:147], off
	s_nop 0
	global_load_dwordx4 v[148:151], v[148:149], off
	v_mov_b32_e32 v197, 0
	v_mov_b32_e32 v211, 0
	v_readlane_b32 s46, v243, 5
	v_readlane_b32 s47, v243, 6
	v_readlane_b32 s48, v243, 7
	v_readlane_b32 s49, v243, 8
	v_readlane_b32 s50, v243, 9
	v_readlane_b32 s51, v243, 10
	v_readlane_b32 s52, v243, 11
	v_readlane_b32 s53, v243, 12
	v_readlane_b32 s54, v243, 13
	v_readlane_b32 s55, v243, 14
	v_readlane_b32 s56, v243, 15
	v_readlane_b32 s57, v243, 16
	v_readlane_b32 s58, v243, 17
	v_readlane_b32 s59, v243, 18
	s_waitcnt vmcnt(0)
	v_mov_b32_e32 v208, v152
	v_mov_b32_e32 v209, v156
	v_mov_b32_e32 v156, v153
	v_mov_b32_e32 v152, v154
	v_mov_b32_e32 v153, v158
	v_mov_b32_e32 v158, v155
	v_pk_add_f32 v[154:155], v[208:209], v[156:157]
	v_pk_add_f32 v[152:153], v[152:153], v[158:159]
	v_mov_b32_e32 v156, v188
	v_mov_b32_e32 v157, v192
	v_mov_b32_e32 v192, v189
	v_mov_b32_e32 v158, v190
	v_mov_b32_e32 v159, v194
	v_mov_b32_e32 v194, v191
	v_pk_add_f32 v[152:153], v[154:155], v[152:153]
	v_pk_add_f32 v[154:155], v[156:157], v[192:193]
	v_pk_add_f32 v[156:157], v[158:159], v[194:195]
	v_mov_b32_e32 v188, v212
	v_pk_add_f32 v[154:155], v[154:155], v[156:157]
	v_mov_b32_e32 v157, v152
	v_mov_b32_e32 v156, v154
	v_mov_b32_e32 v152, v155
	v_pk_add_f32 v[152:153], v[156:157], v[152:153]
	ds_bpermute_b32 v155, v196, v153
	ds_bpermute_b32 v154, v196, v152
	v_mov_b32_e32 v189, v216
	v_mov_b32_e32 v216, v213
	v_mov_b32_e32 v190, v214
	v_mov_b32_e32 v191, v218
	s_waitcnt lgkmcnt(0)
	v_pk_add_f32 v[152:153], v[152:153], v[154:155]
	ds_bpermute_b32 v155, v207, v153
	ds_bpermute_b32 v154, v207, v152
	v_mov_b32_e32 v218, v215
	v_mov_b32_e32 v208, v220
	v_mov_b32_e32 v209, v224
	v_mov_b32_e32 v224, v221
	v_mov_b32_e32 v212, v222
	v_mov_b32_e32 v213, v226
	v_mov_b32_e32 v226, v223
	v_pk_add_f32 v[156:157], v[188:189], v[216:217]
	v_pk_add_f32 v[158:159], v[190:191], v[218:219]
	v_pk_add_f32 v[188:189], v[208:209], v[224:225]
	v_pk_add_f32 v[190:191], v[212:213], v[226:227]
	s_waitcnt lgkmcnt(0)
; DI unsigned pack2(float lo, float hi) { f32x2 v = {lo, hi}; bf16v2 r = __builtin_convertvector(v, bf16v2); return __builtin_bit_cast(unsigned, r); }
; DI float dpp_ror1(float v) { return __int_as_float(__builtin_amdgcn_update_dpp(0, __float_as_int(v), 0x121, 0xf, 0xf, false)); }
; DI float dpp_ror2(float v) { return __int_as_float(__builtin_amdgcn_update_dpp(0, __float_as_int(v), 0x122, 0xf, 0xf, false)); }
;   DI void operator()(const f32x4 (&acc)[2][2][4][2], const Unit& u, int wr, int wc, int fr, int fq) const {
;     ...
;       for (int m = 0; m < 4; ++m) {
;         float g[8], a[8];
;         const float rs1 = rsv[m], rs2 = rs1 * rs1;
; #pragma unroll
;         for (int e = 0; e < 4; ++e) { g[e] = acc[ai][0][m][0][e] * acc[ai][1][m][0][e] * rs2; g[4 + e] = acc[ai][0][m][1][e] * acc[ai][1][m][1][e] * rs2; }
; #pragma unroll
;         for (int e = 0; e < 8; ++e) {
;           const float x1 = dpp_ror1(g[e]), x2 = dpp_ror2(g[e]);
;           const float pr1 = (fr == 0) ? p1[e] : x1, pr2 = (fr < 2) ? p2[e] : x2;
;           a[e] = w2[e] * g[e] + w1[e] * pr1 + w0[e] * pr2;
;           p1[e] = x1; p2[e] = x2;
;         }
;         if (m == 0 && fr < 2) {
;           float* hc = headC + (size_t)(span * 2 + fr) * 2048 + col;
;           *(f32x4*)hc = (f32x4){a[0], a[1], a[2], a[3]}; *(f32x4*)(hc + 4) = (f32x4){a[4], a[5], a[6], a[7]};
;         } else {
;           u32x4 w; w.x = pack2(a[0] * rs1, a[1] * rs1); w.y = pack2(a[2] * rs1, a[3] * rs1); w.z = pack2(a[4] * rs1, a[5] * rs1); w.w = pack2(a[6] * rs1, a[7] * rs1);
;           *(u32x4*)(C + (size_t)(row0 + 16 * m + fr) * 2048 + col) = w;
;         }
	v_pk_add_f32 v[152:153], v[152:153], v[154:155]
	v_pk_add_f32 v[156:157], v[156:157], v[158:159]
	v_pk_add_f32 v[158:159], v[188:189], v[190:191]
	v_pk_fma_f32 v[188:189], v[152:153], s[30:31], v[176:177] op_sel_hi:[1,0,0]
	v_mov_b32_e32 v153, v156
	v_mul_f32_e32 v152, 0x4b800000, v189
	v_cmp_gt_f32_e64 s[10:11], s84, v189
	v_mov_b32_e32 v156, v159
	v_mov_b32_e32 v194, v123
	v_cndmask_b32_e64 v152, v189, v152, s[10:11]
	v_rsq_f32_e32 v168, v152
	v_mov_b32_e32 v152, v158
	v_pk_add_f32 v[152:153], v[152:153], v[156:157]
	ds_bpermute_b32 v155, v196, v153
	ds_bpermute_b32 v154, v196, v152
	v_mul_f32_e32 v156, 0x45800000, v168
	v_cndmask_b32_e64 v195, v168, v156, s[10:11]
	v_mov_b32_e32 v217, 0
	v_mul_f32_e32 v156, v125, v113
	s_waitcnt lgkmcnt(0)
	v_pk_add_f32 v[190:191], v[152:153], v[154:155]
	v_mov_b32_e32 v152, v111
	v_mov_b32_e32 v153, v195
	v_mul_f32_e32 v154, v124, v112
	v_pk_mul_f32 v[152:153], v[194:195], v[152:153]
	v_mul_f32_e32 v155, v120, v108
	v_mul_f32_e32 v154, v154, v153
	v_pk_mul_f32 v[222:223], v[152:153], v[152:153] op_sel:[0,1] op_sel_hi:[1,0]
	v_mov_b32_e32 v213, 0
	v_mov_b32_dpp v217, v154 row_ror:1 row_mask:0xf bank_mask:0xf
	v_cndmask_b32_e64 v152, v217, 0, s[0:1]
	v_mul_f32_e32 v157, v121, v109
	v_mul_f32_e32 v158, v126, v114
	v_mul_f32_e32 v159, v122, v110
	v_mul_f32_e32 v168, v127, v115
	v_mul_f32_e32 v194, v155, v153
	v_mul_f32_e32 v155, v156, v153
	v_mov_b32_dpp v213, v154 row_ror:2 row_mask:0xf bank_mask:0xf
	v_mov_b32_e32 v221, 0
	v_mul_f32_e32 v152, v144, v152
	v_mul_f32_e32 v208, v157, v153
	v_mul_f32_e32 v156, v158, v153
	v_mul_f32_e32 v159, v159, v153
	v_mul_f32_e32 v157, v168, v153
	v_mov_b32_dpp v221, v155 row_ror:1 row_mask:0xf bank_mask:0xf
	v_cndmask_b32_e64 v153, v213, 0, s[8:9]
	v_fmac_f32_e32 v152, v148, v154
	v_mov_b32_e32 v219, 0
	v_fmac_f32_e32 v152, v140, v153
	v_cndmask_b32_e64 v153, v221, 0, s[0:1]
	v_mov_b32_dpp v219, v155 row_ror:2 row_mask:0xf bank_mask:0xf
	v_mul_f32_e32 v153, v145, v153
	v_mov_b32_e32 v216, 0
	v_cndmask_b32_e64 v154, v219, 0, s[8:9]
	v_fmac_f32_e32 v153, v149, v155
	v_mov_b32_dpp v216, v156 row_ror:1 row_mask:0xf bank_mask:0xf
	v_fmac_f32_e32 v153, v141, v154
	v_mov_b32_e32 v212, 0
	v_cndmask_b32_e64 v154, v216, 0, s[0:1]
	v_mov_b32_e32 v220, 0
	v_mov_b32_dpp v212, v156 row_ror:2 row_mask:0xf bank_mask:0xf
	v_mul_f32_e32 v154, v146, v154
	v_mov_b32_dpp v220, v157 row_ror:1 row_mask:0xf bank_mask:0xf
	v_cndmask_b32_e64 v155, v212, 0, s[8:9]
	v_fmac_f32_e32 v154, v150, v156
	v_mov_b32_e32 v218, 0
	v_fmac_f32_e32 v154, v142, v155
	v_cndmask_b32_e64 v155, v220, 0, s[0:1]
	v_mov_b32_dpp v218, v157 row_ror:2 row_mask:0xf bank_mask:0xf
	v_mul_f32_e32 v155, v147, v155
	v_cndmask_b32_e64 v156, v218, 0, s[8:9]
	v_fmac_f32_e32 v155, v151, v157
	v_mov_b32_dpp v197, v194 row_ror:1 row_mask:0xf bank_mask:0xf
	v_fmac_f32_e32 v155, v143, v156
	v_mov_b32_e32 v189, 0
	v_cndmask_b32_e64 v156, v197, 0, s[0:1]
	v_mov_b32_e32 v214, 0
	v_mov_b32_dpp v189, v194 row_ror:2 row_mask:0xf bank_mask:0xf
	v_mul_f32_e32 v156, v132, v156
	v_mov_b32_dpp v214, v208 row_ror:1 row_mask:0xf bank_mask:0xf
	v_cndmask_b32_e64 v157, v189, 0, s[8:9]
	v_fmac_f32_e32 v156, v136, v194
	v_fmac_f32_e32 v156, v128, v157
	v_cndmask_b32_e64 v157, v214, 0, s[0:1]
	v_mov_b32_e32 v209, 0
	v_mul_f32_e32 v157, v133, v157
	v_fmac_f32_e32 v157, v137, v208
	v_mov_b32_dpp v209, v208 row_ror:2 row_mask:0xf bank_mask:0xf
	v_mov_b32_e32 v208, 0
	v_cndmask_b32_e64 v158, v209, 0, s[8:9]
	v_fmac_f32_e32 v157, v129, v158
	v_mov_b32_dpp v208, v159 row_ror:1 row_mask:0xf bank_mask:0xf
	v_mov_b32_e32 v194, 0
	v_cndmask_b32_e64 v158, v208, 0, s[0:1]
	ds_bpermute_b32 v193, v207, v191
	ds_bpermute_b32 v192, v207, v190
	v_mov_b32_dpp v194, v159 row_ror:2 row_mask:0xf bank_mask:0xf
	v_mov_b32_e32 v215, 0
	v_mul_f32_e32 v158, v134, v158
	v_cndmask_b32_e64 v168, v194, 0, s[8:9]
	v_mov_b32_dpp v215, v222 row_ror:1 row_mask:0xf bank_mask:0xf
	v_fmac_f32_e32 v158, v138, v159
	v_mov_b32_dpp v211, v222 row_ror:2 row_mask:0xf bank_mask:0xf
	v_fmac_f32_e32 v158, v130, v168
	v_cndmask_b32_e64 v168, v215, 0, s[0:1]
	v_mul_f32_e32 v159, v139, v222
	v_cndmask_b32_e64 v223, v211, 0, s[8:9]
	v_fmac_f32_e32 v159, v135, v168
	v_cmp_gt_f32_e32 vcc, s84, v188
	v_fmac_f32_e32 v159, v131, v223
	s_and_saveexec_b64 s[10:11], s[4:5]
	s_xor_b64 s[10:11], exec, s[10:11]
	s_cbranch_execz .LBB0_1056
	v_mul_f32_e32 v152, v195, v152
	v_mul_f32_e32 v153, v195, v153
	v_cvt_pk_bf16_f32 v152, v152, v153
	v_mul_f32_e32 v153, v195, v154
	v_mul_f32_e32 v154, v195, v155
	v_cvt_pk_bf16_f32 v153, v153, v154
	v_mul_f32_e32 v154, v195, v156
	v_mul_f32_e32 v155, v195, v157
	v_cvt_pk_bf16_f32 v154, v154, v155
	v_mul_f32_e32 v155, v195, v158
	v_mul_f32_e32 v156, v195, v159
	v_cvt_pk_bf16_f32 v155, v155, v156
	v_lshlrev_b64 v[156:157], 12, v[186:187]
	v_lshl_add_u64 v[156:157], s[18:19], 0, v[156:157]
	v_lshl_add_u64 v[156:157], v[178:179], 1, v[156:157]
	global_store_dwordx4 v[156:157], v[152:155], off

; #define PG8_STAGE(bufoff, gbase, voff) do { _Pragma("unroll") for (int _i = 0; _i < 2; ++_i) \
;     __builtin_amdgcn_global_load_lds((const unsigned*)((const char*)(gbase) + (voff)[_i]), (LAS unsigned*)(lds + (bufoff) + ldsw + _i * 8192), 16, 0, 0); } while (0)
; #define PG8_LDA(dst, b, h) do { _Pragma("unroll") for (int m = 0; m < 4; ++m) _Pragma("unroll") for (int k = 0; k < 2; ++k) dst[m][k] = *(const LAS bf16x8*)(lds + PG8_SA(b, h) + aoff + m * 2048 + k * 1024); } while (0)
; #define PG8_LDB(dst, b, h) do { _Pragma("unroll") for (int n = 0; n < 2; ++n) _Pragma("unroll") for (int k = 0; k < 2; ++k) dst[n][k] = *(const LAS bf16x8*)(lds + PG8_SB(b, h) + boff + n * 2048 + k * 1024); } while (0)
; #define PG8_MMA(ai, bj, At, Bt) do { __builtin_amdgcn_s_setprio(1); _Pragma("unroll") for (int m = 0; m < 4; ++m) _Pragma("unroll") for (int n = 0; n < 2; ++n) _Pragma("unroll") for (int k = 0; k < 2; ++k) \
;     acc[ai][bj][m][n] = __builtin_amdgcn_mfma_f32_16x16x32_bf16(Bt[n][k], At[m][k], acc[ai][bj][m][n], 0, 0, 0); __builtin_amdgcn_s_setprio(0); } while (0)
; #define PG8_WAIT_V(n) asm volatile("s_waitcnt vmcnt(" #n ")" ::: "memory")
; #define PG8_WAIT_L(n) asm volatile("s_waitcnt lgkmcnt(" #n ")" ::: "memory")
; #define PG8_BAR __builtin_amdgcn_s_barrier()
; #define PG8_SCHED __builtin_amdgcn_sched_barrier(0)
; template <class Epi, class Sched = StaticOrder>
; DI void gemm_phase(LAS unsigned char* lds, const Gemm g, const Sched& S, const Epi& E) {
;     ...
;       PG8_LDB(B0, 0, 0); PG8_SCHED; PG8_LDA(At, 0, 0); PG8_STAGE(PG8_SA(1, 1), a1 + hstep, voffA);
;       PG8_WAIT_L(8); PG8_BAR; PG8_WAIT_L(0); PG8_MMA(0, 0, At, B0); PG8_BAR; PG8_SCHED;
;       PG8_LDB(B1, 0, 1); PG8_STAGE(PG8_SB(0, 0), b2, voffB);
;       PG8_BAR; PG8_WAIT_L(0); PG8_MMA(0, 1, At, B1); PG8_BAR;
;       PG8_LDA(At, 0, 1); PG8_STAGE(PG8_SA(0, 0), a2, voffA);
;       PG8_BAR; PG8_WAIT_L(0); PG8_MMA(1, 0, At, B0); PG8_BAR; PG8_SCHED;
;       PG8_STAGE(PG8_SB(0, 1), b2 + hstep, voffB);
;       PG8_WAIT_V(6); PG8_BAR; PG8_MMA(1, 1, At, B1); PG8_BAR;
.LBB0_1194:
	ds_read_b128 v[128:131], v214
	ds_read_b128 v[132:135], v214 offset:1024
	ds_read_b128 v[136:139], v214 offset:2048
	ds_read_b128 v[140:143], v214 offset:3072
	s_add_u32 s24, s22, 0xfff80080
	s_addc_u32 s25, s23, -1
	s_cmp_eq_u32 s54, 28
	s_cselect_b32 s27, s17, s25
	s_cselect_b32 s26, s43, s24
	s_cselect_b32 s25, s15, s53
	s_cselect_b32 s24, s51, s52
	s_add_i32 m0, s37, 0xc000
	ds_read_b128 v[144:147], v215
	ds_read_b128 v[148:151], v215 offset:1024
	ds_read_b128 v[152:155], v215 offset:2048
	ds_read_b128 v[156:159], v215 offset:3072
	ds_read_b128 v[160:163], v215 offset:4096
	ds_read_b128 v[164:167], v215 offset:5120
	ds_read_b128 v[168:171], v215 offset:6144
	ds_read_b128 v[172:175], v215 offset:7168
	global_load_lds_dwordx4 v184, s[22:23]
	s_add_i32 m0, s37, 0xe000
	s_nop 0
	global_load_lds_dwordx4 v186, s[22:23]
	ds_read_b128 v[192:195], v216
	ds_read_b128 v[196:199], v216 offset:1024
	ds_read_b128 v[200:203], v216 offset:2048
	ds_read_b128 v[204:207], v216 offset:3072
	s_waitcnt vmcnt(8)
	s_waitcnt lgkmcnt(4)
	s_setprio 1
	s_barrier
	v_mfma_f32_16x16x32_bf16 v[124:127], v[128:131], v[144:147], v[124:127]
	v_mfma_f32_16x16x32_bf16 v[120:123], v[136:139], v[144:147], v[120:123]
	v_mfma_f32_16x16x32_bf16 v[108:111], v[128:131], v[152:155], v[108:111]
	v_mfma_f32_16x16x32_bf16 v[104:107], v[136:139], v[152:155], v[104:107]
	v_mfma_f32_16x16x32_bf16 v[92:95], v[128:131], v[160:163], v[92:95]
	v_mfma_f32_16x16x32_bf16 v[88:91], v[136:139], v[160:163], v[88:91]
	v_mfma_f32_16x16x32_bf16 v[76:79], v[128:131], v[168:171], v[76:79]
	v_mfma_f32_16x16x32_bf16 v[72:75], v[136:139], v[168:171], v[72:75]
	v_mfma_f32_16x16x32_bf16 v[124:127], v[132:135], v[148:151], v[124:127]
	v_mfma_f32_16x16x32_bf16 v[120:123], v[140:143], v[148:151], v[120:123]
	v_mfma_f32_16x16x32_bf16 v[108:111], v[132:135], v[156:159], v[108:111]
	v_mfma_f32_16x16x32_bf16 v[104:107], v[140:143], v[156:159], v[104:107]
	v_mfma_f32_16x16x32_bf16 v[92:95], v[132:135], v[164:167], v[92:95]
	v_mfma_f32_16x16x32_bf16 v[88:91], v[140:143], v[164:167], v[88:91]
	v_mfma_f32_16x16x32_bf16 v[76:79], v[132:135], v[172:175], v[76:79]
	v_mfma_f32_16x16x32_bf16 v[72:75], v[140:143], v[172:175], v[72:75]
	s_waitcnt lgkmcnt(0)
	v_mfma_f32_16x16x32_bf16 v[116:119], v[192:195], v[144:147], v[116:119]
	v_mfma_f32_16x16x32_bf16 v[112:115], v[200:203], v[144:147], v[112:115]
	v_mfma_f32_16x16x32_bf16 v[100:103], v[192:195], v[152:155], v[100:103]
	v_mfma_f32_16x16x32_bf16 v[96:99], v[200:203], v[152:155], v[96:99]
	v_mfma_f32_16x16x32_bf16 v[84:87], v[192:195], v[160:163], v[84:87]
	v_mfma_f32_16x16x32_bf16 v[80:83], v[200:203], v[160:163], v[80:83]
	v_mfma_f32_16x16x32_bf16 v[68:71], v[192:195], v[168:171], v[68:71]
	v_mfma_f32_16x16x32_bf16 v[64:67], v[200:203], v[168:171], v[64:67]
	v_mfma_f32_16x16x32_bf16 v[116:119], v[196:199], v[148:151], v[116:119]
	v_mfma_f32_16x16x32_bf16 v[112:115], v[204:207], v[148:151], v[112:115]
	v_mfma_f32_16x16x32_bf16 v[100:103], v[196:199], v[156:159], v[100:103]
	v_mfma_f32_16x16x32_bf16 v[96:99], v[204:207], v[156:159], v[96:99]
	v_mfma_f32_16x16x32_bf16 v[84:87], v[196:199], v[164:167], v[84:87]
	v_mfma_f32_16x16x32_bf16 v[80:83], v[204:207], v[164:167], v[80:83]
	v_mfma_f32_16x16x32_bf16 v[68:71], v[196:199], v[172:175], v[68:71]
	v_mfma_f32_16x16x32_bf16 v[64:67], v[204:207], v[172:175], v[64:67]
	s_barrier
	s_setprio 0
	s_add_i32 s55, s48, s35
	s_add_u32 s98, s24, 0x80
	s_addc_u32 s99, s25, 0
	s_add_u32 s100, s26, 0x80
	s_addc_u32 s101, s27, 0
	ds_read_b128 v[144:147], v215 offset:16384
	ds_read_b128 v[148:151], v215 offset:17408
	ds_read_b128 v[152:155], v215 offset:18432
	ds_read_b128 v[156:159], v215 offset:19456
	ds_read_b128 v[160:163], v215 offset:20480
	ds_read_b128 v[164:167], v215 offset:21504
	ds_read_b128 v[168:171], v215 offset:22528
	ds_read_b128 v[172:175], v215 offset:23552
	s_mov_b32 m0, s55
	s_nop 0
	global_load_lds_dwordx4 v180, s[24:25]
	s_add_i32 m0, s55, 0x2000
	s_nop 0
	global_load_lds_dwordx4 v176, s[24:25]
	s_mov_b32 m0, s37
	s_nop 0
	global_load_lds_dwordx4 v182, s[26:27]
	s_mov_b32 m0, s38
	s_nop 0
	global_load_lds_dwordx4 v178, s[26:27]
	s_add_u32 s56, s24, 0x80000
	s_addc_u32 s57, s25, 0
	s_add_i32 s55, s49, s35
	s_waitcnt vmcnt(6)
	s_waitcnt lgkmcnt(0)
	s_setprio 1
	s_barrier
	v_mfma_f32_16x16x32_bf16 v[60:63], v[128:131], v[144:147], v[60:63]
	s_mov_b32 m0, s55
	v_mfma_f32_16x16x32_bf16 v[56:59], v[136:139], v[144:147], v[56:59]
	global_load_lds_dwordx4 v180, s[56:57]
	v_mfma_f32_16x16x32_bf16 v[44:47], v[128:131], v[152:155], v[44:47]
	s_bitset1_b32 m0, 13
	v_mfma_f32_16x16x32_bf16 v[40:43], v[136:139], v[152:155], v[40:43]
	global_load_lds_dwordx4 v176, s[56:57]
	v_mfma_f32_16x16x32_bf16 v[28:31], v[128:131], v[160:163], v[28:31]
	v_mfma_f32_16x16x32_bf16 v[24:27], v[136:139], v[160:163], v[24:27]
	v_mfma_f32_16x16x32_bf16 v[12:15], v[128:131], v[168:171], v[12:15]
	v_mfma_f32_16x16x32_bf16 v[8:11], v[136:139], v[168:171], v[8:11]
	v_mfma_f32_16x16x32_bf16 v[60:63], v[132:135], v[148:151], v[60:63]
	v_mfma_f32_16x16x32_bf16 v[56:59], v[140:143], v[148:151], v[56:59]
	v_mfma_f32_16x16x32_bf16 v[44:47], v[132:135], v[156:159], v[44:47]
	v_mfma_f32_16x16x32_bf16 v[40:43], v[140:143], v[156:159], v[40:43]
	v_mfma_f32_16x16x32_bf16 v[28:31], v[132:135], v[164:167], v[28:31]
	v_mfma_f32_16x16x32_bf16 v[24:27], v[140:143], v[164:167], v[24:27]
	v_mfma_f32_16x16x32_bf16 v[12:15], v[132:135], v[172:175], v[12:15]
	v_mfma_f32_16x16x32_bf16 v[8:11], v[140:143], v[172:175], v[8:11]
	v_mfma_f32_16x16x32_bf16 v[52:55], v[192:195], v[144:147], v[52:55]
	v_mfma_f32_16x16x32_bf16 v[48:51], v[200:203], v[144:147], v[48:51]
	v_mfma_f32_16x16x32_bf16 v[36:39], v[192:195], v[152:155], v[36:39]
	v_mfma_f32_16x16x32_bf16 v[32:35], v[200:203], v[152:155], v[32:35]
	v_mfma_f32_16x16x32_bf16 v[20:23], v[192:195], v[160:163], v[20:23]
	v_mfma_f32_16x16x32_bf16 v[16:19], v[200:203], v[160:163], v[16:19]
	v_mfma_f32_16x16x32_bf16 v[4:7], v[192:195], v[168:171], v[4:7]
	v_mfma_f32_16x16x32_bf16 v[0:3], v[200:203], v[168:171], v[0:3]
	v_mfma_f32_16x16x32_bf16 v[52:55], v[196:199], v[148:151], v[52:55]
	v_mfma_f32_16x16x32_bf16 v[48:51], v[204:207], v[148:151], v[48:51]
	v_mfma_f32_16x16x32_bf16 v[36:39], v[196:199], v[156:159], v[36:39]
	v_mfma_f32_16x16x32_bf16 v[32:35], v[204:207], v[156:159], v[32:35]
	v_mfma_f32_16x16x32_bf16 v[20:23], v[196:199], v[164:167], v[20:23]
	v_mfma_f32_16x16x32_bf16 v[16:19], v[204:207], v[164:167], v[16:19]
	v_mfma_f32_16x16x32_bf16 v[4:7], v[196:199], v[172:175], v[4:7]
	v_mfma_f32_16x16x32_bf16 v[0:3], v[204:207], v[172:175], v[0:3]
	s_barrier
; #define PG8_STAGE(bufoff, gbase, voff) do { _Pragma("unroll") for (int _i = 0; _i < 2; ++_i) \
;     __builtin_amdgcn_global_load_lds((const unsigned*)((const char*)(gbase) + (voff)[_i]), (LAS unsigned*)(lds + (bufoff) + ldsw + _i * 8192), 16, 0, 0); } while (0)
; #define PG8_LDA(dst, b, h) do { _Pragma("unroll") for (int m = 0; m < 4; ++m) _Pragma("unroll") for (int k = 0; k < 2; ++k) dst[m][k] = *(const LAS bf16x8*)(lds + PG8_SA(b, h) + aoff + m * 2048 + k * 1024); } while (0)
; #define PG8_LDB(dst, b, h) do { _Pragma("unroll") for (int n = 0; n < 2; ++n) _Pragma("unroll") for (int k = 0; k < 2; ++k) dst[n][k] = *(const LAS bf16x8*)(lds + PG8_SB(b, h) + boff + n * 2048 + k * 1024); } while (0)
; #define PG8_MMA(ai, bj, At, Bt) do { __builtin_amdgcn_s_setprio(1); _Pragma("unroll") for (int m = 0; m < 4; ++m) _Pragma("unroll") for (int n = 0; n < 2; ++n) _Pragma("unroll") for (int k = 0; k < 2; ++k) \
;     acc[ai][bj][m][n] = __builtin_amdgcn_mfma_f32_16x16x32_bf16(Bt[n][k], At[m][k], acc[ai][bj][m][n], 0, 0, 0); __builtin_amdgcn_s_setprio(0); } while (0)
; #define PG8_WAIT_V(n) asm volatile("s_waitcnt vmcnt(" #n ")" ::: "memory")
; #define PG8_WAIT_L(n) asm volatile("s_waitcnt lgkmcnt(" #n ")" ::: "memory")
; #define PG8_BAR __builtin_amdgcn_s_barrier()
; #define PG8_SCHED __builtin_amdgcn_sched_barrier(0)
; template <class Epi, class Sched = StaticOrder>
; DI void gemm_phase(LAS unsigned char* lds, const Gemm g, const Sched& S, const Epi& E) {
;     ...
;       PG8_LDB(B0, 1, 0); PG8_SCHED; PG8_LDA(At, 1, 0); PG8_STAGE(PG8_SA(0, 1), a2 + hstep, voffA);
;       PG8_WAIT_L(8); PG8_BAR; PG8_WAIT_L(0); PG8_MMA(0, 0, At, B0); PG8_BAR; PG8_SCHED;
;       PG8_LDB(B1, 1, 1); PG8_STAGE(PG8_SB(1, 0), b3, voffB);
;       PG8_BAR; PG8_WAIT_L(0); PG8_MMA(0, 1, At, B1); PG8_BAR;
;       PG8_LDA(At, 1, 1); PG8_STAGE(PG8_SA(1, 0), a3, voffA);
;       PG8_BAR; PG8_WAIT_L(0); PG8_MMA(1, 0, At, B0); PG8_BAR; PG8_SCHED;
;       PG8_STAGE(PG8_SB(1, 1), b3 + hstep, voffB);
;       PG8_WAIT_V(6); PG8_BAR; PG8_MMA(1, 1, At, B1); PG8_BAR;
	s_setprio 0
	s_add_i32 s55, 0, 0x18000
	v_add_u32_e32 v140, s55, v212
	ds_read_b128 v[128:131], v140
	ds_read_b128 v[132:135], v140 offset:1024
	ds_read_b128 v[136:139], v140 offset:2048
	ds_read_b128 v[140:143], v140 offset:3072
	s_add_u32 s26, s26, 0x80000
	s_addc_u32 s27, s27, 0
	s_mov_b32 m0, s39
	ds_read_b128 v[144:147], v215 offset:32768
	ds_read_b128 v[148:151], v215 offset:33792
	ds_read_b128 v[152:155], v215 offset:34816
	ds_read_b128 v[156:159], v215 offset:35840
	ds_read_b128 v[160:163], v215 offset:36864
	ds_read_b128 v[164:167], v215 offset:37888
	ds_read_b128 v[168:171], v215 offset:38912
	ds_read_b128 v[172:175], v215 offset:39936
	global_load_lds_dwordx4 v182, s[26:27]
	s_mov_b32 m0, s40
	s_nop 0
	global_load_lds_dwordx4 v178, s[26:27]
	s_add_i32 s26, 0, 0x1c000
	v_add_u32_e32 v204, s26, v212
	ds_read_b128 v[192:195], v204
	ds_read_b128 v[196:199], v204 offset:1024
	ds_read_b128 v[200:203], v204 offset:2048
	ds_read_b128 v[204:207], v204 offset:3072
	s_waitcnt vmcnt(8)
	s_waitcnt lgkmcnt(4)
	s_setprio 1
	s_barrier
	v_mfma_f32_16x16x32_bf16 v[124:127], v[128:131], v[144:147], v[124:127]
	v_mfma_f32_16x16x32_bf16 v[120:123], v[136:139], v[144:147], v[120:123]
	v_mfma_f32_16x16x32_bf16 v[108:111], v[128:131], v[152:155], v[108:111]
	v_mfma_f32_16x16x32_bf16 v[104:107], v[136:139], v[152:155], v[104:107]
	v_mfma_f32_16x16x32_bf16 v[92:95], v[128:131], v[160:163], v[92:95]
	v_mfma_f32_16x16x32_bf16 v[88:91], v[136:139], v[160:163], v[88:91]
	v_mfma_f32_16x16x32_bf16 v[76:79], v[128:131], v[168:171], v[76:79]
	v_mfma_f32_16x16x32_bf16 v[72:75], v[136:139], v[168:171], v[72:75]
	v_mfma_f32_16x16x32_bf16 v[124:127], v[132:135], v[148:151], v[124:127]
	v_mfma_f32_16x16x32_bf16 v[120:123], v[140:143], v[148:151], v[120:123]
	v_mfma_f32_16x16x32_bf16 v[108:111], v[132:135], v[156:159], v[108:111]
	v_mfma_f32_16x16x32_bf16 v[104:107], v[140:143], v[156:159], v[104:107]
	v_mfma_f32_16x16x32_bf16 v[92:95], v[132:135], v[164:167], v[92:95]
	v_mfma_f32_16x16x32_bf16 v[88:91], v[140:143], v[164:167], v[88:91]
	v_mfma_f32_16x16x32_bf16 v[76:79], v[132:135], v[172:175], v[76:79]
	v_mfma_f32_16x16x32_bf16 v[72:75], v[140:143], v[172:175], v[72:75]
	s_waitcnt lgkmcnt(0)
	v_mfma_f32_16x16x32_bf16 v[116:119], v[192:195], v[144:147], v[116:119]
	v_mfma_f32_16x16x32_bf16 v[112:115], v[200:203], v[144:147], v[112:115]
	v_mfma_f32_16x16x32_bf16 v[100:103], v[192:195], v[152:155], v[100:103]
	v_mfma_f32_16x16x32_bf16 v[96:99], v[200:203], v[152:155], v[96:99]
	v_mfma_f32_16x16x32_bf16 v[84:87], v[192:195], v[160:163], v[84:87]
	v_mfma_f32_16x16x32_bf16 v[80:83], v[200:203], v[160:163], v[80:83]
	v_mfma_f32_16x16x32_bf16 v[68:71], v[192:195], v[168:171], v[68:71]
	v_mfma_f32_16x16x32_bf16 v[64:67], v[200:203], v[168:171], v[64:67]
	v_mfma_f32_16x16x32_bf16 v[116:119], v[196:199], v[148:151], v[116:119]
	v_mfma_f32_16x16x32_bf16 v[112:115], v[204:207], v[148:151], v[112:115]
	v_mfma_f32_16x16x32_bf16 v[100:103], v[196:199], v[156:159], v[100:103]
	v_mfma_f32_16x16x32_bf16 v[96:99], v[204:207], v[156:159], v[96:99]
	v_mfma_f32_16x16x32_bf16 v[84:87], v[196:199], v[164:167], v[84:87]
	v_mfma_f32_16x16x32_bf16 v[80:83], v[204:207], v[164:167], v[80:83]
	v_mfma_f32_16x16x32_bf16 v[68:71], v[196:199], v[172:175], v[68:71]
	v_mfma_f32_16x16x32_bf16 v[64:67], v[204:207], v[172:175], v[64:67]
	s_barrier
	s_setprio 0
	s_add_i32 s27, s55, s35
	ds_read_b128 v[144:147], v215 offset:49152
	ds_read_b128 v[148:151], v215 offset:50176
	ds_read_b128 v[152:155], v215 offset:51200
	ds_read_b128 v[156:159], v215 offset:52224
	ds_read_b128 v[160:163], v215 offset:53248
	ds_read_b128 v[164:167], v215 offset:54272
	ds_read_b128 v[168:171], v215 offset:55296
	ds_read_b128 v[172:175], v215 offset:56320
	s_mov_b32 m0, s27
	s_nop 0
	global_load_lds_dwordx4 v180, s[98:99]
	s_add_i32 m0, s27, 0x2000
	s_nop 0
	global_load_lds_dwordx4 v176, s[98:99]
	s_mov_b32 m0, s44
	s_nop 0
	global_load_lds_dwordx4 v182, s[100:101]
	s_mov_b32 m0, s45
	s_nop 0
	global_load_lds_dwordx4 v178, s[100:101]
	s_add_u32 s24, s24, 0x80080
	s_addc_u32 s25, s25, 0
	s_add_i32 s26, s26, s35
	s_add_i32 s54, s54, 2
	s_add_u32 s22, s22, 0x100
	s_addc_u32 s23, s23, 0
	s_add_u32 s52, s52, 0x100
	s_addc_u32 s53, s53, 0
	s_cmp_gt_u32 s54, 29
	s_waitcnt vmcnt(6)
	s_waitcnt lgkmcnt(0)
	s_setprio 1
	s_barrier
	v_mfma_f32_16x16x32_bf16 v[60:63], v[128:131], v[144:147], v[60:63]
	s_mov_b32 m0, s26
	v_mfma_f32_16x16x32_bf16 v[56:59], v[136:139], v[144:147], v[56:59]
	global_load_lds_dwordx4 v180, s[24:25]
	v_mfma_f32_16x16x32_bf16 v[44:47], v[128:131], v[152:155], v[44:47]
	s_bitset1_b32 m0, 13
	v_mfma_f32_16x16x32_bf16 v[40:43], v[136:139], v[152:155], v[40:43]
	global_load_lds_dwordx4 v176, s[24:25]
	v_mfma_f32_16x16x32_bf16 v[28:31], v[128:131], v[160:163], v[28:31]
	v_mfma_f32_16x16x32_bf16 v[24:27], v[136:139], v[160:163], v[24:27]
	v_mfma_f32_16x16x32_bf16 v[12:15], v[128:131], v[168:171], v[12:15]
	v_mfma_f32_16x16x32_bf16 v[8:11], v[136:139], v[168:171], v[8:11]
	v_mfma_f32_16x16x32_bf16 v[60:63], v[132:135], v[148:151], v[60:63]
	v_mfma_f32_16x16x32_bf16 v[56:59], v[140:143], v[148:151], v[56:59]
	v_mfma_f32_16x16x32_bf16 v[44:47], v[132:135], v[156:159], v[44:47]
	v_mfma_f32_16x16x32_bf16 v[40:43], v[140:143], v[156:159], v[40:43]
	v_mfma_f32_16x16x32_bf16 v[28:31], v[132:135], v[164:167], v[28:31]
	v_mfma_f32_16x16x32_bf16 v[24:27], v[140:143], v[164:167], v[24:27]
	v_mfma_f32_16x16x32_bf16 v[12:15], v[132:135], v[172:175], v[12:15]
	v_mfma_f32_16x16x32_bf16 v[8:11], v[140:143], v[172:175], v[8:11]
	v_mfma_f32_16x16x32_bf16 v[52:55], v[192:195], v[144:147], v[52:55]
	v_mfma_f32_16x16x32_bf16 v[48:51], v[200:203], v[144:147], v[48:51]
	v_mfma_f32_16x16x32_bf16 v[36:39], v[192:195], v[152:155], v[36:39]
	v_mfma_f32_16x16x32_bf16 v[32:35], v[200:203], v[152:155], v[32:35]
	v_mfma_f32_16x16x32_bf16 v[20:23], v[192:195], v[160:163], v[20:23]
	v_mfma_f32_16x16x32_bf16 v[16:19], v[200:203], v[160:163], v[16:19]
	v_mfma_f32_16x16x32_bf16 v[4:7], v[192:195], v[168:171], v[4:7]
	v_mfma_f32_16x16x32_bf16 v[0:3], v[200:203], v[168:171], v[0:3]
	v_mfma_f32_16x16x32_bf16 v[52:55], v[196:199], v[148:151], v[52:55]
	v_mfma_f32_16x16x32_bf16 v[48:51], v[204:207], v[148:151], v[48:51]
	v_mfma_f32_16x16x32_bf16 v[36:39], v[196:199], v[156:159], v[36:39]
	v_mfma_f32_16x16x32_bf16 v[32:35], v[204:207], v[156:159], v[32:35]
	v_mfma_f32_16x16x32_bf16 v[20:23], v[196:199], v[164:167], v[20:23]
	v_mfma_f32_16x16x32_bf16 v[16:19], v[204:207], v[164:167], v[16:19]
	v_mfma_f32_16x16x32_bf16 v[4:7], v[196:199], v[172:175], v[4:7]
	v_mfma_f32_16x16x32_bf16 v[0:3], v[204:207], v[172:175], v[0:3]
	s_barrier
; DI unsigned pack2(float lo, float hi) { f32x2 v = {lo, hi}; bf16v2 r = __builtin_convertvector(v, bf16v2); return __builtin_bit_cast(unsigned, r); }
;   DI void operator()(const f32x4 (&acc)[2][2][4][2], const Unit& u, int wr, int wc, int fr, int fq) const {
;     const int row0 = u.pm * BM + wr * 64 + fr, col0 = u.pn * BM + wc * 32 + 8 * fq;
; #pragma unroll
;     for (int ai = 0; ai < 2; ++ai) {
;       f32x4 bv[4][2][2];
; #pragma unroll
;       for (int m = 0; m < 4; ++m)
; #pragma unroll
;         for (int bj = 0; bj < 2; ++bj) {
;           const float* bp = base + (size_t)(row0 + ai * HALF + m * 16) * 2048 + col0 + bj * HALF;
;           bv[m][bj][0] = *(const f32x4*)bp; bv[m][bj][1] = *(const f32x4*)(bp + 4);
;         }
; #pragma unroll
;       for (int m = 0; m < 4; ++m) {
;         const int row = row0 + ai * HALF + m * 16;
;         const size_t off = (size_t)row * 2048 + col0;
;         float ss = 0.f;
; #pragma unroll
;         for (int bj = 0; bj < 2; ++bj) {
;           const f32x4 v0 = acc[ai][bj][m][0] + bv[m][bj][0], v1 = acc[ai][bj][m][1] + bv[m][bj][1];
;           *(f32x4*)(C + off + bj * HALF) = v0; *(f32x4*)(C + off + bj * HALF + 4) = v1;
;           if (xb) {
;             u32x4 w; w.x = pack2(v0[0], v0[1]); w.y = pack2(v0[2], v0[3]); w.z = pack2(v1[0], v1[1]); w.w = pack2(v1[2], v1[3]);
;             *(u32x4*)(xb + off + bj * HALF) = w;
;             ss += v0[0] * v0[0] + v0[1] * v0[1] + v0[2] * v0[2] + v0[3] * v0[3] + v1[0] * v1[0] + v1[1] * v1[1] + v1[2] * v1[2] + v1[3] * v1[3];
;           }
;         }
;         if (xb) {
;           ss += __shfl_xor(ss, 16); ss += __shfl_xor(ss, 32);
;           if (fq == 0) ssq[(size_t)row * 32 + u.pn * 4 + wc] = ss;
;         }
	s_setprio 0
	s_cbranch_scc0 .LBB0_1194
	v_lshl_add_u32 v194, s12, 8, v211
	v_lshl_or_b32 v192, s42, 8, v213
	v_readlane_b32 s52, v243, 3
	v_ashrrev_i32_e32 v193, 31, v192
	v_readlane_b32 s66, v243, 17
	v_readlane_b32 s67, v243, 18
	v_ashrrev_i32_e32 v195, 31, v194
	v_lshlrev_b64 v[128:129], 13, v[194:195]
	v_lshl_add_u64 v[196:197], v[192:193], 2, s[66:67]
	v_lshl_add_u64 v[236:237], v[196:197], 0, v[128:129]
	global_load_dwordx4 v[220:223], v[236:237], off
	global_load_dwordx4 v[224:227], v[236:237], off offset:16
	global_load_dwordx4 v[228:231], v[236:237], off offset:512
	global_load_dwordx4 v[232:235], v[236:237], off offset:528
	v_or_b32_e32 v206, 16, v194
	v_or_b32_e32 v202, 32, v194
	v_or_b32_e32 v198, 48, v194
	v_ashrrev_i32_e32 v207, 31, v206
	v_ashrrev_i32_e32 v203, 31, v202
	v_ashrrev_i32_e32 v199, 31, v198
	v_lshlrev_b64 v[128:129], 13, v[206:207]
	v_lshlrev_b64 v[130:131], 13, v[202:203]
	v_lshlrev_b64 v[132:133], 13, v[198:199]
	v_lshl_add_u64 v[208:209], v[196:197], 0, v[128:129]
	v_lshl_add_u64 v[204:205], v[196:197], 0, v[130:131]
	v_lshl_add_u64 v[200:201], v[196:197], 0, v[132:133]
	global_load_dwordx4 v[168:171], v[208:209], off offset:16
	global_load_dwordx4 v[172:175], v[208:209], off
	global_load_dwordx4 v[160:163], v[208:209], off offset:528
	global_load_dwordx4 v[164:167], v[208:209], off offset:512
	global_load_dwordx4 v[152:155], v[204:205], off offset:16
	global_load_dwordx4 v[156:159], v[204:205], off
	global_load_dwordx4 v[144:147], v[204:205], off offset:528
	global_load_dwordx4 v[148:151], v[204:205], off offset:512
	global_load_dwordx4 v[136:139], v[200:201], off offset:16
	global_load_dwordx4 v[140:143], v[200:201], off
	global_load_dwordx4 v[128:131], v[200:201], off offset:528
	global_load_dwordx4 v[132:135], v[200:201], off offset:512
	v_and_b32_e32 v218, 64, v217
	v_xor_b32_e32 v238, 16, v217
	v_add_u32_e32 v240, 64, v218
	v_xor_b32_e32 v239, 32, v217
	v_cmp_lt_i32_e32 vcc, v238, v240
	v_lshlrev_b64 v[218:219], 11, v[194:195]
	s_lshl_b32 s22, s42, 2
	v_cndmask_b32_e32 v241, v217, v238, vcc
	v_cmp_lt_i32_e32 vcc, v239, v240
	s_ashr_i32 s23, s22, 31
	v_readlane_b32 s53, v243, 4
	v_cndmask_b32_e32 v240, v217, v239, vcc
	v_lshl_add_u64 v[238:239], v[218:219], 0, v[192:193]
	v_lshlrev_b32_e32 v218, 2, v241
	v_lshl_add_u64 v[238:239], v[238:239], 1, s[2:3]
	v_readlane_b32 s54, v243, 5
	v_readlane_b32 s55, v243, 6
	v_readlane_b32 s56, v243, 7
	v_readlane_b32 s57, v243, 8
	v_readlane_b32 s58, v243, 9
	v_readlane_b32 s59, v243, 10
	v_readlane_b32 s60, v243, 11
	v_readlane_b32 s61, v243, 12
	v_readlane_b32 s62, v243, 13
	v_readlane_b32 s63, v243, 14
	v_readlane_b32 s64, v243, 15
	v_readlane_b32 s65, v243, 16
	s_waitcnt vmcnt(0)
	v_pk_add_f32 v[126:127], v[126:127], v[222:223]
	v_pk_add_f32 v[124:125], v[124:125], v[220:221]
	v_pk_add_f32 v[116:117], v[116:117], v[228:229]
	v_pk_add_f32 v[122:123], v[122:123], v[226:227]
	v_pk_add_f32 v[120:121], v[120:121], v[224:225]
	v_pk_add_f32 v[220:221], v[112:113], v[232:233]
	global_store_dwordx4 v[236:237], v[124:127], off
	global_store_dwordx4 v[236:237], v[120:123], off offset:16
	v_cvt_pk_bf16_f32 v112, v124, v125
	v_mul_f32_e32 v125, v125, v125
	v_mul_f32_e32 v219, v117, v117
	v_pk_add_f32 v[118:119], v[118:119], v[230:231]
	v_fmac_f32_e32 v125, v124, v124
	v_fmac_f32_e32 v219, v116, v116
	v_fmac_f32_e32 v125, v126, v126
	v_fmac_f32_e32 v219, v118, v118
	v_fmac_f32_e32 v125, v127, v127
	v_fmac_f32_e32 v219, v119, v119
	v_fmac_f32_e32 v125, v120, v120
	v_fmac_f32_e32 v219, v220, v220
	v_pk_add_f32 v[222:223], v[114:115], v[234:235]
	v_fmac_f32_e32 v125, v121, v121
	v_fmac_f32_e32 v219, v221, v221
	v_fmac_f32_e32 v125, v122, v122
	v_fmac_f32_e32 v219, v222, v222
	v_fmac_f32_e32 v125, v123, v123
	v_fmac_f32_e32 v219, v223, v223
	v_cvt_pk_bf16_f32 v114, v120, v121
	v_add_f32_e32 v121, v125, v219
	v_cvt_pk_bf16_f32 v115, v122, v123
	ds_bpermute_b32 v122, v218, v121
	v_cvt_pk_bf16_f32 v113, v126, v127
	global_store_dwordx4 v[238:239], v[112:115], off
	global_store_dwordx4 v[236:237], v[116:119], off offset:512
	global_store_dwordx4 v[236:237], v[220:223], off offset:528
	v_lshlrev_b32_e32 v126, 2, v240
	v_cvt_pk_bf16_f32 v120, v116, v117
	s_waitcnt lgkmcnt(0)
	v_add_f32_e32 v112, v121, v122
	ds_bpermute_b32 v113, v126, v112
	v_cvt_pk_bf16_f32 v121, v118, v119
	v_cvt_pk_bf16_f32 v122, v220, v221
	v_cvt_pk_bf16_f32 v123, v222, v223
	global_store_dwordx4 v[238:239], v[120:123], off offset:256
	s_and_saveexec_b64 s[24:25], s[0:1]
	s_cbranch_execz .LBB0_1197
	s_waitcnt lgkmcnt(0)
	v_add_f32_e32 v114, v112, v113
	v_lshlrev_b64 v[112:113], 7, v[194:195]
	v_lshl_add_u64 v[112:113], s[8:9], 0, v[112:113]
	v_lshl_add_u64 v[112:113], s[22:23], 2, v[112:113]
	s_lshl_b32 s12, s41, 2
	v_lshl_add_u64 v[112:113], v[112:113], 0, s[12:13]
	global_store_dword v[112:113], v114, off

; #define PG8_STAGE(bufoff, gbase, voff) do { _Pragma("unroll") for (int _i = 0; _i < 2; ++_i) \
;     __builtin_amdgcn_global_load_lds((const unsigned*)((const char*)(gbase) + (voff)[_i]), (LAS unsigned*)(lds + (bufoff) + ldsw + _i * 8192), 16, 0, 0); } while (0)
; #define PG8_LDA(dst, b, h) do { _Pragma("unroll") for (int m = 0; m < 4; ++m) _Pragma("unroll") for (int k = 0; k < 2; ++k) dst[m][k] = *(const LAS bf16x8*)(lds + PG8_SA(b, h) + aoff + m * 2048 + k * 1024); } while (0)
; #define PG8_LDB(dst, b, h) do { _Pragma("unroll") for (int n = 0; n < 2; ++n) _Pragma("unroll") for (int k = 0; k < 2; ++k) dst[n][k] = *(const LAS bf16x8*)(lds + PG8_SB(b, h) + boff + n * 2048 + k * 1024); } while (0)
; #define PG8_MMA(ai, bj, At, Bt) do { __builtin_amdgcn_s_setprio(1); _Pragma("unroll") for (int m = 0; m < 4; ++m) _Pragma("unroll") for (int n = 0; n < 2; ++n) _Pragma("unroll") for (int k = 0; k < 2; ++k) \
;     acc[ai][bj][m][n] = __builtin_amdgcn_mfma_f32_16x16x32_bf16(Bt[n][k], At[m][k], acc[ai][bj][m][n], 0, 0, 0); __builtin_amdgcn_s_setprio(0); } while (0)
; #define PG8_WAIT_V(n) asm volatile("s_waitcnt vmcnt(" #n ")" ::: "memory")
; #define PG8_WAIT_L(n) asm volatile("s_waitcnt lgkmcnt(" #n ")" ::: "memory")
; #define PG8_BAR __builtin_amdgcn_s_barrier()
; #define PG8_SCHED __builtin_amdgcn_sched_barrier(0)
; template <class Epi, class Sched = StaticOrder>
; DI void gemm_phase(LAS unsigned char* lds, const Gemm g, const Sched& S, const Epi& E) {
;     ...
;       PG8_LDB(B0, 0, 0); PG8_SCHED; PG8_LDA(At, 0, 0); PG8_STAGE(PG8_SA(1, 1), a1 + hstep, voffA);
;       PG8_WAIT_L(8); PG8_BAR; PG8_WAIT_L(0); PG8_MMA(0, 0, At, B0); PG8_BAR; PG8_SCHED;
;       PG8_LDB(B1, 0, 1); PG8_STAGE(PG8_SB(0, 0), b2, voffB);
;       PG8_BAR; PG8_WAIT_L(0); PG8_MMA(0, 1, At, B1); PG8_BAR;
;       PG8_LDA(At, 0, 1); PG8_STAGE(PG8_SA(0, 0), a2, voffA);
;       PG8_BAR; PG8_WAIT_L(0); PG8_MMA(1, 0, At, B0); PG8_BAR; PG8_SCHED;
;       PG8_STAGE(PG8_SB(0, 1), b2 + hstep, voffB);
;       PG8_WAIT_V(6); PG8_BAR; PG8_MMA(1, 1, At, B1); PG8_BAR;
.LBB0_1277:
	ds_read_b128 v[64:67], v201
	ds_read_b128 v[68:71], v201 offset:1024
	ds_read_b128 v[72:75], v201 offset:2048
	ds_read_b128 v[76:79], v201 offset:3072
	s_add_u32 s48, s14, 0xfff80080
	s_addc_u32 s49, s15, -1
	s_cmp_eq_u32 s58, 28
	s_cselect_b32 s51, s41, s49
	s_cselect_b32 s50, s42, s48
	s_cselect_b32 s49, s39, s53
	s_cselect_b32 s48, s43, s52
	s_add_i32 m0, s64, 0xc000
	ds_read_b128 v[80:83], v202
	ds_read_b128 v[84:87], v202 offset:1024
	ds_read_b128 v[88:91], v202 offset:2048
	ds_read_b128 v[92:95], v202 offset:3072
	ds_read_b128 v[180:183], v202 offset:4096
	ds_read_b128 v[184:187], v202 offset:5120
	ds_read_b128 v[188:191], v202 offset:6144
	ds_read_b128 v[192:195], v202 offset:7168
	global_load_lds_dwordx4 v170, s[14:15]
	s_add_i32 m0, s64, 0xe000
	s_nop 0
	global_load_lds_dwordx4 v172, s[14:15]
	ds_read_b128 v[206:209], v203
	ds_read_b128 v[212:215], v203 offset:1024
	ds_read_b128 v[216:219], v203 offset:2048
	ds_read_b128 v[220:223], v203 offset:3072
	s_waitcnt vmcnt(8)
	s_waitcnt lgkmcnt(4)
	s_setprio 1
	s_barrier
	v_mfma_f32_16x16x32_bf16 v[156:159], v[64:67], v[80:83], v[156:159]
	v_mfma_f32_16x16x32_bf16 v[144:147], v[72:75], v[80:83], v[144:147]
	v_mfma_f32_16x16x32_bf16 v[140:143], v[64:67], v[88:91], v[140:143]
	v_mfma_f32_16x16x32_bf16 v[132:135], v[72:75], v[88:91], v[132:135]
	v_mfma_f32_16x16x32_bf16 v[124:127], v[64:67], v[180:183], v[124:127]
	v_mfma_f32_16x16x32_bf16 v[116:119], v[72:75], v[180:183], v[116:119]
	v_mfma_f32_16x16x32_bf16 v[112:115], v[64:67], v[188:191], v[112:115]
	v_mfma_f32_16x16x32_bf16 v[108:111], v[72:75], v[188:191], v[108:111]
	v_mfma_f32_16x16x32_bf16 v[156:159], v[68:71], v[84:87], v[156:159]
	v_mfma_f32_16x16x32_bf16 v[144:147], v[76:79], v[84:87], v[144:147]
	v_mfma_f32_16x16x32_bf16 v[140:143], v[68:71], v[92:95], v[140:143]
	v_mfma_f32_16x16x32_bf16 v[132:135], v[76:79], v[92:95], v[132:135]
	v_mfma_f32_16x16x32_bf16 v[124:127], v[68:71], v[184:187], v[124:127]
	v_mfma_f32_16x16x32_bf16 v[116:119], v[76:79], v[184:187], v[116:119]
	v_mfma_f32_16x16x32_bf16 v[112:115], v[68:71], v[192:195], v[112:115]
	v_mfma_f32_16x16x32_bf16 v[108:111], v[76:79], v[192:195], v[108:111]
	s_waitcnt lgkmcnt(0)
	v_mfma_f32_16x16x32_bf16 v[152:155], v[206:209], v[80:83], v[152:155]
	v_mfma_f32_16x16x32_bf16 v[80:83], v[216:219], v[80:83], v[148:151]
	v_mfma_f32_16x16x32_bf16 v[152:155], v[212:215], v[84:87], v[152:155]
	v_mfma_f32_16x16x32_bf16 v[80:83], v[220:223], v[84:87], v[80:83]
	v_mfma_f32_16x16x32_bf16 v[84:87], v[206:209], v[88:91], v[136:139]
	v_mfma_f32_16x16x32_bf16 v[88:91], v[216:219], v[88:91], v[128:131]
	v_mfma_f32_16x16x32_bf16 v[104:107], v[216:219], v[180:183], v[104:107]
	v_mfma_f32_16x16x32_bf16 v[100:103], v[206:209], v[188:191], v[100:103]
	v_mfma_f32_16x16x32_bf16 v[96:99], v[216:219], v[188:191], v[96:99]
	v_mfma_f32_16x16x32_bf16 v[84:87], v[212:215], v[92:95], v[84:87]
	v_mfma_f32_16x16x32_bf16 v[88:91], v[220:223], v[92:95], v[88:91]
	v_mfma_f32_16x16x32_bf16 v[92:95], v[206:209], v[180:183], v[120:123]
	v_mfma_f32_16x16x32_bf16 v[104:107], v[220:223], v[184:187], v[104:107]
	v_mfma_f32_16x16x32_bf16 v[100:103], v[212:215], v[192:195], v[100:103]
	v_mfma_f32_16x16x32_bf16 v[96:99], v[220:223], v[192:195], v[96:99]
	v_mfma_f32_16x16x32_bf16 v[92:95], v[212:215], v[184:187], v[92:95]
	s_barrier
	s_setprio 0
	s_add_i32 s59, s72, s62
	s_add_u32 s98, s48, 0x80
	s_addc_u32 s99, s49, 0
	s_add_u32 s100, s50, 0x80
	s_addc_u32 s101, s51, 0
	ds_read_b128 v[120:123], v202 offset:16384
	ds_read_b128 v[128:131], v202 offset:17408
	ds_read_b128 v[136:139], v202 offset:18432
	ds_read_b128 v[148:151], v202 offset:19456
	ds_read_b128 v[180:183], v202 offset:20480
	ds_read_b128 v[184:187], v202 offset:21504
	ds_read_b128 v[188:191], v202 offset:22528
	ds_read_b128 v[192:195], v202 offset:23552
	s_mov_b32 m0, s59
	s_nop 0
	global_load_lds_dwordx4 v164, s[48:49]
	s_add_i32 m0, s59, 0x2000
	s_nop 0
	global_load_lds_dwordx4 v160, s[48:49]
	s_mov_b32 m0, s64
	s_nop 0
	global_load_lds_dwordx4 v166, s[50:51]
	s_mov_b32 m0, s65
	s_nop 0
	global_load_lds_dwordx4 v162, s[50:51]
	s_add_u32 s78, s48, 0x80000
	s_addc_u32 s79, s49, 0
	s_add_i32 s59, s73, s62
	s_waitcnt vmcnt(6)
	s_waitcnt lgkmcnt(0)
	s_setprio 1
	s_barrier
	v_mfma_f32_16x16x32_bf16 v[60:63], v[64:67], v[120:123], v[60:63]
	s_mov_b32 m0, s59
	v_mfma_f32_16x16x32_bf16 v[48:51], v[72:75], v[120:123], v[48:51]
	global_load_lds_dwordx4 v164, s[78:79]
	v_mfma_f32_16x16x32_bf16 v[44:47], v[64:67], v[136:139], v[44:47]
	s_bitset1_b32 m0, 13
	v_mfma_f32_16x16x32_bf16 v[36:39], v[72:75], v[136:139], v[36:39]
	global_load_lds_dwordx4 v160, s[78:79]
	v_mfma_f32_16x16x32_bf16 v[28:31], v[64:67], v[180:183], v[28:31]
	v_mfma_f32_16x16x32_bf16 v[20:23], v[72:75], v[180:183], v[20:23]
	v_mfma_f32_16x16x32_bf16 v[16:19], v[64:67], v[188:191], v[16:19]
	v_mfma_f32_16x16x32_bf16 v[12:15], v[72:75], v[188:191], v[12:15]
	v_mfma_f32_16x16x32_bf16 v[60:63], v[68:71], v[128:131], v[60:63]
	v_mfma_f32_16x16x32_bf16 v[48:51], v[76:79], v[128:131], v[48:51]
	v_mfma_f32_16x16x32_bf16 v[44:47], v[68:71], v[148:151], v[44:47]
	v_mfma_f32_16x16x32_bf16 v[36:39], v[76:79], v[148:151], v[36:39]
	v_mfma_f32_16x16x32_bf16 v[28:31], v[68:71], v[184:187], v[28:31]
	v_mfma_f32_16x16x32_bf16 v[20:23], v[76:79], v[184:187], v[20:23]
	v_mfma_f32_16x16x32_bf16 v[16:19], v[68:71], v[192:195], v[16:19]
	v_mfma_f32_16x16x32_bf16 v[12:15], v[76:79], v[192:195], v[12:15]
	v_mfma_f32_16x16x32_bf16 v[56:59], v[206:209], v[120:123], v[56:59]
	v_mfma_f32_16x16x32_bf16 v[52:55], v[216:219], v[120:123], v[52:55]
	v_mfma_f32_16x16x32_bf16 v[40:43], v[206:209], v[136:139], v[40:43]
	v_mfma_f32_16x16x32_bf16 v[32:35], v[216:219], v[136:139], v[32:35]
	v_mfma_f32_16x16x32_bf16 v[24:27], v[206:209], v[180:183], v[24:27]
	v_mfma_f32_16x16x32_bf16 v[8:11], v[216:219], v[180:183], v[8:11]
	v_mfma_f32_16x16x32_bf16 v[4:7], v[206:209], v[188:191], v[4:7]
	v_mfma_f32_16x16x32_bf16 v[0:3], v[216:219], v[188:191], v[0:3]
	v_mfma_f32_16x16x32_bf16 v[56:59], v[212:215], v[128:131], v[56:59]
	v_mfma_f32_16x16x32_bf16 v[52:55], v[220:223], v[128:131], v[52:55]
	v_mfma_f32_16x16x32_bf16 v[40:43], v[212:215], v[148:151], v[40:43]
	v_mfma_f32_16x16x32_bf16 v[32:35], v[220:223], v[148:151], v[32:35]
	v_mfma_f32_16x16x32_bf16 v[24:27], v[212:215], v[184:187], v[24:27]
	v_mfma_f32_16x16x32_bf16 v[8:11], v[220:223], v[184:187], v[8:11]
	v_mfma_f32_16x16x32_bf16 v[4:7], v[212:215], v[192:195], v[4:7]
	v_mfma_f32_16x16x32_bf16 v[0:3], v[220:223], v[192:195], v[0:3]
	s_barrier
; #define PG8_STAGE(bufoff, gbase, voff) do { _Pragma("unroll") for (int _i = 0; _i < 2; ++_i) \
;     __builtin_amdgcn_global_load_lds((const unsigned*)((const char*)(gbase) + (voff)[_i]), (LAS unsigned*)(lds + (bufoff) + ldsw + _i * 8192), 16, 0, 0); } while (0)
; #define PG8_LDA(dst, b, h) do { _Pragma("unroll") for (int m = 0; m < 4; ++m) _Pragma("unroll") for (int k = 0; k < 2; ++k) dst[m][k] = *(const LAS bf16x8*)(lds + PG8_SA(b, h) + aoff + m * 2048 + k * 1024); } while (0)
; #define PG8_LDB(dst, b, h) do { _Pragma("unroll") for (int n = 0; n < 2; ++n) _Pragma("unroll") for (int k = 0; k < 2; ++k) dst[n][k] = *(const LAS bf16x8*)(lds + PG8_SB(b, h) + boff + n * 2048 + k * 1024); } while (0)
; #define PG8_MMA(ai, bj, At, Bt) do { __builtin_amdgcn_s_setprio(1); _Pragma("unroll") for (int m = 0; m < 4; ++m) _Pragma("unroll") for (int n = 0; n < 2; ++n) _Pragma("unroll") for (int k = 0; k < 2; ++k) \
;     acc[ai][bj][m][n] = __builtin_amdgcn_mfma_f32_16x16x32_bf16(Bt[n][k], At[m][k], acc[ai][bj][m][n], 0, 0, 0); __builtin_amdgcn_s_setprio(0); } while (0)
; #define PG8_WAIT_V(n) asm volatile("s_waitcnt vmcnt(" #n ")" ::: "memory")
; #define PG8_WAIT_L(n) asm volatile("s_waitcnt lgkmcnt(" #n ")" ::: "memory")
; #define PG8_BAR __builtin_amdgcn_s_barrier()
; #define PG8_SCHED __builtin_amdgcn_sched_barrier(0)
; template <class Epi, class Sched = StaticOrder>
; DI void gemm_phase(LAS unsigned char* lds, const Gemm g, const Sched& S, const Epi& E) {
;     ...
;       PG8_LDB(B0, 1, 0); PG8_SCHED; PG8_LDA(At, 1, 0); PG8_STAGE(PG8_SA(0, 1), a2 + hstep, voffA);
;       PG8_WAIT_L(8); PG8_BAR; PG8_WAIT_L(0); PG8_MMA(0, 0, At, B0); PG8_BAR; PG8_SCHED;
;       PG8_LDB(B1, 1, 1); PG8_STAGE(PG8_SB(1, 0), b3, voffB);
;       PG8_BAR; PG8_WAIT_L(0); PG8_MMA(0, 1, At, B1); PG8_BAR;
;       PG8_LDA(At, 1, 1); PG8_STAGE(PG8_SA(1, 0), a3, voffA);
;       PG8_BAR; PG8_WAIT_L(0); PG8_MMA(1, 0, At, B0); PG8_BAR; PG8_SCHED;
;       PG8_STAGE(PG8_SB(1, 1), b3 + hstep, voffB);
;       PG8_WAIT_V(6); PG8_BAR; PG8_MMA(1, 1, At, B1); PG8_BAR;
	s_setprio 0
	s_add_i32 s59, 0, 0x18000
	v_add_u32_e32 v76, s59, v198
	ds_read_b128 v[64:67], v76
	ds_read_b128 v[68:71], v76 offset:1024
	ds_read_b128 v[72:75], v76 offset:2048
	ds_read_b128 v[76:79], v76 offset:3072
	s_add_u32 s50, s50, 0x80000
	s_addc_u32 s51, s51, 0
	s_mov_b32 m0, s66
	ds_read_b128 v[120:123], v202 offset:32768
	ds_read_b128 v[128:131], v202 offset:33792
	ds_read_b128 v[180:183], v202 offset:34816
	ds_read_b128 v[184:187], v202 offset:35840
	ds_read_b128 v[188:191], v202 offset:36864
	ds_read_b128 v[192:195], v202 offset:37888
	ds_read_b128 v[206:209], v202 offset:38912
	ds_read_b128 v[212:215], v202 offset:39936
	global_load_lds_dwordx4 v166, s[50:51]
	s_mov_b32 m0, s67
	s_nop 0
	global_load_lds_dwordx4 v162, s[50:51]
	s_add_i32 s50, 0, 0x1c000
	v_add_u32_e32 v244, s50, v198
	ds_read_b128 v[216:219], v244
	ds_read_b128 v[220:223], v244 offset:1024
	ds_read_b128 v[224:227], v244 offset:2048
	ds_read_b128 v[228:231], v244 offset:3072
	s_waitcnt vmcnt(8)
	s_waitcnt lgkmcnt(4)
	s_setprio 1
	s_barrier
	v_mfma_f32_16x16x32_bf16 v[136:139], v[64:67], v[120:123], v[156:159]
	v_mfma_f32_16x16x32_bf16 v[156:159], v[68:71], v[128:131], v[136:139]
	v_mfma_f32_16x16x32_bf16 v[136:139], v[72:75], v[120:123], v[144:147]
	v_mfma_f32_16x16x32_bf16 v[144:147], v[76:79], v[128:131], v[136:139]
	v_mfma_f32_16x16x32_bf16 v[136:139], v[64:67], v[180:183], v[140:143]
	v_mfma_f32_16x16x32_bf16 v[132:135], v[72:75], v[180:183], v[132:135]
	v_mfma_f32_16x16x32_bf16 v[124:127], v[64:67], v[188:191], v[124:127]
	v_mfma_f32_16x16x32_bf16 v[116:119], v[72:75], v[188:191], v[116:119]
	v_mfma_f32_16x16x32_bf16 v[112:115], v[64:67], v[206:209], v[112:115]
	v_mfma_f32_16x16x32_bf16 v[108:111], v[72:75], v[206:209], v[108:111]
	v_mfma_f32_16x16x32_bf16 v[140:143], v[68:71], v[184:187], v[136:139]
	v_mfma_f32_16x16x32_bf16 v[132:135], v[76:79], v[184:187], v[132:135]
	v_mfma_f32_16x16x32_bf16 v[124:127], v[68:71], v[192:195], v[124:127]
	v_mfma_f32_16x16x32_bf16 v[116:119], v[76:79], v[192:195], v[116:119]
	v_mfma_f32_16x16x32_bf16 v[112:115], v[68:71], v[212:215], v[112:115]
	v_mfma_f32_16x16x32_bf16 v[108:111], v[76:79], v[212:215], v[108:111]
	s_waitcnt lgkmcnt(0)
	v_mfma_f32_16x16x32_bf16 v[80:83], v[224:227], v[120:123], v[80:83]
	v_mfma_f32_16x16x32_bf16 v[136:139], v[216:219], v[120:123], v[152:155]
	v_mfma_f32_16x16x32_bf16 v[148:151], v[228:231], v[128:131], v[80:83]
	v_mfma_f32_16x16x32_bf16 v[80:83], v[216:219], v[180:183], v[84:87]
	v_mfma_f32_16x16x32_bf16 v[152:155], v[220:223], v[128:131], v[136:139]
	v_mfma_f32_16x16x32_bf16 v[136:139], v[220:223], v[184:187], v[80:83]
	v_mfma_f32_16x16x32_bf16 v[80:83], v[224:227], v[180:183], v[88:91]
	v_mfma_f32_16x16x32_bf16 v[128:131], v[228:231], v[184:187], v[80:83]
	v_mfma_f32_16x16x32_bf16 v[80:83], v[216:219], v[188:191], v[92:95]
	v_mfma_f32_16x16x32_bf16 v[120:123], v[220:223], v[192:195], v[80:83]
	v_mfma_f32_16x16x32_bf16 v[80:83], v[224:227], v[188:191], v[104:107]
	v_mfma_f32_16x16x32_bf16 v[104:107], v[228:231], v[192:195], v[80:83]
	v_mfma_f32_16x16x32_bf16 v[80:83], v[216:219], v[206:209], v[100:103]
	v_mfma_f32_16x16x32_bf16 v[100:103], v[220:223], v[212:215], v[80:83]
	v_mfma_f32_16x16x32_bf16 v[80:83], v[224:227], v[206:209], v[96:99]
	v_mfma_f32_16x16x32_bf16 v[96:99], v[228:231], v[212:215], v[80:83]
	s_barrier
	s_setprio 0
	s_add_i32 s51, s59, s62
	s_nop 2
	ds_read_b128 v[80:83], v202 offset:49152
	ds_read_b128 v[84:87], v202 offset:50176
	ds_read_b128 v[88:91], v202 offset:51200
	ds_read_b128 v[92:95], v202 offset:52224
	ds_read_b128 v[180:183], v202 offset:53248
	ds_read_b128 v[184:187], v202 offset:54272
	ds_read_b128 v[188:191], v202 offset:55296
	ds_read_b128 v[192:195], v202 offset:56320
	s_mov_b32 m0, s51
	s_nop 0
	global_load_lds_dwordx4 v164, s[98:99]
	s_add_i32 m0, s51, 0x2000
	s_nop 0
	global_load_lds_dwordx4 v160, s[98:99]
	s_mov_b32 m0, s55
	s_nop 0
	global_load_lds_dwordx4 v166, s[100:101]
	s_mov_b32 m0, s68
	s_nop 0
	global_load_lds_dwordx4 v162, s[100:101]
	s_add_u32 s48, s48, 0x80080
	s_addc_u32 s49, s49, 0
	s_add_i32 s50, s50, s62
	s_add_i32 s58, s58, 2
	s_add_u32 s14, s14, 0x100
	s_addc_u32 s15, s15, 0
	s_add_u32 s52, s52, 0x100
	s_addc_u32 s53, s53, 0
	s_cmp_gt_u32 s58, 29
	s_waitcnt vmcnt(6)
	s_waitcnt lgkmcnt(0)
	s_setprio 1
	s_barrier
	v_mfma_f32_16x16x32_bf16 v[60:63], v[64:67], v[80:83], v[60:63]
	s_mov_b32 m0, s50
	v_mfma_f32_16x16x32_bf16 v[48:51], v[72:75], v[80:83], v[48:51]
	global_load_lds_dwordx4 v164, s[48:49]
	v_mfma_f32_16x16x32_bf16 v[44:47], v[64:67], v[88:91], v[44:47]
	s_bitset1_b32 m0, 13
	v_mfma_f32_16x16x32_bf16 v[36:39], v[72:75], v[88:91], v[36:39]
	global_load_lds_dwordx4 v160, s[48:49]
	v_mfma_f32_16x16x32_bf16 v[28:31], v[64:67], v[180:183], v[28:31]
	v_mfma_f32_16x16x32_bf16 v[20:23], v[72:75], v[180:183], v[20:23]
	v_mfma_f32_16x16x32_bf16 v[16:19], v[64:67], v[188:191], v[16:19]
	v_mfma_f32_16x16x32_bf16 v[12:15], v[72:75], v[188:191], v[12:15]
	v_mfma_f32_16x16x32_bf16 v[60:63], v[68:71], v[84:87], v[60:63]
	v_mfma_f32_16x16x32_bf16 v[48:51], v[76:79], v[84:87], v[48:51]
	v_mfma_f32_16x16x32_bf16 v[44:47], v[68:71], v[92:95], v[44:47]
	v_mfma_f32_16x16x32_bf16 v[36:39], v[76:79], v[92:95], v[36:39]
	v_mfma_f32_16x16x32_bf16 v[28:31], v[68:71], v[184:187], v[28:31]
	v_mfma_f32_16x16x32_bf16 v[20:23], v[76:79], v[184:187], v[20:23]
	v_mfma_f32_16x16x32_bf16 v[16:19], v[68:71], v[192:195], v[16:19]
	v_mfma_f32_16x16x32_bf16 v[12:15], v[76:79], v[192:195], v[12:15]
	v_mfma_f32_16x16x32_bf16 v[56:59], v[216:219], v[80:83], v[56:59]
	v_mfma_f32_16x16x32_bf16 v[52:55], v[224:227], v[80:83], v[52:55]
	v_mfma_f32_16x16x32_bf16 v[40:43], v[216:219], v[88:91], v[40:43]
	v_mfma_f32_16x16x32_bf16 v[32:35], v[224:227], v[88:91], v[32:35]
	v_mfma_f32_16x16x32_bf16 v[24:27], v[216:219], v[180:183], v[24:27]
	v_mfma_f32_16x16x32_bf16 v[8:11], v[224:227], v[180:183], v[8:11]
	v_mfma_f32_16x16x32_bf16 v[4:7], v[216:219], v[188:191], v[4:7]
	v_mfma_f32_16x16x32_bf16 v[0:3], v[224:227], v[188:191], v[0:3]
	v_mfma_f32_16x16x32_bf16 v[56:59], v[220:223], v[84:87], v[56:59]
	v_mfma_f32_16x16x32_bf16 v[52:55], v[228:231], v[84:87], v[52:55]
	v_mfma_f32_16x16x32_bf16 v[40:43], v[220:223], v[92:95], v[40:43]
	v_mfma_f32_16x16x32_bf16 v[32:35], v[228:231], v[92:95], v[32:35]
	v_mfma_f32_16x16x32_bf16 v[24:27], v[220:223], v[184:187], v[24:27]
	v_mfma_f32_16x16x32_bf16 v[8:11], v[228:231], v[184:187], v[8:11]
	v_mfma_f32_16x16x32_bf16 v[4:7], v[220:223], v[192:195], v[4:7]
	v_mfma_f32_16x16x32_bf16 v[0:3], v[228:231], v[192:195], v[0:3]
	s_barrier
; DI float dpp_ror1(float v) { return __int_as_float(__builtin_amdgcn_update_dpp(0, __float_as_int(v), 0x121, 0xf, 0xf, false)); }
; DI float dpp_ror2(float v) { return __int_as_float(__builtin_amdgcn_update_dpp(0, __float_as_int(v), 0x122, 0xf, 0xf, false)); }
; DI float row_rstd(const float* ssq, int row, int fq) {
;   const f32x4 a = *(const f32x4*)(ssq + (size_t)row * 32 + fq * 8), b = *(const f32x4*)(ssq + (size_t)row * 32 + fq * 8 + 4);
;   float sm = ((a[0] + a[1]) + (a[2] + a[3])) + ((b[0] + b[1]) + (b[2] + b[3]));
;   sm += __shfl_xor(sm, 16); sm += __shfl_xor(sm, 32);
;   return rsqrtf(sm * (1.0f / 2048.f) + 1e-6f);
; }
;   DI void operator()(const f32x4 (&acc)[2][2][4][2], const Unit& u, int wr, int wc, int fr, int fq) const {
;     const int col = u.pn * 128 + wc * 32 + 8 * fq;
;     float w0[8], w1[8], w2[8], bb[8];
; #pragma unroll
;     for (int e = 0; e < 8; ++e) { w0[e] = cw[col + e]; w1[e] = cw[5632 + col + e]; w2[e] = cw[2 * 5632 + col + e]; bb[e] = cb[col + e]; }
; #pragma unroll
;     for (int ai = 0; ai < 2; ++ai) {
;       const int row0 = u.pm * BM + ai * HALF + wr * 64, span = row0 >> 6;
;       float rsv[4];
; #pragma unroll
;       for (int m = 0; m < 4; ++m) rsv[m] = row_rstd(ssq, row0 + 16 * m + fr, fq);
;       float p1[8], p2[8];
; #pragma unroll
;       for (int e = 0; e < 8; ++e) { p1[e] = 0.f; p2[e] = 0.f; }
; #pragma unroll
;       for (int m = 0; m < 4; ++m) {
;         float g[8], uu[8], a[8];
;         const float rs = rsv[m];
; #pragma unroll
;         for (int e = 0; e < 4; ++e) { g[e] = acc[ai][0][m][0][e] * rs; g[4 + e] = acc[ai][0][m][1][e] * rs; uu[e] = acc[ai][1][m][0][e] * rs; uu[4 + e] = acc[ai][1][m][1][e] * rs; }
; #pragma unroll
;         for (int e = 0; e < 8; ++e) {
;           const float x1 = dpp_ror1(g[e]), x2 = dpp_ror2(g[e]);
;           const float pr1 = (fr == 0) ? p1[e] : x1, pr2 = (fr < 2) ? p2[e] : x2;
;           a[e] = w2[e] * g[e] + w1[e] * pr1 + w0[e] * pr2 + bb[e];
;           p1[e] = x1; p2[e] = x2;
;         }
	s_setprio 0
	s_cbranch_scc0 .LBB0_1277
	s_lshl_b32 s39, s12, 8
	s_add_i32 s39, s39, s54
	v_or_b32_e32 v190, s39, v179
	v_ashrrev_i32_e32 v191, 31, v190
	v_lshlrev_b64 v[64:65], 7, v[190:191]
	v_or_b32_e32 v188, 16, v190
	v_lshl_add_u64 v[64:65], v[168:169], 0, v[64:65]
	v_ashrrev_i32_e32 v189, 31, v188
	global_load_dwordx4 v[192:195], v[64:65], off
	global_load_dwordx4 v[206:209], v[64:65], off offset:16
	v_lshlrev_b64 v[64:65], 7, v[188:189]
	v_lshl_add_u64 v[64:65], v[168:169], 0, v[64:65]
	global_load_dwordx4 v[212:215], v[64:65], off
	global_load_dwordx4 v[216:219], v[64:65], off offset:16
	v_or_b32_e32 v186, 32, v190
	v_ashrrev_i32_e32 v187, 31, v186
	v_lshlrev_b64 v[64:65], 7, v[186:187]
	v_or_b32_e32 v184, 48, v190
	v_lshl_add_u64 v[64:65], v[168:169], 0, v[64:65]
	v_ashrrev_i32_e32 v185, 31, v184
	global_load_dwordx4 v[220:223], v[64:65], off
	global_load_dwordx4 v[224:227], v[64:65], off offset:16
	v_lshlrev_b64 v[64:65], 7, v[184:185]
	v_lshl_add_u64 v[64:65], v[168:169], 0, v[64:65]
	global_load_dwordx4 v[228:231], v[64:65], off
	global_load_dwordx4 v[232:235], v[64:65], off offset:16
	v_lshl_or_b32 v180, s13, 7, v200
	v_and_b32_e32 v65, 64, v204
	v_xor_b32_e32 v64, 16, v204
	v_ashrrev_i32_e32 v181, 31, v180
	v_add_u32_e32 v65, 64, v65
	v_xor_b32_e32 v66, 32, v204
	v_lshlrev_b64 v[182:183], 2, v[180:181]
	v_cmp_lt_i32_e32 vcc, v64, v65
	v_lshl_add_u64 v[88:89], s[16:17], 0, v[182:183]
	v_lshl_add_u64 v[72:73], s[18:19], 0, v[182:183]
	v_cndmask_b32_e32 v64, v204, v64, vcc
	v_cmp_lt_i32_e32 vcc, v66, v65
	v_lshl_add_u64 v[74:75], v[88:89], 0, s[30:31]
	v_lshl_add_u64 v[76:77], v[88:89], 0, s[34:35]
	v_cndmask_b32_e32 v65, v204, v66, vcc
	v_add_co_u32_e32 v90, vcc, 0x5000, v88
	v_lshlrev_b32_e32 v187, 2, v64
	s_nop 0
	v_addc_co_u32_e32 v91, vcc, 0, v89, vcc
	v_add_co_u32_e32 v92, vcc, 0xb000, v88
	v_lshlrev_b32_e32 v185, 2, v65
	s_nop 0
	v_addc_co_u32_e32 v93, vcc, 0, v89, vcc
	global_load_dwordx4 v[64:67], v[88:89], off offset:16
	global_load_dwordx4 v[80:83], v[88:89], off
	global_load_dwordx4 v[68:71], v[72:73], off offset:16
	global_load_dwordx4 v[84:87], v[72:73], off
	s_nop 0
	global_load_dwordx4 v[72:75], v[74:75], off offset:16
	s_nop 0
	global_load_dwordx4 v[76:79], v[76:77], off offset:16
	s_nop 0
	global_load_dwordx4 v[88:91], v[90:91], off offset:2048
	s_nop 0
	global_load_dwordx4 v[92:95], v[92:93], off
	v_mov_b32_e32 v211, 0
	v_mov_b32_e32 v205, 0
	s_waitcnt vmcnt(0)
	v_mov_b32_e32 v196, v192
	v_mov_b32_e32 v197, v206
	v_mov_b32_e32 v206, v193
	v_mov_b32_e32 v192, v194
	v_mov_b32_e32 v193, v208
	v_mov_b32_e32 v208, v195
	v_pk_add_f32 v[194:195], v[196:197], v[206:207]
	v_pk_add_f32 v[192:193], v[192:193], v[208:209]
	v_mov_b32_e32 v196, v212
	v_mov_b32_e32 v197, v216
	v_mov_b32_e32 v216, v213
	v_mov_b32_e32 v206, v214
	v_mov_b32_e32 v207, v218
	v_mov_b32_e32 v218, v215
	v_pk_add_f32 v[192:193], v[194:195], v[192:193]
	v_pk_add_f32 v[194:195], v[196:197], v[216:217]
	v_pk_add_f32 v[196:197], v[206:207], v[218:219]
	v_mov_b32_e32 v208, v220
	v_pk_add_f32 v[194:195], v[194:195], v[196:197]
	v_mov_b32_e32 v197, v192
	v_mov_b32_e32 v196, v194
	v_mov_b32_e32 v192, v195
	v_pk_add_f32 v[192:193], v[196:197], v[192:193]
	ds_bpermute_b32 v195, v187, v193
	ds_bpermute_b32 v194, v187, v192
	v_mov_b32_e32 v209, v224
	v_mov_b32_e32 v224, v221
	v_mov_b32_e32 v212, v222
	v_mov_b32_e32 v213, v226
	s_waitcnt lgkmcnt(0)
	v_pk_add_f32 v[192:193], v[192:193], v[194:195]
	ds_bpermute_b32 v195, v185, v193
	ds_bpermute_b32 v194, v185, v192
	v_mov_b32_e32 v226, v223
	v_mov_b32_e32 v196, v228
	v_mov_b32_e32 v197, v232
	v_mov_b32_e32 v232, v229
	s_waitcnt lgkmcnt(0)
	v_pk_add_f32 v[192:193], v[192:193], v[194:195]
	v_mov_b32_e32 v206, v230
	v_pk_fma_f32 v[192:193], v[192:193], s[36:37], v[178:179] op_sel_hi:[1,0,0]
	v_mov_b32_e32 v207, v234
	v_mul_f32_e32 v189, 0x4b800000, v193
	v_cmp_gt_f32_e64 s[12:13], s74, v193
	v_mov_b32_e32 v234, v231
	v_pk_add_f32 v[208:209], v[208:209], v[224:225]
	v_cndmask_b32_e64 v189, v193, v189, s[12:13]
	v_rsq_f32_e32 v189, v189
	v_pk_add_f32 v[212:213], v[212:213], v[226:227]
	v_pk_add_f32 v[196:197], v[196:197], v[232:233]
	v_pk_add_f32 v[194:195], v[206:207], v[234:235]
	v_mul_f32_e32 v191, 0x45800000, v189
	v_cndmask_b32_e64 v220, v189, v191, s[12:13]
	v_pk_add_f32 v[208:209], v[208:209], v[212:213]
	v_pk_add_f32 v[194:195], v[196:197], v[194:195]
	v_pk_mul_f32 v[156:157], v[156:157], v[220:221] op_sel_hi:[1,0]
	v_mov_b32_e32 v216, 0
	v_mov_b32_e32 v218, 0
	v_mov_b32_e32 v196, v194
	v_mov_b32_e32 v197, v208
	v_mov_b32_e32 v208, v195
	v_mov_b32_dpp v216, v156 row_ror:1 row_mask:0xf bank_mask:0xf
	v_mov_b32_dpp v218, v157 row_ror:1 row_mask:0xf bank_mask:0xf
	v_pk_add_f32 v[194:195], v[196:197], v[208:209]
	v_cndmask_b32_e64 v207, v218, 0, s[0:1]
	v_cndmask_b32_e64 v206, v216, 0, s[0:1]
	v_pk_mul_f32 v[158:159], v[158:159], v[220:221] op_sel_hi:[1,0]
	v_mov_b32_e32 v212, 0
	v_mov_b32_e32 v214, 0
	ds_bpermute_b32 v197, v187, v195
	ds_bpermute_b32 v196, v187, v194
	v_mov_b32_e32 v215, 0
	v_mov_b32_e32 v217, 0
	v_pk_mul_f32 v[206:207], v[88:89], v[206:207]
	v_mov_b32_dpp v212, v158 row_ror:1 row_mask:0xf bank_mask:0xf
	v_mov_b32_dpp v214, v159 row_ror:1 row_mask:0xf bank_mask:0xf
	v_mov_b32_dpp v215, v156 row_ror:2 row_mask:0xf bank_mask:0xf
	v_mov_b32_dpp v217, v157 row_ror:2 row_mask:0xf bank_mask:0xf
	v_pk_fma_f32 v[156:157], v[92:93], v[156:157], v[206:207]
	v_mov_b32_e32 v213, 0
	v_cndmask_b32_e64 v207, v214, 0, s[0:1]
	v_cndmask_b32_e64 v206, v212, 0, s[0:1]
	v_cndmask_b32_e64 v209, v217, 0, s[4:5]
	v_cndmask_b32_e64 v208, v215, 0, s[4:5]
	v_mov_b32_dpp v211, v158 row_ror:2 row_mask:0xf bank_mask:0xf
	v_mov_b32_dpp v213, v159 row_ror:2 row_mask:0xf bank_mask:0xf
	v_pk_mul_f32 v[206:207], v[90:91], v[206:207]
	v_pk_fma_f32 v[156:157], v[80:81], v[208:209], v[156:157]
	v_cndmask_b32_e64 v209, v213, 0, s[4:5]
	v_cndmask_b32_e64 v208, v211, 0, s[4:5]
	v_pk_fma_f32 v[158:159], v[94:95], v[158:159], v[206:207]
	v_pk_mul_f32 v[144:145], v[144:145], v[220:221] op_sel_hi:[1,0]
	v_pk_fma_f32 v[158:159], v[82:83], v[208:209], v[158:159]
	v_mov_b32_e32 v207, 0
	v_mov_b32_e32 v209, 0
	v_pk_mul_f32 v[146:147], v[146:147], v[220:221] op_sel_hi:[1,0]
	v_mov_b32_e32 v191, 0
	s_waitcnt lgkmcnt(0)
; DI unsigned pack2(float lo, float hi) { f32x2 v = {lo, hi}; bf16v2 r = __builtin_convertvector(v, bf16v2); return __builtin_bit_cast(unsigned, r); }
; DI float silu_f(float x) { return x * sigmoid_f(x); }
; DI float dpp_ror1(float v) { return __int_as_float(__builtin_amdgcn_update_dpp(0, __float_as_int(v), 0x121, 0xf, 0xf, false)); }
; DI float dpp_ror2(float v) { return __int_as_float(__builtin_amdgcn_update_dpp(0, __float_as_int(v), 0x122, 0xf, 0xf, false)); }
;   DI void operator()(const f32x4 (&acc)[2][2][4][2], const Unit& u, int wr, int wc, int fr, int fq) const {
;     ...
;       for (int m = 0; m < 4; ++m) {
;         float g[8], uu[8], a[8];
;         const float rs = rsv[m];
; #pragma unroll
;         for (int e = 0; e < 4; ++e) { g[e] = acc[ai][0][m][0][e] * rs; g[4 + e] = acc[ai][0][m][1][e] * rs; uu[e] = acc[ai][1][m][0][e] * rs; uu[4 + e] = acc[ai][1][m][1][e] * rs; }
; #pragma unroll
;         for (int e = 0; e < 8; ++e) {
;           const float x1 = dpp_ror1(g[e]), x2 = dpp_ror2(g[e]);
;           const float pr1 = (fr == 0) ? p1[e] : x1, pr2 = (fr < 2) ? p2[e] : x2;
;           a[e] = w2[e] * g[e] + w1[e] * pr1 + w0[e] * pr2 + bb[e];
;           p1[e] = x1; p2[e] = x2;
;         }
;         if (m == 0 && fr < 2) {
;           float* ha = headA + (size_t)(span * 2 + fr) * 5632 + col; float* hu = headU + (size_t)(span * 2 + fr) * 5632 + col;
;           *(f32x4*)ha = (f32x4){a[0], a[1], a[2], a[3]}; *(f32x4*)(ha + 4) = (f32x4){a[4], a[5], a[6], a[7]};
;           *(f32x4*)hu = (f32x4){uu[0], uu[1], uu[2], uu[3]}; *(f32x4*)(hu + 4) = (f32x4){uu[4], uu[5], uu[6], uu[7]};
;         } else {
;           u32x4 w;
;           w.x = pack2(silu_f(a[0]) * uu[0], silu_f(a[1]) * uu[1]);
;           w.y = pack2(silu_f(a[2]) * uu[2], silu_f(a[3]) * uu[3]);
;           w.z = pack2(silu_f(a[4]) * uu[4], silu_f(a[5]) * uu[5]);
;           w.w = pack2(silu_f(a[6]) * uu[6], silu_f(a[7]) * uu[7]);
;           *(u32x4*)(H + (size_t)(row0 + 16 * m + fr) * 5632 + col) = w;
;         }
	v_pk_add_f32 v[194:195], v[194:195], v[196:197]
	v_mov_b32_dpp v207, v144 row_ror:1 row_mask:0xf bank_mask:0xf
	v_mov_b32_dpp v209, v145 row_ror:1 row_mask:0xf bank_mask:0xf
	v_mov_b32_dpp v191, v146 row_ror:1 row_mask:0xf bank_mask:0xf
	v_mov_b32_dpp v205, v147 row_ror:1 row_mask:0xf bank_mask:0xf
	ds_bpermute_b32 v197, v185, v195
	ds_bpermute_b32 v196, v185, v194
	v_pk_mul_f32 v[152:153], v[152:153], v[220:221] op_sel_hi:[1,0]
	v_pk_mul_f32 v[148:149], v[148:149], v[220:221] op_sel_hi:[1,0]
	v_pk_mul_f32 v[154:155], v[154:155], v[220:221] op_sel_hi:[1,0]
	v_pk_mul_f32 v[150:151], v[150:151], v[220:221] op_sel_hi:[1,0]
	v_mov_b32_e32 v206, 0
	v_mov_b32_e32 v208, 0
	v_cndmask_b32_e64 v223, v209, 0, s[0:1]
	v_cndmask_b32_e64 v222, v207, 0, s[0:1]
	v_mov_b32_e32 v189, 0
	v_mov_b32_e32 v193, 0
	v_cndmask_b32_e64 v221, v205, 0, s[0:1]
	v_cndmask_b32_e64 v220, v191, 0, s[0:1]
	v_mov_b32_dpp v206, v144 row_ror:2 row_mask:0xf bank_mask:0xf
	v_mov_b32_dpp v208, v145 row_ror:2 row_mask:0xf bank_mask:0xf
	v_pk_mul_f32 v[222:223], v[72:73], v[222:223]
	v_mov_b32_dpp v189, v146 row_ror:2 row_mask:0xf bank_mask:0xf
	v_mov_b32_dpp v193, v147 row_ror:2 row_mask:0xf bank_mask:0xf
	v_pk_mul_f32 v[220:221], v[74:75], v[220:221]
	v_cndmask_b32_e64 v225, v208, 0, s[4:5]
	v_cndmask_b32_e64 v224, v206, 0, s[4:5]
	v_pk_fma_f32 v[144:145], v[76:77], v[144:145], v[222:223]
	v_cndmask_b32_e64 v223, v193, 0, s[4:5]
	v_cndmask_b32_e64 v222, v189, 0, s[4:5]
	v_pk_fma_f32 v[146:147], v[78:79], v[146:147], v[220:221]
	v_pk_fma_f32 v[144:145], v[64:65], v[224:225], v[144:145]
	v_pk_fma_f32 v[146:147], v[66:67], v[222:223], v[146:147]
	v_cmp_gt_f32_e32 vcc, s74, v192
	v_pk_add_f32 v[156:157], v[84:85], v[156:157]
	v_pk_add_f32 v[158:159], v[86:87], v[158:159]
	v_pk_add_f32 v[144:145], v[68:69], v[144:145]
	v_pk_add_f32 v[146:147], v[70:71], v[146:147]
	s_and_saveexec_b64 s[12:13], s[10:11]
	s_xor_b64 s[12:13], exec, s[12:13]
	s_cbranch_execz .LBB0_1280
	v_mul_f32_e32 v219, 0xbfb8aa3b, v156
	v_exp_f32_e32 v219, v219
	v_mul_f32_e32 v220, 0xbfb8aa3b, v157
	v_exp_f32_e32 v220, v220
	v_mul_f32_e32 v222, 0xbfb8aa3b, v159
	v_add_f32_e32 v219, 1.0, v219
	v_exp_f32_e32 v223, v222
	v_add_f32_e32 v221, 1.0, v220
	v_rcp_f32_e32 v220, v219
	v_mul_f32_e32 v219, 0xbfb8aa3b, v158
	v_exp_f32_e32 v219, v219
	v_rcp_f32_e32 v221, v221
	v_add_f32_e32 v219, 1.0, v219
	v_rcp_f32_e32 v222, v219
	v_add_f32_e32 v219, 1.0, v223
	v_rcp_f32_e32 v223, v219
	v_pk_mul_f32 v[156:157], v[156:157], v[220:221]
	s_nop 0
	v_pk_mul_f32 v[152:153], v[152:153], v[156:157]
	v_pk_mul_f32 v[156:157], v[158:159], v[222:223]
	v_cvt_pk_bf16_f32 v152, v152, v153
	v_mul_f32_e32 v153, 0xbfb8aa3b, v144
	v_pk_mul_f32 v[154:155], v[154:155], v[156:157]
	v_exp_f32_e32 v156, v153
	v_mul_f32_e32 v153, 0xbfb8aa3b, v145
	v_exp_f32_e32 v157, v153
	v_cvt_pk_bf16_f32 v153, v154, v155
	v_add_f32_e32 v154, 1.0, v156
	v_mul_f32_e32 v156, 0xbfb8aa3b, v146
	v_add_f32_e32 v155, 1.0, v157
	v_mul_f32_e32 v157, 0xbfb8aa3b, v147
	v_exp_f32_e32 v156, v156
	v_exp_f32_e32 v157, v157
	v_rcp_f32_e32 v154, v154
	v_rcp_f32_e32 v155, v155
	v_add_f32_e32 v156, 1.0, v156
	v_add_f32_e32 v157, 1.0, v157
	v_rcp_f32_e32 v156, v156
	v_rcp_f32_e32 v157, v157
	v_pk_mul_f32 v[144:145], v[144:145], v[154:155]
	s_nop 0
	v_pk_mul_f32 v[144:145], v[148:149], v[144:145]
	s_nop 0
	v_cvt_pk_bf16_f32 v154, v144, v145
	v_pk_mul_f32 v[144:145], v[146:147], v[156:157]
	s_nop 0
	v_pk_mul_f32 v[144:145], v[150:151], v[144:145]
	s_nop 0
	v_cvt_pk_bf16_f32 v155, v144, v145
	v_mov_b64_e32 v[144:145], s[20:21]
	v_mad_i64_i32 v[144:145], s[14:15], v190, s75, v[144:145]
	v_lshl_add_u64 v[144:145], v[180:181], 1, v[144:145]
	global_store_dwordx4 v[144:145], v[152:155], off

; #define PG8_STAGE(bufoff, gbase, voff) do { _Pragma("unroll") for (int _i = 0; _i < 2; ++_i) \
;     __builtin_amdgcn_global_load_lds((const unsigned*)((const char*)(gbase) + (voff)[_i]), (LAS unsigned*)(lds + (bufoff) + ldsw + _i * 8192), 16, 0, 0); } while (0)
; #define PG8_LDA(dst, b, h) do { _Pragma("unroll") for (int m = 0; m < 4; ++m) _Pragma("unroll") for (int k = 0; k < 2; ++k) dst[m][k] = *(const LAS bf16x8*)(lds + PG8_SA(b, h) + aoff + m * 2048 + k * 1024); } while (0)
; #define PG8_LDB(dst, b, h) do { _Pragma("unroll") for (int n = 0; n < 2; ++n) _Pragma("unroll") for (int k = 0; k < 2; ++k) dst[n][k] = *(const LAS bf16x8*)(lds + PG8_SB(b, h) + boff + n * 2048 + k * 1024); } while (0)
; #define PG8_MMA(ai, bj, At, Bt) do { __builtin_amdgcn_s_setprio(1); _Pragma("unroll") for (int m = 0; m < 4; ++m) _Pragma("unroll") for (int n = 0; n < 2; ++n) _Pragma("unroll") for (int k = 0; k < 2; ++k) \
;     acc[ai][bj][m][n] = __builtin_amdgcn_mfma_f32_16x16x32_bf16(Bt[n][k], At[m][k], acc[ai][bj][m][n], 0, 0, 0); __builtin_amdgcn_s_setprio(0); } while (0)
; #define PG8_WAIT_V(n) asm volatile("s_waitcnt vmcnt(" #n ")" ::: "memory")
; #define PG8_WAIT_L(n) asm volatile("s_waitcnt lgkmcnt(" #n ")" ::: "memory")
; #define PG8_BAR __builtin_amdgcn_s_barrier()
; #define PG8_SCHED __builtin_amdgcn_sched_barrier(0)
; template <class Epi, class Sched = StaticOrder>
; DI void gemm_phase(LAS unsigned char* lds, const Gemm g, const Sched& S, const Epi& E) {
;     ...
;       PG8_LDB(B0, 0, 0); PG8_SCHED; PG8_LDA(At, 0, 0); PG8_STAGE(PG8_SA(1, 1), a1 + hstep, voffA);
;       PG8_WAIT_L(8); PG8_BAR; PG8_WAIT_L(0); PG8_MMA(0, 0, At, B0); PG8_BAR; PG8_SCHED;
;       PG8_LDB(B1, 0, 1); PG8_STAGE(PG8_SB(0, 0), b2, voffB);
;       PG8_BAR; PG8_WAIT_L(0); PG8_MMA(0, 1, At, B1); PG8_BAR;
;       PG8_LDA(At, 0, 1); PG8_STAGE(PG8_SA(0, 0), a2, voffA);
;       PG8_BAR; PG8_WAIT_L(0); PG8_MMA(1, 0, At, B0); PG8_BAR; PG8_SCHED;
;       PG8_STAGE(PG8_SB(0, 1), b2 + hstep, voffB);
;       PG8_WAIT_V(6); PG8_BAR; PG8_MMA(1, 1, At, B1); PG8_BAR;
.LBB0_1424:
	ds_read_b128 v[144:147], v159
	ds_read_b128 v[148:151], v159 offset:1024
	ds_read_b128 v[152:155], v159 offset:2048
	ds_read_b128 v[162:165], v159 offset:3072
	s_add_u32 s18, s16, 0xffea0080
	s_addc_u32 s19, s17, -1
	s_cmpk_eq_i32 s47, 0x54
	s_cselect_b32 s21, s3, s19
	s_cselect_b32 s20, s2, s18
	s_cselect_b32 s19, s5, s46
	s_cselect_b32 s18, s4, s45
	s_add_i32 m0, s30, 0xc000
	ds_read_b128 v[166:169], v160
	ds_read_b128 v[170:173], v160 offset:1024
	ds_read_b128 v[174:177], v160 offset:2048
	ds_read_b128 v[178:181], v160 offset:3072
	ds_read_b128 v[182:185], v160 offset:4096
	ds_read_b128 v[186:189], v160 offset:5120
	ds_read_b128 v[190:193], v160 offset:6144
	ds_read_b128 v[194:197], v160 offset:7168
	global_load_lds_dwordx4 v136, s[16:17]
	s_add_i32 m0, s30, 0xe000
	s_nop 0
	global_load_lds_dwordx4 v138, s[16:17]
	ds_read_b128 v[198:201], v161
	ds_read_b128 v[202:205], v161 offset:1024
	ds_read_b128 v[206:209], v161 offset:2048
	ds_read_b128 v[210:213], v161 offset:3072
	s_waitcnt vmcnt(8)
	s_waitcnt lgkmcnt(4)
	s_setprio 1
	s_barrier
	v_mfma_f32_16x16x32_bf16 v[124:127], v[144:147], v[166:169], v[124:127]
	v_mfma_f32_16x16x32_bf16 v[120:123], v[152:155], v[166:169], v[120:123]
	v_mfma_f32_16x16x32_bf16 v[116:119], v[144:147], v[174:177], v[116:119]
	v_mfma_f32_16x16x32_bf16 v[112:115], v[152:155], v[174:177], v[112:115]
	v_mfma_f32_16x16x32_bf16 v[104:107], v[144:147], v[182:185], v[104:107]
	v_mfma_f32_16x16x32_bf16 v[96:99], v[152:155], v[182:185], v[96:99]
	v_mfma_f32_16x16x32_bf16 v[88:91], v[144:147], v[190:193], v[88:91]
	v_mfma_f32_16x16x32_bf16 v[80:83], v[152:155], v[190:193], v[80:83]
	v_mfma_f32_16x16x32_bf16 v[124:127], v[148:151], v[170:173], v[124:127]
	v_mfma_f32_16x16x32_bf16 v[120:123], v[162:165], v[170:173], v[120:123]
	v_mfma_f32_16x16x32_bf16 v[116:119], v[148:151], v[178:181], v[116:119]
	v_mfma_f32_16x16x32_bf16 v[112:115], v[162:165], v[178:181], v[112:115]
	v_mfma_f32_16x16x32_bf16 v[104:107], v[148:151], v[186:189], v[104:107]
	v_mfma_f32_16x16x32_bf16 v[96:99], v[162:165], v[186:189], v[96:99]
	v_mfma_f32_16x16x32_bf16 v[88:91], v[148:151], v[194:197], v[88:91]
	v_mfma_f32_16x16x32_bf16 v[80:83], v[162:165], v[194:197], v[80:83]
	s_waitcnt lgkmcnt(0)
	v_mfma_f32_16x16x32_bf16 v[108:111], v[198:201], v[166:169], v[108:111]
	v_mfma_f32_16x16x32_bf16 v[100:103], v[206:209], v[166:169], v[100:103]
	v_mfma_f32_16x16x32_bf16 v[92:95], v[198:201], v[174:177], v[92:95]
	v_mfma_f32_16x16x32_bf16 v[84:87], v[206:209], v[174:177], v[84:87]
	v_mfma_f32_16x16x32_bf16 v[76:79], v[198:201], v[182:185], v[76:79]
	v_mfma_f32_16x16x32_bf16 v[72:75], v[206:209], v[182:185], v[72:75]
	v_mfma_f32_16x16x32_bf16 v[68:71], v[198:201], v[190:193], v[68:71]
	v_mfma_f32_16x16x32_bf16 v[64:67], v[206:209], v[190:193], v[64:67]
	v_mfma_f32_16x16x32_bf16 v[108:111], v[202:205], v[170:173], v[108:111]
	v_mfma_f32_16x16x32_bf16 v[100:103], v[210:213], v[170:173], v[100:103]
	v_mfma_f32_16x16x32_bf16 v[92:95], v[202:205], v[178:181], v[92:95]
	v_mfma_f32_16x16x32_bf16 v[84:87], v[210:213], v[178:181], v[84:87]
	v_mfma_f32_16x16x32_bf16 v[76:79], v[202:205], v[186:189], v[76:79]
	v_mfma_f32_16x16x32_bf16 v[72:75], v[210:213], v[186:189], v[72:75]
	v_mfma_f32_16x16x32_bf16 v[68:71], v[202:205], v[194:197], v[68:71]
	v_mfma_f32_16x16x32_bf16 v[64:67], v[210:213], v[194:197], v[64:67]
	s_barrier
	s_setprio 0
	s_add_i32 s48, s39, s28
	s_add_u32 s98, s18, 0x80
	s_addc_u32 s99, s19, 0
	s_add_u32 s100, s20, 0x80
	s_addc_u32 s101, s21, 0
	ds_read_b128 v[166:169], v160 offset:16384
	ds_read_b128 v[170:173], v160 offset:17408
	ds_read_b128 v[174:177], v160 offset:18432
	ds_read_b128 v[178:181], v160 offset:19456
	ds_read_b128 v[182:185], v160 offset:20480
	ds_read_b128 v[186:189], v160 offset:21504
	ds_read_b128 v[190:193], v160 offset:22528
	ds_read_b128 v[194:197], v160 offset:23552
	s_mov_b32 m0, s48
	s_nop 0
	global_load_lds_dwordx4 v132, s[18:19]
	s_add_i32 m0, s48, 0x2000
	s_nop 0
	global_load_lds_dwordx4 v128, s[18:19]
	s_mov_b32 m0, s30
	s_nop 0
	global_load_lds_dwordx4 v134, s[20:21]
	s_mov_b32 m0, s31
	s_nop 0
	global_load_lds_dwordx4 v130, s[20:21]
	s_add_u32 s48, s18, 0x160000
	s_addc_u32 s49, s19, 0
	s_add_i32 s50, s40, s28
	s_waitcnt vmcnt(6)
	s_waitcnt lgkmcnt(0)
	s_setprio 1
	s_barrier
	v_mfma_f32_16x16x32_bf16 v[60:63], v[144:147], v[166:169], v[60:63]
	s_mov_b32 m0, s50
	v_mfma_f32_16x16x32_bf16 v[56:59], v[152:155], v[166:169], v[56:59]
	global_load_lds_dwordx4 v132, s[48:49]
	v_mfma_f32_16x16x32_bf16 v[52:55], v[144:147], v[174:177], v[52:55]
	s_bitset1_b32 m0, 13
	v_mfma_f32_16x16x32_bf16 v[44:47], v[152:155], v[174:177], v[44:47]
	global_load_lds_dwordx4 v128, s[48:49]
	v_mfma_f32_16x16x32_bf16 v[36:39], v[144:147], v[182:185], v[36:39]
	v_mfma_f32_16x16x32_bf16 v[28:31], v[152:155], v[182:185], v[28:31]
	v_mfma_f32_16x16x32_bf16 v[20:23], v[144:147], v[190:193], v[20:23]
	v_mfma_f32_16x16x32_bf16 v[12:15], v[152:155], v[190:193], v[12:15]
	v_mfma_f32_16x16x32_bf16 v[60:63], v[148:151], v[170:173], v[60:63]
	v_mfma_f32_16x16x32_bf16 v[56:59], v[162:165], v[170:173], v[56:59]
	v_mfma_f32_16x16x32_bf16 v[52:55], v[148:151], v[178:181], v[52:55]
	v_mfma_f32_16x16x32_bf16 v[44:47], v[162:165], v[178:181], v[44:47]
	v_mfma_f32_16x16x32_bf16 v[36:39], v[148:151], v[186:189], v[36:39]
	v_mfma_f32_16x16x32_bf16 v[28:31], v[162:165], v[186:189], v[28:31]
	v_mfma_f32_16x16x32_bf16 v[20:23], v[148:151], v[194:197], v[20:23]
	v_mfma_f32_16x16x32_bf16 v[12:15], v[162:165], v[194:197], v[12:15]
	v_mfma_f32_16x16x32_bf16 v[48:51], v[198:201], v[166:169], v[48:51]
	v_mfma_f32_16x16x32_bf16 v[40:43], v[206:209], v[166:169], v[40:43]
	v_mfma_f32_16x16x32_bf16 v[32:35], v[198:201], v[174:177], v[32:35]
	v_mfma_f32_16x16x32_bf16 v[24:27], v[206:209], v[174:177], v[24:27]
	v_mfma_f32_16x16x32_bf16 v[16:19], v[198:201], v[182:185], v[16:19]
	v_mfma_f32_16x16x32_bf16 v[8:11], v[206:209], v[182:185], v[8:11]
	v_mfma_f32_16x16x32_bf16 v[4:7], v[198:201], v[190:193], v[4:7]
	v_mfma_f32_16x16x32_bf16 v[0:3], v[206:209], v[190:193], v[0:3]
	v_mfma_f32_16x16x32_bf16 v[48:51], v[202:205], v[170:173], v[48:51]
	v_mfma_f32_16x16x32_bf16 v[40:43], v[210:213], v[170:173], v[40:43]
	v_mfma_f32_16x16x32_bf16 v[32:35], v[202:205], v[178:181], v[32:35]
	v_mfma_f32_16x16x32_bf16 v[24:27], v[210:213], v[178:181], v[24:27]
	v_mfma_f32_16x16x32_bf16 v[16:19], v[202:205], v[186:189], v[16:19]
	v_mfma_f32_16x16x32_bf16 v[8:11], v[210:213], v[186:189], v[8:11]
	v_mfma_f32_16x16x32_bf16 v[4:7], v[202:205], v[194:197], v[4:7]
	v_mfma_f32_16x16x32_bf16 v[0:3], v[210:213], v[194:197], v[0:3]
	s_barrier
; #define PG8_STAGE(bufoff, gbase, voff) do { _Pragma("unroll") for (int _i = 0; _i < 2; ++_i) \
;     __builtin_amdgcn_global_load_lds((const unsigned*)((const char*)(gbase) + (voff)[_i]), (LAS unsigned*)(lds + (bufoff) + ldsw + _i * 8192), 16, 0, 0); } while (0)
; #define PG8_LDA(dst, b, h) do { _Pragma("unroll") for (int m = 0; m < 4; ++m) _Pragma("unroll") for (int k = 0; k < 2; ++k) dst[m][k] = *(const LAS bf16x8*)(lds + PG8_SA(b, h) + aoff + m * 2048 + k * 1024); } while (0)
; #define PG8_LDB(dst, b, h) do { _Pragma("unroll") for (int n = 0; n < 2; ++n) _Pragma("unroll") for (int k = 0; k < 2; ++k) dst[n][k] = *(const LAS bf16x8*)(lds + PG8_SB(b, h) + boff + n * 2048 + k * 1024); } while (0)
; #define PG8_MMA(ai, bj, At, Bt) do { __builtin_amdgcn_s_setprio(1); _Pragma("unroll") for (int m = 0; m < 4; ++m) _Pragma("unroll") for (int n = 0; n < 2; ++n) _Pragma("unroll") for (int k = 0; k < 2; ++k) \
;     acc[ai][bj][m][n] = __builtin_amdgcn_mfma_f32_16x16x32_bf16(Bt[n][k], At[m][k], acc[ai][bj][m][n], 0, 0, 0); __builtin_amdgcn_s_setprio(0); } while (0)
; #define PG8_WAIT_V(n) asm volatile("s_waitcnt vmcnt(" #n ")" ::: "memory")
; #define PG8_WAIT_L(n) asm volatile("s_waitcnt lgkmcnt(" #n ")" ::: "memory")
; #define PG8_BAR __builtin_amdgcn_s_barrier()
; #define PG8_SCHED __builtin_amdgcn_sched_barrier(0)
; template <class Epi, class Sched = StaticOrder>
; DI void gemm_phase(LAS unsigned char* lds, const Gemm g, const Sched& S, const Epi& E) {
;     ...
;       PG8_LDB(B0, 1, 0); PG8_SCHED; PG8_LDA(At, 1, 0); PG8_STAGE(PG8_SA(0, 1), a2 + hstep, voffA);
;       PG8_WAIT_L(8); PG8_BAR; PG8_WAIT_L(0); PG8_MMA(0, 0, At, B0); PG8_BAR; PG8_SCHED;
;       PG8_LDB(B1, 1, 1); PG8_STAGE(PG8_SB(1, 0), b3, voffB);
;       PG8_BAR; PG8_WAIT_L(0); PG8_MMA(0, 1, At, B1); PG8_BAR;
;       PG8_LDA(At, 1, 1); PG8_STAGE(PG8_SA(1, 0), a3, voffA);
;       PG8_BAR; PG8_WAIT_L(0); PG8_MMA(1, 0, At, B0); PG8_BAR; PG8_SCHED;
;       PG8_STAGE(PG8_SB(1, 1), b3 + hstep, voffB);
;       PG8_WAIT_V(6); PG8_BAR; PG8_MMA(1, 1, At, B1); PG8_BAR;
	s_setprio 0
	s_add_i32 s48, 0, 0x18000
	v_add_u32_e32 v162, s48, v157
	ds_read_b128 v[144:147], v162
	ds_read_b128 v[148:151], v162 offset:1024
	ds_read_b128 v[152:155], v162 offset:2048
	ds_read_b128 v[162:165], v162 offset:3072
	s_add_u32 s20, s20, 0x160000
	s_addc_u32 s21, s21, 0
	s_mov_b32 m0, s33
	ds_read_b128 v[166:169], v160 offset:32768
	ds_read_b128 v[170:173], v160 offset:33792
	ds_read_b128 v[174:177], v160 offset:34816
	ds_read_b128 v[178:181], v160 offset:35840
	ds_read_b128 v[182:185], v160 offset:36864
	ds_read_b128 v[186:189], v160 offset:37888
	ds_read_b128 v[190:193], v160 offset:38912
	ds_read_b128 v[194:197], v160 offset:39936
	global_load_lds_dwordx4 v134, s[20:21]
	s_mov_b32 m0, s34
	s_nop 0
	global_load_lds_dwordx4 v130, s[20:21]
	s_add_i32 s20, 0, 0x1c000
	v_add_u32_e32 v210, s20, v157
	ds_read_b128 v[198:201], v210
	ds_read_b128 v[202:205], v210 offset:1024
	ds_read_b128 v[206:209], v210 offset:2048
	ds_read_b128 v[210:213], v210 offset:3072
	s_waitcnt vmcnt(8)
	s_waitcnt lgkmcnt(4)
	s_setprio 1
	s_barrier
	v_mfma_f32_16x16x32_bf16 v[124:127], v[144:147], v[166:169], v[124:127]
	v_mfma_f32_16x16x32_bf16 v[120:123], v[152:155], v[166:169], v[120:123]
	v_mfma_f32_16x16x32_bf16 v[116:119], v[144:147], v[174:177], v[116:119]
	v_mfma_f32_16x16x32_bf16 v[112:115], v[152:155], v[174:177], v[112:115]
	v_mfma_f32_16x16x32_bf16 v[104:107], v[144:147], v[182:185], v[104:107]
	v_mfma_f32_16x16x32_bf16 v[96:99], v[152:155], v[182:185], v[96:99]
	v_mfma_f32_16x16x32_bf16 v[88:91], v[144:147], v[190:193], v[88:91]
	v_mfma_f32_16x16x32_bf16 v[80:83], v[152:155], v[190:193], v[80:83]
	v_mfma_f32_16x16x32_bf16 v[124:127], v[148:151], v[170:173], v[124:127]
	v_mfma_f32_16x16x32_bf16 v[120:123], v[162:165], v[170:173], v[120:123]
	v_mfma_f32_16x16x32_bf16 v[116:119], v[148:151], v[178:181], v[116:119]
	v_mfma_f32_16x16x32_bf16 v[112:115], v[162:165], v[178:181], v[112:115]
	v_mfma_f32_16x16x32_bf16 v[104:107], v[148:151], v[186:189], v[104:107]
	v_mfma_f32_16x16x32_bf16 v[96:99], v[162:165], v[186:189], v[96:99]
	v_mfma_f32_16x16x32_bf16 v[88:91], v[148:151], v[194:197], v[88:91]
	v_mfma_f32_16x16x32_bf16 v[80:83], v[162:165], v[194:197], v[80:83]
	s_waitcnt lgkmcnt(0)
	v_mfma_f32_16x16x32_bf16 v[108:111], v[198:201], v[166:169], v[108:111]
	v_mfma_f32_16x16x32_bf16 v[100:103], v[206:209], v[166:169], v[100:103]
	v_mfma_f32_16x16x32_bf16 v[92:95], v[198:201], v[174:177], v[92:95]
	v_mfma_f32_16x16x32_bf16 v[84:87], v[206:209], v[174:177], v[84:87]
	v_mfma_f32_16x16x32_bf16 v[76:79], v[198:201], v[182:185], v[76:79]
	v_mfma_f32_16x16x32_bf16 v[72:75], v[206:209], v[182:185], v[72:75]
	v_mfma_f32_16x16x32_bf16 v[68:71], v[198:201], v[190:193], v[68:71]
	v_mfma_f32_16x16x32_bf16 v[64:67], v[206:209], v[190:193], v[64:67]
	v_mfma_f32_16x16x32_bf16 v[108:111], v[202:205], v[170:173], v[108:111]
	v_mfma_f32_16x16x32_bf16 v[100:103], v[210:213], v[170:173], v[100:103]
	v_mfma_f32_16x16x32_bf16 v[92:95], v[202:205], v[178:181], v[92:95]
	v_mfma_f32_16x16x32_bf16 v[84:87], v[210:213], v[178:181], v[84:87]
	v_mfma_f32_16x16x32_bf16 v[76:79], v[202:205], v[186:189], v[76:79]
	v_mfma_f32_16x16x32_bf16 v[72:75], v[210:213], v[186:189], v[72:75]
	v_mfma_f32_16x16x32_bf16 v[68:71], v[202:205], v[194:197], v[68:71]
	v_mfma_f32_16x16x32_bf16 v[64:67], v[210:213], v[194:197], v[64:67]
	s_barrier
	s_setprio 0
	s_add_i32 s21, s48, s28
	ds_read_b128 v[166:169], v160 offset:49152
	ds_read_b128 v[170:173], v160 offset:50176
	ds_read_b128 v[174:177], v160 offset:51200
	ds_read_b128 v[178:181], v160 offset:52224
	ds_read_b128 v[182:185], v160 offset:53248
	ds_read_b128 v[186:189], v160 offset:54272
	ds_read_b128 v[190:193], v160 offset:55296
	ds_read_b128 v[194:197], v160 offset:56320
	s_mov_b32 m0, s21
	s_nop 0
	global_load_lds_dwordx4 v132, s[98:99]
	s_add_i32 m0, s21, 0x2000
	s_nop 0
	global_load_lds_dwordx4 v128, s[98:99]
	s_mov_b32 m0, s35
	s_nop 0
	global_load_lds_dwordx4 v134, s[100:101]
	s_mov_b32 m0, s36
	s_nop 0
	global_load_lds_dwordx4 v130, s[100:101]
	s_add_u32 s18, s18, 0x160080
	s_addc_u32 s19, s19, 0
	s_add_i32 s20, s20, s28
	s_add_i32 s47, s47, 2
	s_add_u32 s16, s16, 0x100
	s_addc_u32 s17, s17, 0
	s_add_u32 s45, s45, 0x100
	s_addc_u32 s46, s46, 0
	s_cmpk_gt_u32 s47, 0x55
	s_waitcnt vmcnt(6)
	s_waitcnt lgkmcnt(0)
	s_setprio 1
	s_barrier
	v_mfma_f32_16x16x32_bf16 v[60:63], v[144:147], v[166:169], v[60:63]
	s_mov_b32 m0, s20
	v_mfma_f32_16x16x32_bf16 v[56:59], v[152:155], v[166:169], v[56:59]
	global_load_lds_dwordx4 v132, s[18:19]
	v_mfma_f32_16x16x32_bf16 v[52:55], v[144:147], v[174:177], v[52:55]
	s_bitset1_b32 m0, 13
	v_mfma_f32_16x16x32_bf16 v[44:47], v[152:155], v[174:177], v[44:47]
	global_load_lds_dwordx4 v128, s[18:19]
	v_mfma_f32_16x16x32_bf16 v[36:39], v[144:147], v[182:185], v[36:39]
	v_mfma_f32_16x16x32_bf16 v[28:31], v[152:155], v[182:185], v[28:31]
	v_mfma_f32_16x16x32_bf16 v[20:23], v[144:147], v[190:193], v[20:23]
	v_mfma_f32_16x16x32_bf16 v[12:15], v[152:155], v[190:193], v[12:15]
	v_mfma_f32_16x16x32_bf16 v[60:63], v[148:151], v[170:173], v[60:63]
	v_mfma_f32_16x16x32_bf16 v[56:59], v[162:165], v[170:173], v[56:59]
	v_mfma_f32_16x16x32_bf16 v[52:55], v[148:151], v[178:181], v[52:55]
	v_mfma_f32_16x16x32_bf16 v[44:47], v[162:165], v[178:181], v[44:47]
	v_mfma_f32_16x16x32_bf16 v[36:39], v[148:151], v[186:189], v[36:39]
	v_mfma_f32_16x16x32_bf16 v[28:31], v[162:165], v[186:189], v[28:31]
	v_mfma_f32_16x16x32_bf16 v[20:23], v[148:151], v[194:197], v[20:23]
	v_mfma_f32_16x16x32_bf16 v[12:15], v[162:165], v[194:197], v[12:15]
	v_mfma_f32_16x16x32_bf16 v[48:51], v[198:201], v[166:169], v[48:51]
	v_mfma_f32_16x16x32_bf16 v[40:43], v[206:209], v[166:169], v[40:43]
	v_mfma_f32_16x16x32_bf16 v[32:35], v[198:201], v[174:177], v[32:35]
	v_mfma_f32_16x16x32_bf16 v[24:27], v[206:209], v[174:177], v[24:27]
	v_mfma_f32_16x16x32_bf16 v[16:19], v[198:201], v[182:185], v[16:19]
	v_mfma_f32_16x16x32_bf16 v[8:11], v[206:209], v[182:185], v[8:11]
	v_mfma_f32_16x16x32_bf16 v[4:7], v[198:201], v[190:193], v[4:7]
	v_mfma_f32_16x16x32_bf16 v[0:3], v[206:209], v[190:193], v[0:3]
	v_mfma_f32_16x16x32_bf16 v[48:51], v[202:205], v[170:173], v[48:51]
	v_mfma_f32_16x16x32_bf16 v[40:43], v[210:213], v[170:173], v[40:43]
	v_mfma_f32_16x16x32_bf16 v[32:35], v[202:205], v[178:181], v[32:35]
	v_mfma_f32_16x16x32_bf16 v[24:27], v[210:213], v[178:181], v[24:27]
	v_mfma_f32_16x16x32_bf16 v[16:19], v[202:205], v[186:189], v[16:19]
	v_mfma_f32_16x16x32_bf16 v[8:11], v[210:213], v[186:189], v[8:11]
	v_mfma_f32_16x16x32_bf16 v[4:7], v[202:205], v[194:197], v[4:7]
	v_mfma_f32_16x16x32_bf16 v[0:3], v[210:213], v[194:197], v[0:3]
	s_barrier
;   DI void operator()(const f32x4 (&acc)[2][2][4][2], const Unit& u, int wr, int wc, int fr, int fq) const {
;     const int row0 = u.pm * BM + wr * 64 + fr, col0 = u.pn * BM + wc * 32 + 8 * fq;
; #pragma unroll
;     for (int ai = 0; ai < 2; ++ai) {
;       f32x4 bv[4][2][2];
; #pragma unroll
;       for (int m = 0; m < 4; ++m)
; #pragma unroll
;         for (int bj = 0; bj < 2; ++bj) {
;           const float* bp = base + (size_t)(row0 + ai * HALF + m * 16) * 2048 + col0 + bj * HALF;
;           bv[m][bj][0] = *(const f32x4*)bp; bv[m][bj][1] = *(const f32x4*)(bp + 4);
;         }
; #pragma unroll
;       for (int m = 0; m < 4; ++m) {
;         const int row = row0 + ai * HALF + m * 16;
;         const size_t off = (size_t)row * 2048 + col0;
;         float ss = 0.f;
; #pragma unroll
;         for (int bj = 0; bj < 2; ++bj) {
;           const f32x4 v0 = acc[ai][bj][m][0] + bv[m][bj][0], v1 = acc[ai][bj][m][1] + bv[m][bj][1];
;           *(f32x4*)(C + off + bj * HALF) = v0; *(f32x4*)(C + off + bj * HALF + 4) = v1;
	s_setprio 0
	s_cbranch_scc0 .LBB0_1424
	v_lshl_or_b32 v144, s44, 8, v158
	v_lshl_add_u32 v154, s43, 8, v156
	v_ashrrev_i32_e32 v145, 31, v144
	v_lshlrev_b64 v[144:145], 2, v[144:145]
	v_ashrrev_i32_e32 v155, 31, v154
	v_lshl_add_u64 v[146:147], s[54:55], 0, v[144:145]
	v_lshlrev_b64 v[148:149], 13, v[154:155]
	v_or_b32_e32 v174, 16, v154
	v_lshl_add_u64 v[170:171], v[146:147], 0, v[148:149]
	v_ashrrev_i32_e32 v175, 31, v174
	global_load_dwordx4 v[150:153], v[170:171], off offset:16
	global_load_dwordx4 v[162:165], v[170:171], off
	global_load_dwordx4 v[166:169], v[170:171], off offset:528
	s_nop 0
	global_load_dwordx4 v[170:173], v[170:171], off offset:512
	v_lshlrev_b64 v[222:223], 13, v[174:175]
	v_or_b32_e32 v190, 32, v154
	v_lshl_add_u64 v[186:187], v[146:147], 0, v[222:223]
	v_ashrrev_i32_e32 v191, 31, v190
	global_load_dwordx4 v[174:177], v[186:187], off offset:16
	global_load_dwordx4 v[178:181], v[186:187], off
	global_load_dwordx4 v[182:185], v[186:187], off offset:528
	s_nop 0
	global_load_dwordx4 v[186:189], v[186:187], off offset:512
	v_lshlrev_b64 v[224:225], 13, v[190:191]
	v_or_b32_e32 v154, 48, v154
	v_lshl_add_u64 v[202:203], v[146:147], 0, v[224:225]
	v_ashrrev_i32_e32 v155, 31, v154
	global_load_dwordx4 v[190:193], v[202:203], off offset:16
	global_load_dwordx4 v[194:197], v[202:203], off
	global_load_dwordx4 v[198:201], v[202:203], off offset:528
	s_nop 0
	global_load_dwordx4 v[202:205], v[202:203], off offset:512
	v_lshlrev_b64 v[154:155], 13, v[154:155]
	v_lshl_add_u64 v[218:219], v[146:147], 0, v[154:155]
	global_load_dwordx4 v[206:209], v[218:219], off offset:16
	global_load_dwordx4 v[210:213], v[218:219], off
	global_load_dwordx4 v[214:217], v[218:219], off offset:528
	s_nop 0
	global_load_dwordx4 v[218:221], v[218:219], off offset:512
	s_and_b64 vcc, exec, s[0:1]
	s_mov_b32 s44, s41
	s_mov_b32 s43, s42
	s_mov_b64 s[18:19], s[4:5]
	s_mov_b64 s[16:17], s[2:3]
	s_waitcnt vmcnt(0)
	v_pk_add_f32 v[120:121], v[120:121], v[150:151]
	v_lshl_add_u64 v[150:151], s[54:55], 0, v[148:149]
	v_pk_add_f32 v[126:127], v[126:127], v[164:165]
	v_pk_add_f32 v[124:125], v[124:125], v[162:163]
	v_lshl_add_u64 v[150:151], v[150:151], 0, v[144:145]
	v_pk_add_f32 v[110:111], v[110:111], v[172:173]
	v_pk_add_f32 v[108:109], v[108:109], v[170:171]
	v_pk_add_f32 v[122:123], v[122:123], v[152:153]
	global_store_dwordx4 v[150:151], v[124:127], off
	global_store_dwordx4 v[150:151], v[120:123], off offset:16
	v_pk_add_f32 v[102:103], v[102:103], v[168:169]
	v_pk_add_f32 v[100:101], v[100:101], v[166:167]
	global_store_dwordx4 v[150:151], v[108:111], off offset:512
	global_store_dwordx4 v[150:151], v[100:103], off offset:528
	v_pk_add_f32 v[94:95], v[94:95], v[188:189]
	v_pk_add_f32 v[108:109], v[112:113], v[174:175]
	v_lshl_add_u64 v[112:113], s[54:55], 0, v[222:223]
	v_pk_add_f32 v[102:103], v[118:119], v[180:181]
	v_pk_add_f32 v[100:101], v[116:117], v[178:179]
	v_lshl_add_u64 v[112:113], v[112:113], 0, v[144:145]
	v_pk_add_f32 v[92:93], v[92:93], v[186:187]
	v_pk_add_f32 v[110:111], v[114:115], v[176:177]
	global_store_dwordx4 v[112:113], v[100:103], off
	global_store_dwordx4 v[112:113], v[108:111], off offset:16
	v_pk_add_f32 v[86:87], v[86:87], v[184:185]
	v_pk_add_f32 v[84:85], v[84:85], v[182:183]
	global_store_dwordx4 v[112:113], v[92:95], off offset:512
	global_store_dwordx4 v[112:113], v[84:87], off offset:528
	v_pk_add_f32 v[78:79], v[78:79], v[204:205]
	v_pk_add_f32 v[92:93], v[96:97], v[190:191]
	v_lshl_add_u64 v[96:97], s[54:55], 0, v[224:225]
	v_pk_add_f32 v[86:87], v[106:107], v[196:197]
	v_pk_add_f32 v[84:85], v[104:105], v[194:195]
	v_lshl_add_u64 v[96:97], v[96:97], 0, v[144:145]
	v_pk_add_f32 v[76:77], v[76:77], v[202:203]
	v_pk_add_f32 v[94:95], v[98:99], v[192:193]
	global_store_dwordx4 v[96:97], v[84:87], off
	global_store_dwordx4 v[96:97], v[92:95], off offset:16
	v_pk_add_f32 v[74:75], v[74:75], v[200:201]
	v_pk_add_f32 v[72:73], v[72:73], v[198:199]
	global_store_dwordx4 v[96:97], v[76:79], off offset:512
	global_store_dwordx4 v[96:97], v[72:75], off offset:528
	v_pk_add_f32 v[70:71], v[70:71], v[220:221]
	v_pk_add_f32 v[76:77], v[80:81], v[206:207]
	v_lshl_add_u64 v[80:81], s[54:55], 0, v[154:155]
	v_pk_add_f32 v[74:75], v[90:91], v[212:213]
	v_pk_add_f32 v[72:73], v[88:89], v[210:211]
	v_lshl_add_u64 v[80:81], v[80:81], 0, v[144:145]
	v_pk_add_f32 v[68:69], v[68:69], v[218:219]
	v_pk_add_f32 v[64:65], v[64:65], v[214:215]
	v_lshl_add_u64 v[154:155], v[148:149], 0, s[10:11]
	v_pk_add_f32 v[78:79], v[82:83], v[208:209]
	global_store_dwordx4 v[80:81], v[72:75], off
	global_store_dwordx4 v[80:81], v[76:79], off offset:16
	v_pk_add_f32 v[66:67], v[66:67], v[216:217]
	global_store_dwordx4 v[80:81], v[68:71], off offset:512
	global_store_dwordx4 v[80:81], v[64:67], off offset:528
	v_lshl_add_u64 v[152:153], v[148:149], 0, s[12:13]
	v_lshl_add_u64 v[150:151], v[148:149], 0, s[14:15]
	v_lshl_add_u64 v[64:65], v[146:147], 0, v[154:155]
	global_load_dwordx4 v[108:111], v[64:65], off offset:16
	global_load_dwordx4 v[120:123], v[64:65], off
	global_load_dwordx4 v[92:95], v[64:65], off offset:528
	global_load_dwordx4 v[100:103], v[64:65], off offset:512
	v_lshl_add_u64 v[64:65], v[146:147], 0, v[152:153]
	global_load_dwordx4 v[88:91], v[64:65], off offset:16
	global_load_dwordx4 v[96:99], v[64:65], off
	global_load_dwordx4 v[76:79], v[64:65], off offset:528
	global_load_dwordx4 v[84:87], v[64:65], off offset:512
	v_lshl_add_u64 v[68:69], v[146:147], 0, v[150:151]
	global_load_dwordx4 v[72:75], v[68:69], off offset:16
	global_load_dwordx4 v[80:83], v[68:69], off
	global_load_dwordx4 v[64:67], v[68:69], off offset:528
	s_nop 0
	global_load_dwordx4 v[68:71], v[68:69], off offset:512
	v_lshl_add_u64 v[148:149], v[148:149], 0, s[6:7]
	v_lshl_add_u64 v[112:113], v[146:147], 0, v[148:149]
	global_load_dwordx4 v[116:119], v[112:113], off offset:16
	global_load_dwordx4 v[124:127], v[112:113], off
	global_load_dwordx4 v[104:107], v[112:113], off offset:528
	s_nop 0
	global_load_dwordx4 v[112:115], v[112:113], off offset:512
	s_waitcnt vmcnt(0)
; #define PG8_WAIT_V(n) asm volatile("s_waitcnt vmcnt(" #n ")" ::: "memory")
; #define PG8_BAR __builtin_amdgcn_s_barrier()
;   DI void operator()(const f32x4 (&acc)[2][2][4][2], const Unit& u, int wr, int wc, int fr, int fq) const {
;     ...
;       for (int m = 0; m < 4; ++m) {
;         const int row = row0 + ai * HALF + m * 16;
;         const size_t off = (size_t)row * 2048 + col0;
;         float ss = 0.f;
; #pragma unroll
;         for (int bj = 0; bj < 2; ++bj) {
;           const f32x4 v0 = acc[ai][bj][m][0] + bv[m][bj][0], v1 = acc[ai][bj][m][1] + bv[m][bj][1];
;           *(f32x4*)(C + off + bj * HALF) = v0; *(f32x4*)(C + off + bj * HALF + 4) = v1;
; template <class Epi, class Sched = StaticOrder>
; DI void gemm_phase(LAS unsigned char* lds, const Gemm g, const Sched& S, const Epi& E) {
;     ...
;     E(acc, cur, wr, wc, fr, fq);
;     if (!has_next) break;
; #pragma unroll
;     for (int a = 0; a < 2; ++a)
; #pragma unroll
;       for (int b = 0; b < 2; ++b)
; #pragma unroll
;         for (int m = 0; m < 4; ++m)
; #pragma unroll
;           for (int n = 0; n < 2; ++n) acc[a][b][m][n] = (f32x4){0.f, 0.f, 0.f, 0.f};
;     cur = nxt; cA = nA; cB = nB; ++ui;
;   }
;   PG8_WAIT_V(0);
;   if (wr == 0) PG8_BAR;
;   PG8_BAR;
	v_pk_add_f32 v[56:57], v[56:57], v[108:109]
	v_lshl_add_u64 v[108:109], s[54:55], 0, v[154:155]
	v_pk_add_f32 v[62:63], v[62:63], v[122:123]
	v_pk_add_f32 v[60:61], v[60:61], v[120:121]
	v_lshl_add_u64 v[108:109], v[108:109], 0, v[144:145]
	v_pk_add_f32 v[50:51], v[50:51], v[102:103]
	v_pk_add_f32 v[48:49], v[48:49], v[100:101]
	v_pk_add_f32 v[58:59], v[58:59], v[110:111]
	global_store_dwordx4 v[108:109], v[60:63], off
	global_store_dwordx4 v[108:109], v[56:59], off offset:16
	v_pk_add_f32 v[42:43], v[42:43], v[94:95]
	v_pk_add_f32 v[40:41], v[40:41], v[92:93]
	global_store_dwordx4 v[108:109], v[48:51], off offset:512
	global_store_dwordx4 v[108:109], v[40:43], off offset:528
	v_pk_add_f32 v[34:35], v[34:35], v[86:87]
	v_lshl_add_u64 v[48:49], s[54:55], 0, v[152:153]
	v_pk_add_f32 v[42:43], v[54:55], v[98:99]
	v_pk_add_f32 v[40:41], v[52:53], v[96:97]
	v_lshl_add_u64 v[48:49], v[48:49], 0, v[144:145]
	v_pk_add_f32 v[32:33], v[32:33], v[84:85]
	v_pk_add_f32 v[46:47], v[46:47], v[90:91]
	v_pk_add_f32 v[44:45], v[44:45], v[88:89]
	global_store_dwordx4 v[48:49], v[40:43], off
	global_store_dwordx4 v[48:49], v[44:47], off offset:16
	v_pk_add_f32 v[26:27], v[26:27], v[78:79]
	v_pk_add_f32 v[24:25], v[24:25], v[76:77]
	global_store_dwordx4 v[48:49], v[32:35], off offset:512
	global_store_dwordx4 v[48:49], v[24:27], off offset:528
	v_pk_add_f32 v[18:19], v[18:19], v[70:71]
	v_lshl_add_u64 v[32:33], s[54:55], 0, v[150:151]
	v_pk_add_f32 v[26:27], v[38:39], v[82:83]
	v_pk_add_f32 v[24:25], v[36:37], v[80:81]
	v_lshl_add_u64 v[32:33], v[32:33], 0, v[144:145]
	v_pk_add_f32 v[16:17], v[16:17], v[68:69]
	v_pk_add_f32 v[30:31], v[30:31], v[74:75]
	v_pk_add_f32 v[28:29], v[28:29], v[72:73]
	global_store_dwordx4 v[32:33], v[24:27], off
	global_store_dwordx4 v[32:33], v[28:31], off offset:16
	v_pk_add_f32 v[10:11], v[10:11], v[66:67]
	v_pk_add_f32 v[8:9], v[8:9], v[64:65]
	global_store_dwordx4 v[32:33], v[16:19], off offset:512
	global_store_dwordx4 v[32:33], v[8:11], off offset:528
	v_pk_add_f32 v[6:7], v[6:7], v[114:115]
	v_lshl_add_u64 v[16:17], s[54:55], 0, v[148:149]
	v_pk_add_f32 v[10:11], v[22:23], v[126:127]
	v_pk_add_f32 v[8:9], v[20:21], v[124:125]
	v_lshl_add_u64 v[16:17], v[16:17], 0, v[144:145]
	v_pk_add_f32 v[4:5], v[4:5], v[112:113]
	v_pk_add_f32 v[14:15], v[14:15], v[118:119]
	v_pk_add_f32 v[12:13], v[12:13], v[116:117]
	global_store_dwordx4 v[16:17], v[8:11], off
	global_store_dwordx4 v[16:17], v[12:15], off offset:16
	v_pk_add_f32 v[2:3], v[2:3], v[106:107]
	v_pk_add_f32 v[0:1], v[0:1], v[104:105]
	global_store_dwordx4 v[16:17], v[4:7], off offset:512
	global_store_dwordx4 v[16:17], v[0:3], off offset:528
	s_cbranch_vccz .LBB0_1417
	s_waitcnt vmcnt(0)
	s_cmpk_gt_u32 s23, 0xff
	s_cbranch_scc1 .LBB0_1428
	s_barrier
